# GEMM tile end: waves 4-7 run their epilogue before their final K-loop barrier so both wave groups epilogues share one barrier interval
# speedup vs baseline: 1.0172x; 1.0006x over previous
; #define PG8_STAGE(bufoff, gbase, voff) do { _Pragma("unroll") for (int _i = 0; _i < 2; ++_i) \
;         __builtin_amdgcn_global_load_lds((const unsigned*)((const char*)(gbase) + (voff)[_i]), (LAS unsigned*)(lds + (bufoff) + ldsw + _i * 8192), 16, 0, 0); } while (0)
; #define PG8_LDA(dst, b, h) do { _Pragma("unroll") for (int m = 0; m < 4; ++m) _Pragma("unroll") for (int k = 0; k < 2; ++k) dst[m][k] = *(const LAS bf16x8*)(lds + PG8_SA(b, h) + aoff + m * 2048 + k * 1024); } while (0)
; #define PG8_LDB(dst, b, h) do { _Pragma("unroll") for (int n = 0; n < 2; ++n) _Pragma("unroll") for (int k = 0; k < 2; ++k) dst[n][k] = *(const LAS bf16x8*)(lds + PG8_SB(b, h) + boff + n * 2048 + k * 1024); } while (0)
; #define PG8_WAIT_V(n) asm volatile("s_waitcnt vmcnt(" #n ")" ::: "memory")
; #define PG8_WAIT_L(n) asm volatile("s_waitcnt lgkmcnt(" #n ")" ::: "memory")
; #define PG8_BAR __builtin_amdgcn_s_barrier()
; #define PG8_SCHED __builtin_amdgcn_sched_barrier(0)
; template <class Epi>
; __device__ __forceinline__ void gemm_phase(LAS unsigned char* lds, const Gemm g, const StaticOrder& S, const Epi& E) {
;     ...
;         const bool has_next = S.next(ui + 1, nxt);
;         const char* nA = has_next ? (const char*)g.A + (size_t)nxt.pm * tstepA : cA; const char* nB = has_next ? (const char*)g.Bt + (size_t)nxt.pn * tstepB : cB;
;         for (int t = 0; t < nt; t += 2) {
;             const bool last = (t == nt - 2);
;             const char* a1 = cA + (size_t)(t + 1) * kstep;
;             const char* a2 = last ? nA : cA + (size_t)(t + 2) * kstep; const char* b2 = last ? nB : cB + (size_t)(t + 2) * kstep;
;             const char* a3 = a2 + kstep; const char* b3 = b2 + kstep;
;             PG8_LDB(B0, 0, 0); PG8_SCHED; PG8_LDA(At, 0, 0); PG8_STAGE(PG8_SA(1, 1), a1 + hstepA, voffA);
;             PG8_WAIT_L(8); PG8_BAR; PG8_WAIT_L(0); PG8_MMA(0, 0, At, B0); PG8_BAR; PG8_SCHED;
;             PG8_LDB(B1, 0, 1); PG8_STAGE(PG8_SB(0, 0), b2, voffB);
;             PG8_BAR; PG8_WAIT_L(0); PG8_MMA(0, 1, At, B1); PG8_BAR;
;             PG8_LDA(At, 0, 1); PG8_STAGE(PG8_SA(0, 0), a2, voffA);
;             PG8_BAR; PG8_WAIT_L(0); PG8_MMA(1, 0, At, B0); PG8_BAR; PG8_SCHED;
;             PG8_STAGE(PG8_SB(0, 1), b2 + hstepB, voffB);
;             PG8_WAIT_V(6); PG8_BAR; PG8_MMA(1, 1, At, B1); PG8_BAR;
.LBB0_140:
	v_mov_b64_e32 v[0:1], 0x800
	s_ashr_i32 s15, s14, 31
	v_cmp_lt_i64_e32 vcc, s[16:17], v[0:1]
	s_lshl_b64 s[16:17], s[14:15], 20
	v_readlane_b32 s18, v252, 53
	v_readlane_b32 s19, v252, 54
	s_add_u32 s16, s18, s16
	s_addc_u32 s17, s19, s17
	s_and_b64 s[18:19], vcc, exec
	s_cselect_b32 s15, s17, s23
	s_cselect_b32 s49, s16, s22
	s_ashr_i32 s5, s4, 31
	s_lshl_b64 s[18:19], s[4:5], 20
	s_add_u32 s18, s34, s18
	s_addc_u32 s19, s35, s19
	s_and_b64 s[26:27], vcc, exec
	s_cselect_b32 s5, s19, s25
	s_cselect_b32 s50, s18, s24
	s_add_u32 s22, s22, 0x84000
	s_addc_u32 s23, s23, 0
	s_add_u32 s51, s24, 0x8000
	s_addc_u32 s52, s25, 0
	s_mov_b32 s54, -2
	s_add_u32 s24, s22, 0xfff84000
	s_addc_u32 s25, s23, -1
	s_cmp_eq_u32 s54, 28
	s_cselect_b32 s28, s49, s24
	s_cselect_b32 s29, s15, s25
	s_cselect_b32 s24, s50, s51
	s_cselect_b32 s25, s5, s52
	s_add_u32 s26, s28, 0x4000
	s_addc_u32 s27, s29, 0
	s_add_i32 m0, s37, 0xc000
	v_lshl_add_u64 v[188:189], s[22:23], 0, v[128:129]
	global_load_lds_dwordx4 v[188:189], off
	s_add_i32 m0, s37, 0xe000
	v_lshl_add_u64 v[188:189], s[22:23], 0, v[130:131]
	global_load_lds_dwordx4 v[188:189], off
	s_mov_b32 s55, 0x10000
	v_add_u32_e32 v148, s55, v134
	ds_read_b128 v[136:139], v148
	ds_read_b128 v[144:147], v148 offset:2048
	ds_read_b128 v[140:143], v148 offset:1024
	ds_read_b128 v[148:151], v148 offset:3072
	ds_read_b128 v[156:159], v135
	ds_read_b128 v[164:167], v135 offset:2048
	ds_read_b128 v[172:175], v135 offset:4096
	ds_read_b128 v[180:183], v135 offset:6144
	ds_read_b128 v[160:163], v135 offset:1024
	ds_read_b128 v[168:171], v135 offset:3072
	ds_read_b128 v[176:179], v135 offset:5120
	ds_read_b128 v[184:187], v135 offset:7168
	s_mov_b32 s58, 0x14000
	s_add_i32 s55, s55, s36
	v_add_u32_e32 v152, s58, v134
	ds_read_b128 v[188:191], v152
	ds_read_b128 v[196:199], v152 offset:2048
	ds_read_b128 v[192:195], v152 offset:1024
	ds_read_b128 v[200:203], v152 offset:3072
	s_waitcnt lgkmcnt(0)
	s_barrier
	v_mfma_f32_16x16x32_bf16 v[124:127], v[136:139], v[156:159], 0
	s_setprio 1
	v_mfma_f32_16x16x32_bf16 v[120:123], v[144:147], v[156:159], 0
	v_mfma_f32_16x16x32_bf16 v[108:111], v[136:139], v[164:167], 0
	v_mfma_f32_16x16x32_bf16 v[104:107], v[144:147], v[164:167], 0
	v_mfma_f32_16x16x32_bf16 v[92:95], v[136:139], v[172:175], 0
	v_mfma_f32_16x16x32_bf16 v[88:91], v[144:147], v[172:175], 0
	v_mfma_f32_16x16x32_bf16 v[76:79], v[136:139], v[180:183], 0
	v_mfma_f32_16x16x32_bf16 v[72:75], v[144:147], v[180:183], 0
	v_mfma_f32_16x16x32_bf16 v[124:127], v[140:143], v[160:163], v[124:127]
	v_mfma_f32_16x16x32_bf16 v[120:123], v[148:151], v[160:163], v[120:123]
	v_mfma_f32_16x16x32_bf16 v[108:111], v[140:143], v[168:171], v[108:111]
	v_mfma_f32_16x16x32_bf16 v[104:107], v[148:151], v[168:171], v[104:107]
	v_mfma_f32_16x16x32_bf16 v[92:95], v[140:143], v[176:179], v[92:95]
	v_mfma_f32_16x16x32_bf16 v[88:91], v[148:151], v[176:179], v[88:91]
	v_mfma_f32_16x16x32_bf16 v[76:79], v[140:143], v[184:187], v[76:79]
	v_mfma_f32_16x16x32_bf16 v[72:75], v[148:151], v[184:187], v[72:75]
	v_mfma_f32_16x16x32_bf16 v[116:119], v[188:191], v[156:159], 0
	v_mfma_f32_16x16x32_bf16 v[112:115], v[196:199], v[156:159], 0
	v_mfma_f32_16x16x32_bf16 v[100:103], v[188:191], v[164:167], 0
	v_mfma_f32_16x16x32_bf16 v[96:99], v[196:199], v[164:167], 0
	v_mfma_f32_16x16x32_bf16 v[84:87], v[188:191], v[172:175], 0
	v_mfma_f32_16x16x32_bf16 v[80:83], v[196:199], v[172:175], 0
	v_mfma_f32_16x16x32_bf16 v[68:71], v[188:191], v[180:183], 0
	v_mfma_f32_16x16x32_bf16 v[64:67], v[196:199], v[180:183], 0
	v_mfma_f32_16x16x32_bf16 v[116:119], v[192:195], v[160:163], v[116:119]
	v_mfma_f32_16x16x32_bf16 v[112:115], v[200:203], v[160:163], v[112:115]
	v_mfma_f32_16x16x32_bf16 v[100:103], v[192:195], v[168:171], v[100:103]
	v_mfma_f32_16x16x32_bf16 v[96:99], v[200:203], v[168:171], v[96:99]
	v_mfma_f32_16x16x32_bf16 v[84:87], v[192:195], v[176:179], v[84:87]
	v_mfma_f32_16x16x32_bf16 v[80:83], v[200:203], v[176:179], v[80:83]
	v_mfma_f32_16x16x32_bf16 v[68:71], v[192:195], v[184:187], v[68:71]
	s_setprio 0
	v_mfma_f32_16x16x32_bf16 v[64:67], v[200:203], v[184:187], v[64:67]
	s_barrier
	s_mov_b32 m0, s55
	v_lshl_add_u64 v[204:205], s[24:25], 0, v[128:129]
	global_load_lds_dwordx4 v[204:205], off
	s_add_i32 m0, s55, 0x2000
	v_lshl_add_u64 v[204:205], s[24:25], 0, v[130:131]
	global_load_lds_dwordx4 v[204:205], off
	s_mov_b32 m0, s37
	v_lshl_add_u64 v[204:205], s[28:29], 0, v[128:129]
	global_load_lds_dwordx4 v[204:205], off
	s_mov_b32 m0, s38
	v_lshl_add_u64 v[204:205], s[28:29], 0, v[130:131]
	global_load_lds_dwordx4 v[204:205], off
	s_add_u32 s56, s24, 0x80000
	s_addc_u32 s57, s25, 0
	s_add_i32 s55, s58, s36
	s_mov_b32 m0, s55
	v_lshl_add_u64 v[204:205], s[56:57], 0, v[128:129]
	global_load_lds_dwordx4 v[204:205], off
	s_add_i32 m0, s55, 0x2000
	v_lshl_add_u64 v[204:205], s[56:57], 0, v[130:131]
	global_load_lds_dwordx4 v[204:205], off
	ds_read_b128 v[156:159], v135 offset:16384
	ds_read_b128 v[164:167], v135 offset:18432
	ds_read_b128 v[172:175], v135 offset:20480
	ds_read_b128 v[180:183], v135 offset:22528
	ds_read_b128 v[160:163], v135 offset:17408
	ds_read_b128 v[168:171], v135 offset:19456
	ds_read_b128 v[176:179], v135 offset:21504
	ds_read_b128 v[184:187], v135 offset:23552
	s_waitcnt vmcnt(6)
	s_waitcnt lgkmcnt(0)
	s_barrier
; #define PG8_STAGE(bufoff, gbase, voff) do { _Pragma("unroll") for (int _i = 0; _i < 2; ++_i) \
;         __builtin_amdgcn_global_load_lds((const unsigned*)((const char*)(gbase) + (voff)[_i]), (LAS unsigned*)(lds + (bufoff) + ldsw + _i * 8192), 16, 0, 0); } while (0)
; #define PG8_LDA(dst, b, h) do { _Pragma("unroll") for (int m = 0; m < 4; ++m) _Pragma("unroll") for (int k = 0; k < 2; ++k) dst[m][k] = *(const LAS bf16x8*)(lds + PG8_SA(b, h) + aoff + m * 2048 + k * 1024); } while (0)
; #define PG8_LDB(dst, b, h) do { _Pragma("unroll") for (int n = 0; n < 2; ++n) _Pragma("unroll") for (int k = 0; k < 2; ++k) dst[n][k] = *(const LAS bf16x8*)(lds + PG8_SB(b, h) + boff + n * 2048 + k * 1024); } while (0)
; #define PG8_MMA(ai, bj, At, Bt) do { __builtin_amdgcn_s_setprio(1); _Pragma("unroll") for (int m = 0; m < 4; ++m) _Pragma("unroll") for (int n = 0; n < 2; ++n) _Pragma("unroll") for (int k = 0; k < 2; ++k) \
;         acc[ai][bj][m][n] = __builtin_amdgcn_mfma_f32_16x16x32_bf16(Bt[n][k], At[m][k], acc[ai][bj][m][n], 0, 0, 0); __builtin_amdgcn_s_setprio(0); } while (0)
; #define PG8_WAIT_V(n) asm volatile("s_waitcnt vmcnt(" #n ")" ::: "memory")
; #define PG8_WAIT_L(n) asm volatile("s_waitcnt lgkmcnt(" #n ")" ::: "memory")
; #define PG8_BAR __builtin_amdgcn_s_barrier()
; #define PG8_SCHED __builtin_amdgcn_sched_barrier(0)
; template <class Epi>
; __device__ __forceinline__ void gemm_phase(LAS unsigned char* lds, const Gemm g, const StaticOrder& S, const Epi& E) {
;     ...
;             PG8_BAR; PG8_WAIT_L(0); PG8_MMA(1, 0, At, B0); PG8_BAR; PG8_SCHED;
;             PG8_STAGE(PG8_SB(0, 1), b2 + hstepB, voffB);
;             PG8_WAIT_V(6); PG8_BAR; PG8_MMA(1, 1, At, B1); PG8_BAR;
;             PG8_LDB(B0, 1, 0); PG8_SCHED; PG8_LDA(At, 1, 0); PG8_STAGE(PG8_SA(0, 1), a2 + hstepA, voffA);
;             PG8_WAIT_L(8); PG8_BAR; PG8_WAIT_L(0); PG8_MMA(0, 0, At, B0); PG8_BAR; PG8_SCHED;
;             PG8_LDB(B1, 1, 1); PG8_STAGE(PG8_SB(1, 0), b3, voffB);
;             PG8_BAR; PG8_WAIT_L(0); PG8_MMA(0, 1, At, B1); PG8_BAR;
	v_mfma_f32_16x16x32_bf16 v[60:63], v[136:139], v[156:159], 0
	s_setprio 1
	v_mfma_f32_16x16x32_bf16 v[56:59], v[144:147], v[156:159], 0
	v_mfma_f32_16x16x32_bf16 v[44:47], v[136:139], v[164:167], 0
	v_mfma_f32_16x16x32_bf16 v[40:43], v[144:147], v[164:167], 0
	v_mfma_f32_16x16x32_bf16 v[28:31], v[136:139], v[172:175], 0
	v_mfma_f32_16x16x32_bf16 v[24:27], v[144:147], v[172:175], 0
	v_mfma_f32_16x16x32_bf16 v[12:15], v[136:139], v[180:183], 0
	v_mfma_f32_16x16x32_bf16 v[8:11], v[144:147], v[180:183], 0
	v_mfma_f32_16x16x32_bf16 v[60:63], v[140:143], v[160:163], v[60:63]
	v_mfma_f32_16x16x32_bf16 v[56:59], v[148:151], v[160:163], v[56:59]
	v_mfma_f32_16x16x32_bf16 v[44:47], v[140:143], v[168:171], v[44:47]
	v_mfma_f32_16x16x32_bf16 v[40:43], v[148:151], v[168:171], v[40:43]
	v_mfma_f32_16x16x32_bf16 v[28:31], v[140:143], v[176:179], v[28:31]
	v_mfma_f32_16x16x32_bf16 v[24:27], v[148:151], v[176:179], v[24:27]
	v_mfma_f32_16x16x32_bf16 v[12:15], v[140:143], v[184:187], v[12:15]
	v_mfma_f32_16x16x32_bf16 v[8:11], v[148:151], v[184:187], v[8:11]
	v_mfma_f32_16x16x32_bf16 v[52:55], v[188:191], v[156:159], 0
	v_mfma_f32_16x16x32_bf16 v[48:51], v[196:199], v[156:159], 0
	s_add_i32 s55, 0, 0x18000
	v_add_u32_e32 v148, s55, v134
	v_mfma_f32_16x16x32_bf16 v[36:39], v[188:191], v[164:167], 0
	v_mfma_f32_16x16x32_bf16 v[32:35], v[196:199], v[164:167], 0
	v_mfma_f32_16x16x32_bf16 v[20:23], v[188:191], v[172:175], 0
	v_mfma_f32_16x16x32_bf16 v[16:19], v[196:199], v[172:175], 0
	v_mfma_f32_16x16x32_bf16 v[4:7], v[188:191], v[180:183], 0
	v_mfma_f32_16x16x32_bf16 v[0:3], v[196:199], v[180:183], 0
	v_mfma_f32_16x16x32_bf16 v[52:55], v[192:195], v[160:163], v[52:55]
	v_mfma_f32_16x16x32_bf16 v[48:51], v[200:203], v[160:163], v[48:51]
	v_mfma_f32_16x16x32_bf16 v[36:39], v[192:195], v[168:171], v[36:39]
	v_mfma_f32_16x16x32_bf16 v[32:35], v[200:203], v[168:171], v[32:35]
	v_mfma_f32_16x16x32_bf16 v[20:23], v[192:195], v[176:179], v[20:23]
	v_mfma_f32_16x16x32_bf16 v[16:19], v[200:203], v[176:179], v[16:19]
	v_mfma_f32_16x16x32_bf16 v[4:7], v[192:195], v[184:187], v[4:7]
	s_setprio 0
	v_mfma_f32_16x16x32_bf16 v[0:3], v[200:203], v[184:187], v[0:3]
	s_barrier
	s_add_u32 s28, s28, 0x80000
	s_addc_u32 s29, s29, 0
	s_mov_b32 m0, s39
	v_lshl_add_u64 v[188:189], s[28:29], 0, v[128:129]
	global_load_lds_dwordx4 v[188:189], off
	s_mov_b32 m0, s40
	v_lshl_add_u64 v[188:189], s[28:29], 0, v[130:131]
	global_load_lds_dwordx4 v[188:189], off
	ds_read_b128 v[136:139], v148
	ds_read_b128 v[144:147], v148 offset:2048
	ds_read_b128 v[140:143], v148 offset:1024
	ds_read_b128 v[148:151], v148 offset:3072
	ds_read_b128 v[156:159], v135 offset:32768
	ds_read_b128 v[164:167], v135 offset:34816
	ds_read_b128 v[172:175], v135 offset:36864
	ds_read_b128 v[180:183], v135 offset:38912
	ds_read_b128 v[160:163], v135 offset:33792
	ds_read_b128 v[168:171], v135 offset:35840
	ds_read_b128 v[176:179], v135 offset:37888
	ds_read_b128 v[184:187], v135 offset:39936
	s_mov_b32 s56, 0x1c000
	s_add_u32 s28, s24, 0x4000
	s_addc_u32 s29, s25, 0
	s_add_i32 s55, s55, s36
	v_add_u32_e32 v152, s56, v134
	ds_read_b128 v[188:191], v152
	ds_read_b128 v[196:199], v152 offset:2048
	ds_read_b128 v[192:195], v152 offset:1024
	ds_read_b128 v[200:203], v152 offset:3072
	s_waitcnt lgkmcnt(0)
	s_barrier
	v_mfma_f32_16x16x32_bf16 v[124:127], v[136:139], v[156:159], v[124:127]
	s_setprio 1
	v_mfma_f32_16x16x32_bf16 v[120:123], v[144:147], v[156:159], v[120:123]
	v_mfma_f32_16x16x32_bf16 v[108:111], v[136:139], v[164:167], v[108:111]
	v_mfma_f32_16x16x32_bf16 v[104:107], v[144:147], v[164:167], v[104:107]
	v_mfma_f32_16x16x32_bf16 v[92:95], v[136:139], v[172:175], v[92:95]
	v_mfma_f32_16x16x32_bf16 v[88:91], v[144:147], v[172:175], v[88:91]
	v_mfma_f32_16x16x32_bf16 v[76:79], v[136:139], v[180:183], v[76:79]
	v_mfma_f32_16x16x32_bf16 v[72:75], v[144:147], v[180:183], v[72:75]
	v_mfma_f32_16x16x32_bf16 v[124:127], v[140:143], v[160:163], v[124:127]
	v_mfma_f32_16x16x32_bf16 v[120:123], v[148:151], v[160:163], v[120:123]
	v_mfma_f32_16x16x32_bf16 v[108:111], v[140:143], v[168:171], v[108:111]
	v_mfma_f32_16x16x32_bf16 v[104:107], v[148:151], v[168:171], v[104:107]
	v_mfma_f32_16x16x32_bf16 v[92:95], v[140:143], v[176:179], v[92:95]
	v_mfma_f32_16x16x32_bf16 v[88:91], v[148:151], v[176:179], v[88:91]
	v_mfma_f32_16x16x32_bf16 v[76:79], v[140:143], v[184:187], v[76:79]
	v_mfma_f32_16x16x32_bf16 v[72:75], v[148:151], v[184:187], v[72:75]
	v_mfma_f32_16x16x32_bf16 v[116:119], v[188:191], v[156:159], v[116:119]
	v_mfma_f32_16x16x32_bf16 v[112:115], v[196:199], v[156:159], v[112:115]
	v_mfma_f32_16x16x32_bf16 v[100:103], v[188:191], v[164:167], v[100:103]
	v_mfma_f32_16x16x32_bf16 v[96:99], v[196:199], v[164:167], v[96:99]
	v_mfma_f32_16x16x32_bf16 v[84:87], v[188:191], v[172:175], v[84:87]
	v_mfma_f32_16x16x32_bf16 v[80:83], v[196:199], v[172:175], v[80:83]
	v_mfma_f32_16x16x32_bf16 v[68:71], v[188:191], v[180:183], v[68:71]
	v_mfma_f32_16x16x32_bf16 v[64:67], v[196:199], v[180:183], v[64:67]
	v_mfma_f32_16x16x32_bf16 v[116:119], v[192:195], v[160:163], v[116:119]
	v_mfma_f32_16x16x32_bf16 v[112:115], v[200:203], v[160:163], v[112:115]
	v_mfma_f32_16x16x32_bf16 v[100:103], v[192:195], v[168:171], v[100:103]
	v_mfma_f32_16x16x32_bf16 v[96:99], v[200:203], v[168:171], v[96:99]
	v_mfma_f32_16x16x32_bf16 v[84:87], v[192:195], v[176:179], v[84:87]
	v_mfma_f32_16x16x32_bf16 v[80:83], v[200:203], v[176:179], v[80:83]
	v_mfma_f32_16x16x32_bf16 v[68:71], v[192:195], v[184:187], v[68:71]
	s_setprio 0
	v_mfma_f32_16x16x32_bf16 v[64:67], v[200:203], v[184:187], v[64:67]
	s_barrier
; #define PG8_STAGE(bufoff, gbase, voff) do { _Pragma("unroll") for (int _i = 0; _i < 2; ++_i) \
;         __builtin_amdgcn_global_load_lds((const unsigned*)((const char*)(gbase) + (voff)[_i]), (LAS unsigned*)(lds + (bufoff) + ldsw + _i * 8192), 16, 0, 0); } while (0)
; #define PG8_LDA(dst, b, h) do { _Pragma("unroll") for (int m = 0; m < 4; ++m) _Pragma("unroll") for (int k = 0; k < 2; ++k) dst[m][k] = *(const LAS bf16x8*)(lds + PG8_SA(b, h) + aoff + m * 2048 + k * 1024); } while (0)
; #define PG8_LDB(dst, b, h) do { _Pragma("unroll") for (int n = 0; n < 2; ++n) _Pragma("unroll") for (int k = 0; k < 2; ++k) dst[n][k] = *(const LAS bf16x8*)(lds + PG8_SB(b, h) + boff + n * 2048 + k * 1024); } while (0)
; #define PG8_MMA(ai, bj, At, Bt) do { __builtin_amdgcn_s_setprio(1); _Pragma("unroll") for (int m = 0; m < 4; ++m) _Pragma("unroll") for (int n = 0; n < 2; ++n) _Pragma("unroll") for (int k = 0; k < 2; ++k) \
;         acc[ai][bj][m][n] = __builtin_amdgcn_mfma_f32_16x16x32_bf16(Bt[n][k], At[m][k], acc[ai][bj][m][n], 0, 0, 0); __builtin_amdgcn_s_setprio(0); } while (0)
; #define PG8_WAIT_V(n) asm volatile("s_waitcnt vmcnt(" #n ")" ::: "memory")
; #define PG8_WAIT_L(n) asm volatile("s_waitcnt lgkmcnt(" #n ")" ::: "memory")
; #define PG8_BAR __builtin_amdgcn_s_barrier()
; #define PG8_SCHED __builtin_amdgcn_sched_barrier(0)
; template <class Epi>
; __device__ __forceinline__ void gemm_phase(LAS unsigned char* lds, const Gemm g, const StaticOrder& S, const Epi& E) {
;     ...
;             const bool last = (t == nt - 2);
;             const char* a1 = cA + (size_t)(t + 1) * kstep;
;             const char* a2 = last ? nA : cA + (size_t)(t + 2) * kstep; const char* b2 = last ? nB : cB + (size_t)(t + 2) * kstep;
;             const char* a3 = a2 + kstep; const char* b3 = b2 + kstep;
;             PG8_LDB(B0, 0, 0); PG8_SCHED; PG8_LDA(At, 0, 0); PG8_STAGE(PG8_SA(1, 1), a1 + hstepA, voffA);
;             PG8_WAIT_L(8); PG8_BAR; PG8_WAIT_L(0); PG8_MMA(0, 0, At, B0); PG8_BAR; PG8_SCHED;
;             PG8_LDB(B1, 0, 1); PG8_STAGE(PG8_SB(0, 0), b2, voffB);
;     ...
;             PG8_LDA(At, 1, 1); PG8_STAGE(PG8_SA(1, 0), a3, voffA);
;             PG8_BAR; PG8_WAIT_L(0); PG8_MMA(1, 0, At, B0); PG8_BAR; PG8_SCHED;
;             PG8_STAGE(PG8_SB(1, 1), b3 + hstepB, voffB);
;             PG8_WAIT_V(6); PG8_BAR; PG8_MMA(1, 1, At, B1); PG8_BAR;
	s_mov_b32 m0, s55
	v_lshl_add_u64 v[204:205], s[28:29], 0, v[128:129]
	global_load_lds_dwordx4 v[204:205], off
	s_add_i32 m0, s55, 0x2000
	v_lshl_add_u64 v[204:205], s[28:29], 0, v[130:131]
	global_load_lds_dwordx4 v[204:205], off
	s_mov_b32 m0, s43
	v_lshl_add_u64 v[204:205], s[26:27], 0, v[128:129]
	global_load_lds_dwordx4 v[204:205], off
	s_mov_b32 m0, s44
	v_lshl_add_u64 v[204:205], s[26:27], 0, v[130:131]
	global_load_lds_dwordx4 v[204:205], off
	s_add_u32 s24, s24, 0x84000
	s_addc_u32 s25, s25, 0
	s_add_i32 s26, s56, s36
	s_mov_b32 m0, s26
	v_lshl_add_u64 v[204:205], s[24:25], 0, v[128:129]
	global_load_lds_dwordx4 v[204:205], off
	s_add_i32 m0, s26, 0x2000
	v_lshl_add_u64 v[204:205], s[24:25], 0, v[130:131]
	global_load_lds_dwordx4 v[204:205], off
	ds_read_b128 v[156:159], v135 offset:49152
	ds_read_b128 v[164:167], v135 offset:51200
	ds_read_b128 v[172:175], v135 offset:53248
	ds_read_b128 v[180:183], v135 offset:55296
	ds_read_b128 v[160:163], v135 offset:50176
	ds_read_b128 v[168:171], v135 offset:52224
	ds_read_b128 v[176:179], v135 offset:54272
	ds_read_b128 v[184:187], v135 offset:56320
	s_waitcnt vmcnt(6)
	s_waitcnt lgkmcnt(0)
	s_barrier
	v_mfma_f32_16x16x32_bf16 v[60:63], v[136:139], v[156:159], v[60:63]
	s_setprio 1
	v_mfma_f32_16x16x32_bf16 v[56:59], v[144:147], v[156:159], v[56:59]
	v_mfma_f32_16x16x32_bf16 v[44:47], v[136:139], v[164:167], v[44:47]
	v_mfma_f32_16x16x32_bf16 v[40:43], v[144:147], v[164:167], v[40:43]
	v_mfma_f32_16x16x32_bf16 v[28:31], v[136:139], v[172:175], v[28:31]
	v_mfma_f32_16x16x32_bf16 v[24:27], v[144:147], v[172:175], v[24:27]
	v_mfma_f32_16x16x32_bf16 v[12:15], v[136:139], v[180:183], v[12:15]
	v_mfma_f32_16x16x32_bf16 v[8:11], v[144:147], v[180:183], v[8:11]
	v_mfma_f32_16x16x32_bf16 v[60:63], v[140:143], v[160:163], v[60:63]
	v_mfma_f32_16x16x32_bf16 v[56:59], v[148:151], v[160:163], v[56:59]
	v_mfma_f32_16x16x32_bf16 v[44:47], v[140:143], v[168:171], v[44:47]
	v_mfma_f32_16x16x32_bf16 v[40:43], v[148:151], v[168:171], v[40:43]
	v_mfma_f32_16x16x32_bf16 v[28:31], v[140:143], v[176:179], v[28:31]
	v_mfma_f32_16x16x32_bf16 v[24:27], v[148:151], v[176:179], v[24:27]
	v_mfma_f32_16x16x32_bf16 v[12:15], v[140:143], v[184:187], v[12:15]
	v_mfma_f32_16x16x32_bf16 v[8:11], v[148:151], v[184:187], v[8:11]
	v_mfma_f32_16x16x32_bf16 v[52:55], v[188:191], v[156:159], v[52:55]
	v_mfma_f32_16x16x32_bf16 v[48:51], v[196:199], v[156:159], v[48:51]
	s_add_i32 s54, s54, 2
	s_add_u32 s22, s22, 0x8000
	s_addc_u32 s23, s23, 0
	s_add_u32 s51, s51, 0x8000
	s_addc_u32 s52, s52, 0
	v_mfma_f32_16x16x32_bf16 v[36:39], v[188:191], v[164:167], v[36:39]
	v_mfma_f32_16x16x32_bf16 v[32:35], v[196:199], v[164:167], v[32:35]
	v_mfma_f32_16x16x32_bf16 v[20:23], v[188:191], v[172:175], v[20:23]
	v_mfma_f32_16x16x32_bf16 v[16:19], v[196:199], v[172:175], v[16:19]
	v_mfma_f32_16x16x32_bf16 v[4:7], v[188:191], v[180:183], v[4:7]
	v_mfma_f32_16x16x32_bf16 v[0:3], v[196:199], v[180:183], v[0:3]
	v_mfma_f32_16x16x32_bf16 v[52:55], v[192:195], v[160:163], v[52:55]
	v_mfma_f32_16x16x32_bf16 v[48:51], v[200:203], v[160:163], v[48:51]
	v_mfma_f32_16x16x32_bf16 v[36:39], v[192:195], v[168:171], v[36:39]
	v_mfma_f32_16x16x32_bf16 v[32:35], v[200:203], v[168:171], v[32:35]
	v_mfma_f32_16x16x32_bf16 v[20:23], v[192:195], v[176:179], v[20:23]
	v_mfma_f32_16x16x32_bf16 v[16:19], v[200:203], v[176:179], v[16:19]
	v_mfma_f32_16x16x32_bf16 v[4:7], v[192:195], v[184:187], v[4:7]
	s_cmp_gt_u32 s54, 29
	s_setprio 0
	v_mfma_f32_16x16x32_bf16 v[0:3], v[200:203], v[184:187], v[0:3]
	s_cbranch_scc1 .Lkexit_141
	s_barrier
.LBB0_141:
	s_add_u32 s24, s22, 0xfff84000
	s_addc_u32 s25, s23, -1
	s_cmp_eq_u32 s54, 28
	s_cselect_b32 s28, s49, s24
	s_cselect_b32 s29, s15, s25
	s_cselect_b32 s24, s50, s51
	s_cselect_b32 s25, s5, s52
	s_add_u32 s26, s28, 0x4000
	s_addc_u32 s27, s29, 0
	s_add_i32 m0, s37, 0xc000
	v_lshl_add_u64 v[188:189], s[22:23], 0, v[128:129]
	global_load_lds_dwordx4 v[188:189], off
	s_add_i32 m0, s37, 0xe000
	v_lshl_add_u64 v[188:189], s[22:23], 0, v[130:131]
	global_load_lds_dwordx4 v[188:189], off
	s_mov_b32 s55, 0x10000
	v_add_u32_e32 v148, s55, v134
	ds_read_b128 v[136:139], v148
	ds_read_b128 v[144:147], v148 offset:2048
	ds_read_b128 v[140:143], v148 offset:1024
	ds_read_b128 v[148:151], v148 offset:3072
	ds_read_b128 v[156:159], v135
	ds_read_b128 v[164:167], v135 offset:2048
	ds_read_b128 v[172:175], v135 offset:4096
	ds_read_b128 v[180:183], v135 offset:6144
	ds_read_b128 v[160:163], v135 offset:1024
	ds_read_b128 v[168:171], v135 offset:3072
	ds_read_b128 v[176:179], v135 offset:5120
	ds_read_b128 v[184:187], v135 offset:7168
	s_mov_b32 s58, 0x14000
	s_add_i32 s55, s55, s36
	v_add_u32_e32 v152, s58, v134
	ds_read_b128 v[188:191], v152
	ds_read_b128 v[196:199], v152 offset:2048
	ds_read_b128 v[192:195], v152 offset:1024
	ds_read_b128 v[200:203], v152 offset:3072
	s_waitcnt lgkmcnt(0)
	s_barrier
; #define PG8_STAGE(bufoff, gbase, voff) do { _Pragma("unroll") for (int _i = 0; _i < 2; ++_i) \
;         __builtin_amdgcn_global_load_lds((const unsigned*)((const char*)(gbase) + (voff)[_i]), (LAS unsigned*)(lds + (bufoff) + ldsw + _i * 8192), 16, 0, 0); } while (0)
; #define PG8_LDA(dst, b, h) do { _Pragma("unroll") for (int m = 0; m < 4; ++m) _Pragma("unroll") for (int k = 0; k < 2; ++k) dst[m][k] = *(const LAS bf16x8*)(lds + PG8_SA(b, h) + aoff + m * 2048 + k * 1024); } while (0)
; #define PG8_LDB(dst, b, h) do { _Pragma("unroll") for (int n = 0; n < 2; ++n) _Pragma("unroll") for (int k = 0; k < 2; ++k) dst[n][k] = *(const LAS bf16x8*)(lds + PG8_SB(b, h) + boff + n * 2048 + k * 1024); } while (0)
; #define PG8_MMA(ai, bj, At, Bt) do { __builtin_amdgcn_s_setprio(1); _Pragma("unroll") for (int m = 0; m < 4; ++m) _Pragma("unroll") for (int n = 0; n < 2; ++n) _Pragma("unroll") for (int k = 0; k < 2; ++k) \
;         acc[ai][bj][m][n] = __builtin_amdgcn_mfma_f32_16x16x32_bf16(Bt[n][k], At[m][k], acc[ai][bj][m][n], 0, 0, 0); __builtin_amdgcn_s_setprio(0); } while (0)
; #define PG8_WAIT_V(n) asm volatile("s_waitcnt vmcnt(" #n ")" ::: "memory")
; #define PG8_WAIT_L(n) asm volatile("s_waitcnt lgkmcnt(" #n ")" ::: "memory")
; #define PG8_BAR __builtin_amdgcn_s_barrier()
; #define PG8_SCHED __builtin_amdgcn_sched_barrier(0)
; template <class Epi>
; __device__ __forceinline__ void gemm_phase(LAS unsigned char* lds, const Gemm g, const StaticOrder& S, const Epi& E) {
;     ...
;             PG8_WAIT_L(8); PG8_BAR; PG8_WAIT_L(0); PG8_MMA(0, 0, At, B0); PG8_BAR; PG8_SCHED;
;             PG8_LDB(B1, 0, 1); PG8_STAGE(PG8_SB(0, 0), b2, voffB);
;             PG8_BAR; PG8_WAIT_L(0); PG8_MMA(0, 1, At, B1); PG8_BAR;
;             PG8_LDA(At, 0, 1); PG8_STAGE(PG8_SA(0, 0), a2, voffA);
;             PG8_BAR; PG8_WAIT_L(0); PG8_MMA(1, 0, At, B0); PG8_BAR; PG8_SCHED;
;             PG8_STAGE(PG8_SB(0, 1), b2 + hstepB, voffB);
;             PG8_WAIT_V(6); PG8_BAR; PG8_MMA(1, 1, At, B1); PG8_BAR;
	v_mfma_f32_16x16x32_bf16 v[124:127], v[136:139], v[156:159], v[124:127]
	s_setprio 1
	v_mfma_f32_16x16x32_bf16 v[120:123], v[144:147], v[156:159], v[120:123]
	v_mfma_f32_16x16x32_bf16 v[108:111], v[136:139], v[164:167], v[108:111]
	v_mfma_f32_16x16x32_bf16 v[104:107], v[144:147], v[164:167], v[104:107]
	v_mfma_f32_16x16x32_bf16 v[92:95], v[136:139], v[172:175], v[92:95]
	v_mfma_f32_16x16x32_bf16 v[88:91], v[144:147], v[172:175], v[88:91]
	v_mfma_f32_16x16x32_bf16 v[76:79], v[136:139], v[180:183], v[76:79]
	v_mfma_f32_16x16x32_bf16 v[72:75], v[144:147], v[180:183], v[72:75]
	v_mfma_f32_16x16x32_bf16 v[124:127], v[140:143], v[160:163], v[124:127]
	v_mfma_f32_16x16x32_bf16 v[120:123], v[148:151], v[160:163], v[120:123]
	v_mfma_f32_16x16x32_bf16 v[108:111], v[140:143], v[168:171], v[108:111]
	v_mfma_f32_16x16x32_bf16 v[104:107], v[148:151], v[168:171], v[104:107]
	v_mfma_f32_16x16x32_bf16 v[92:95], v[140:143], v[176:179], v[92:95]
	v_mfma_f32_16x16x32_bf16 v[88:91], v[148:151], v[176:179], v[88:91]
	v_mfma_f32_16x16x32_bf16 v[76:79], v[140:143], v[184:187], v[76:79]
	v_mfma_f32_16x16x32_bf16 v[72:75], v[148:151], v[184:187], v[72:75]
	v_mfma_f32_16x16x32_bf16 v[116:119], v[188:191], v[156:159], v[116:119]
	v_mfma_f32_16x16x32_bf16 v[112:115], v[196:199], v[156:159], v[112:115]
	v_mfma_f32_16x16x32_bf16 v[100:103], v[188:191], v[164:167], v[100:103]
	v_mfma_f32_16x16x32_bf16 v[96:99], v[196:199], v[164:167], v[96:99]
	v_mfma_f32_16x16x32_bf16 v[84:87], v[188:191], v[172:175], v[84:87]
	v_mfma_f32_16x16x32_bf16 v[80:83], v[196:199], v[172:175], v[80:83]
	v_mfma_f32_16x16x32_bf16 v[68:71], v[188:191], v[180:183], v[68:71]
	v_mfma_f32_16x16x32_bf16 v[64:67], v[196:199], v[180:183], v[64:67]
	v_mfma_f32_16x16x32_bf16 v[116:119], v[192:195], v[160:163], v[116:119]
	v_mfma_f32_16x16x32_bf16 v[112:115], v[200:203], v[160:163], v[112:115]
	v_mfma_f32_16x16x32_bf16 v[100:103], v[192:195], v[168:171], v[100:103]
	v_mfma_f32_16x16x32_bf16 v[96:99], v[200:203], v[168:171], v[96:99]
	v_mfma_f32_16x16x32_bf16 v[84:87], v[192:195], v[176:179], v[84:87]
	v_mfma_f32_16x16x32_bf16 v[80:83], v[200:203], v[176:179], v[80:83]
	v_mfma_f32_16x16x32_bf16 v[68:71], v[192:195], v[184:187], v[68:71]
	s_setprio 0
	v_mfma_f32_16x16x32_bf16 v[64:67], v[200:203], v[184:187], v[64:67]
	s_barrier
	s_mov_b32 m0, s55
	v_lshl_add_u64 v[204:205], s[24:25], 0, v[128:129]
	global_load_lds_dwordx4 v[204:205], off
	s_add_i32 m0, s55, 0x2000
	v_lshl_add_u64 v[204:205], s[24:25], 0, v[130:131]
	global_load_lds_dwordx4 v[204:205], off
	s_mov_b32 m0, s37
	v_lshl_add_u64 v[204:205], s[28:29], 0, v[128:129]
	global_load_lds_dwordx4 v[204:205], off
	s_mov_b32 m0, s38
	v_lshl_add_u64 v[204:205], s[28:29], 0, v[130:131]
	global_load_lds_dwordx4 v[204:205], off
	s_add_u32 s56, s24, 0x80000
	s_addc_u32 s57, s25, 0
	s_add_i32 s55, s58, s36
	s_mov_b32 m0, s55
	v_lshl_add_u64 v[204:205], s[56:57], 0, v[128:129]
	global_load_lds_dwordx4 v[204:205], off
	s_add_i32 m0, s55, 0x2000
	v_lshl_add_u64 v[204:205], s[56:57], 0, v[130:131]
	global_load_lds_dwordx4 v[204:205], off
	ds_read_b128 v[156:159], v135 offset:16384
	ds_read_b128 v[164:167], v135 offset:18432
	ds_read_b128 v[172:175], v135 offset:20480
	ds_read_b128 v[180:183], v135 offset:22528
	ds_read_b128 v[160:163], v135 offset:17408
	ds_read_b128 v[168:171], v135 offset:19456
	ds_read_b128 v[176:179], v135 offset:21504
	ds_read_b128 v[184:187], v135 offset:23552
	s_waitcnt vmcnt(6)
	s_waitcnt lgkmcnt(0)
	s_barrier
	v_mfma_f32_16x16x32_bf16 v[60:63], v[136:139], v[156:159], v[60:63]
	s_setprio 1
	v_mfma_f32_16x16x32_bf16 v[56:59], v[144:147], v[156:159], v[56:59]
	v_mfma_f32_16x16x32_bf16 v[44:47], v[136:139], v[164:167], v[44:47]
	v_mfma_f32_16x16x32_bf16 v[40:43], v[144:147], v[164:167], v[40:43]
	v_mfma_f32_16x16x32_bf16 v[28:31], v[136:139], v[172:175], v[28:31]
	v_mfma_f32_16x16x32_bf16 v[24:27], v[144:147], v[172:175], v[24:27]
	v_mfma_f32_16x16x32_bf16 v[12:15], v[136:139], v[180:183], v[12:15]
	v_mfma_f32_16x16x32_bf16 v[8:11], v[144:147], v[180:183], v[8:11]
	v_mfma_f32_16x16x32_bf16 v[60:63], v[140:143], v[160:163], v[60:63]
	v_mfma_f32_16x16x32_bf16 v[56:59], v[148:151], v[160:163], v[56:59]
	v_mfma_f32_16x16x32_bf16 v[44:47], v[140:143], v[168:171], v[44:47]
	v_mfma_f32_16x16x32_bf16 v[40:43], v[148:151], v[168:171], v[40:43]
	v_mfma_f32_16x16x32_bf16 v[28:31], v[140:143], v[176:179], v[28:31]
	v_mfma_f32_16x16x32_bf16 v[24:27], v[148:151], v[176:179], v[24:27]
	v_mfma_f32_16x16x32_bf16 v[12:15], v[140:143], v[184:187], v[12:15]
	v_mfma_f32_16x16x32_bf16 v[8:11], v[148:151], v[184:187], v[8:11]
	v_mfma_f32_16x16x32_bf16 v[52:55], v[188:191], v[156:159], v[52:55]
	v_mfma_f32_16x16x32_bf16 v[48:51], v[196:199], v[156:159], v[48:51]
	s_add_i32 s55, 0, 0x18000
	v_add_u32_e32 v148, s55, v134
	v_mfma_f32_16x16x32_bf16 v[36:39], v[188:191], v[164:167], v[36:39]
	v_mfma_f32_16x16x32_bf16 v[32:35], v[196:199], v[164:167], v[32:35]
	v_mfma_f32_16x16x32_bf16 v[20:23], v[188:191], v[172:175], v[20:23]
	v_mfma_f32_16x16x32_bf16 v[16:19], v[196:199], v[172:175], v[16:19]
	v_mfma_f32_16x16x32_bf16 v[4:7], v[188:191], v[180:183], v[4:7]
	v_mfma_f32_16x16x32_bf16 v[0:3], v[196:199], v[180:183], v[0:3]
	v_mfma_f32_16x16x32_bf16 v[52:55], v[192:195], v[160:163], v[52:55]
	v_mfma_f32_16x16x32_bf16 v[48:51], v[200:203], v[160:163], v[48:51]
	v_mfma_f32_16x16x32_bf16 v[36:39], v[192:195], v[168:171], v[36:39]
	v_mfma_f32_16x16x32_bf16 v[32:35], v[200:203], v[168:171], v[32:35]
	v_mfma_f32_16x16x32_bf16 v[20:23], v[192:195], v[176:179], v[20:23]
	v_mfma_f32_16x16x32_bf16 v[16:19], v[200:203], v[176:179], v[16:19]
	v_mfma_f32_16x16x32_bf16 v[4:7], v[192:195], v[184:187], v[4:7]
	s_setprio 0
	v_mfma_f32_16x16x32_bf16 v[0:3], v[200:203], v[184:187], v[0:3]
	s_barrier
; #define PG8_STAGE(bufoff, gbase, voff) do { _Pragma("unroll") for (int _i = 0; _i < 2; ++_i) \
;         __builtin_amdgcn_global_load_lds((const unsigned*)((const char*)(gbase) + (voff)[_i]), (LAS unsigned*)(lds + (bufoff) + ldsw + _i * 8192), 16, 0, 0); } while (0)
; #define PG8_LDA(dst, b, h) do { _Pragma("unroll") for (int m = 0; m < 4; ++m) _Pragma("unroll") for (int k = 0; k < 2; ++k) dst[m][k] = *(const LAS bf16x8*)(lds + PG8_SA(b, h) + aoff + m * 2048 + k * 1024); } while (0)
; #define PG8_LDB(dst, b, h) do { _Pragma("unroll") for (int n = 0; n < 2; ++n) _Pragma("unroll") for (int k = 0; k < 2; ++k) dst[n][k] = *(const LAS bf16x8*)(lds + PG8_SB(b, h) + boff + n * 2048 + k * 1024); } while (0)
; #define PG8_MMA(ai, bj, At, Bt) do { __builtin_amdgcn_s_setprio(1); _Pragma("unroll") for (int m = 0; m < 4; ++m) _Pragma("unroll") for (int n = 0; n < 2; ++n) _Pragma("unroll") for (int k = 0; k < 2; ++k) \
;         acc[ai][bj][m][n] = __builtin_amdgcn_mfma_f32_16x16x32_bf16(Bt[n][k], At[m][k], acc[ai][bj][m][n], 0, 0, 0); __builtin_amdgcn_s_setprio(0); } while (0)
; #define PG8_WAIT_V(n) asm volatile("s_waitcnt vmcnt(" #n ")" ::: "memory")
; #define PG8_WAIT_L(n) asm volatile("s_waitcnt lgkmcnt(" #n ")" ::: "memory")
; #define PG8_BAR __builtin_amdgcn_s_barrier()
; #define PG8_SCHED __builtin_amdgcn_sched_barrier(0)
; template <class Epi>
; __device__ __forceinline__ void gemm_phase(LAS unsigned char* lds, const Gemm g, const StaticOrder& S, const Epi& E) {
;     ...
;             PG8_LDB(B0, 1, 0); PG8_SCHED; PG8_LDA(At, 1, 0); PG8_STAGE(PG8_SA(0, 1), a2 + hstepA, voffA);
;             PG8_WAIT_L(8); PG8_BAR; PG8_WAIT_L(0); PG8_MMA(0, 0, At, B0); PG8_BAR; PG8_SCHED;
;             PG8_LDB(B1, 1, 1); PG8_STAGE(PG8_SB(1, 0), b3, voffB);
;             PG8_BAR; PG8_WAIT_L(0); PG8_MMA(0, 1, At, B1); PG8_BAR;
;             PG8_LDA(At, 1, 1); PG8_STAGE(PG8_SA(1, 0), a3, voffA);
;             PG8_BAR; PG8_WAIT_L(0); PG8_MMA(1, 0, At, B0); PG8_BAR; PG8_SCHED;
;             PG8_STAGE(PG8_SB(1, 1), b3 + hstepB, voffB);
;             PG8_WAIT_V(6); PG8_BAR; PG8_MMA(1, 1, At, B1); PG8_BAR;
	s_add_u32 s28, s28, 0x80000
	s_addc_u32 s29, s29, 0
	s_mov_b32 m0, s39
	v_lshl_add_u64 v[188:189], s[28:29], 0, v[128:129]
	global_load_lds_dwordx4 v[188:189], off
	s_mov_b32 m0, s40
	v_lshl_add_u64 v[188:189], s[28:29], 0, v[130:131]
	global_load_lds_dwordx4 v[188:189], off
	ds_read_b128 v[136:139], v148
	ds_read_b128 v[144:147], v148 offset:2048
	ds_read_b128 v[140:143], v148 offset:1024
	ds_read_b128 v[148:151], v148 offset:3072
	ds_read_b128 v[156:159], v135 offset:32768
	ds_read_b128 v[164:167], v135 offset:34816
	ds_read_b128 v[172:175], v135 offset:36864
	ds_read_b128 v[180:183], v135 offset:38912
	ds_read_b128 v[160:163], v135 offset:33792
	ds_read_b128 v[168:171], v135 offset:35840
	ds_read_b128 v[176:179], v135 offset:37888
	ds_read_b128 v[184:187], v135 offset:39936
	s_mov_b32 s56, 0x1c000
	s_add_u32 s28, s24, 0x4000
	s_addc_u32 s29, s25, 0
	s_add_i32 s55, s55, s36
	v_add_u32_e32 v152, s56, v134
	ds_read_b128 v[188:191], v152
	ds_read_b128 v[196:199], v152 offset:2048
	ds_read_b128 v[192:195], v152 offset:1024
	ds_read_b128 v[200:203], v152 offset:3072
	s_waitcnt lgkmcnt(0)
	s_barrier
	v_mfma_f32_16x16x32_bf16 v[124:127], v[136:139], v[156:159], v[124:127]
	s_setprio 1
	v_mfma_f32_16x16x32_bf16 v[120:123], v[144:147], v[156:159], v[120:123]
	v_mfma_f32_16x16x32_bf16 v[108:111], v[136:139], v[164:167], v[108:111]
	v_mfma_f32_16x16x32_bf16 v[104:107], v[144:147], v[164:167], v[104:107]
	v_mfma_f32_16x16x32_bf16 v[92:95], v[136:139], v[172:175], v[92:95]
	v_mfma_f32_16x16x32_bf16 v[88:91], v[144:147], v[172:175], v[88:91]
	v_mfma_f32_16x16x32_bf16 v[76:79], v[136:139], v[180:183], v[76:79]
	v_mfma_f32_16x16x32_bf16 v[72:75], v[144:147], v[180:183], v[72:75]
	v_mfma_f32_16x16x32_bf16 v[124:127], v[140:143], v[160:163], v[124:127]
	v_mfma_f32_16x16x32_bf16 v[120:123], v[148:151], v[160:163], v[120:123]
	v_mfma_f32_16x16x32_bf16 v[108:111], v[140:143], v[168:171], v[108:111]
	v_mfma_f32_16x16x32_bf16 v[104:107], v[148:151], v[168:171], v[104:107]
	v_mfma_f32_16x16x32_bf16 v[92:95], v[140:143], v[176:179], v[92:95]
	v_mfma_f32_16x16x32_bf16 v[88:91], v[148:151], v[176:179], v[88:91]
	v_mfma_f32_16x16x32_bf16 v[76:79], v[140:143], v[184:187], v[76:79]
	v_mfma_f32_16x16x32_bf16 v[72:75], v[148:151], v[184:187], v[72:75]
	v_mfma_f32_16x16x32_bf16 v[116:119], v[188:191], v[156:159], v[116:119]
	v_mfma_f32_16x16x32_bf16 v[112:115], v[196:199], v[156:159], v[112:115]
	v_mfma_f32_16x16x32_bf16 v[100:103], v[188:191], v[164:167], v[100:103]
	v_mfma_f32_16x16x32_bf16 v[96:99], v[196:199], v[164:167], v[96:99]
	v_mfma_f32_16x16x32_bf16 v[84:87], v[188:191], v[172:175], v[84:87]
	v_mfma_f32_16x16x32_bf16 v[80:83], v[196:199], v[172:175], v[80:83]
	v_mfma_f32_16x16x32_bf16 v[68:71], v[188:191], v[180:183], v[68:71]
	v_mfma_f32_16x16x32_bf16 v[64:67], v[196:199], v[180:183], v[64:67]
	v_mfma_f32_16x16x32_bf16 v[116:119], v[192:195], v[160:163], v[116:119]
	v_mfma_f32_16x16x32_bf16 v[112:115], v[200:203], v[160:163], v[112:115]
	v_mfma_f32_16x16x32_bf16 v[100:103], v[192:195], v[168:171], v[100:103]
	v_mfma_f32_16x16x32_bf16 v[96:99], v[200:203], v[168:171], v[96:99]
	v_mfma_f32_16x16x32_bf16 v[84:87], v[192:195], v[176:179], v[84:87]
	v_mfma_f32_16x16x32_bf16 v[80:83], v[200:203], v[176:179], v[80:83]
	v_mfma_f32_16x16x32_bf16 v[68:71], v[192:195], v[184:187], v[68:71]
	s_setprio 0
	v_mfma_f32_16x16x32_bf16 v[64:67], v[200:203], v[184:187], v[64:67]
	s_barrier
	s_mov_b32 m0, s55
	v_lshl_add_u64 v[204:205], s[28:29], 0, v[128:129]
	global_load_lds_dwordx4 v[204:205], off
	s_add_i32 m0, s55, 0x2000
	v_lshl_add_u64 v[204:205], s[28:29], 0, v[130:131]
	global_load_lds_dwordx4 v[204:205], off
	s_mov_b32 m0, s43
	v_lshl_add_u64 v[204:205], s[26:27], 0, v[128:129]
	global_load_lds_dwordx4 v[204:205], off
	s_mov_b32 m0, s44
	v_lshl_add_u64 v[204:205], s[26:27], 0, v[130:131]
	global_load_lds_dwordx4 v[204:205], off
	s_add_u32 s24, s24, 0x84000
	s_addc_u32 s25, s25, 0
	s_add_i32 s26, s56, s36
	s_mov_b32 m0, s26
	v_lshl_add_u64 v[204:205], s[24:25], 0, v[128:129]
	global_load_lds_dwordx4 v[204:205], off
	s_add_i32 m0, s26, 0x2000
	v_lshl_add_u64 v[204:205], s[24:25], 0, v[130:131]
	global_load_lds_dwordx4 v[204:205], off
	ds_read_b128 v[156:159], v135 offset:49152
	ds_read_b128 v[164:167], v135 offset:51200
	ds_read_b128 v[172:175], v135 offset:53248
	ds_read_b128 v[180:183], v135 offset:55296
	ds_read_b128 v[160:163], v135 offset:50176
	ds_read_b128 v[168:171], v135 offset:52224
	ds_read_b128 v[176:179], v135 offset:54272
	ds_read_b128 v[184:187], v135 offset:56320
	s_waitcnt vmcnt(6)
	s_waitcnt lgkmcnt(0)
	s_barrier
	v_mfma_f32_16x16x32_bf16 v[60:63], v[136:139], v[156:159], v[60:63]
	s_setprio 1
	v_mfma_f32_16x16x32_bf16 v[56:59], v[144:147], v[156:159], v[56:59]
	v_mfma_f32_16x16x32_bf16 v[44:47], v[136:139], v[164:167], v[44:47]
	v_mfma_f32_16x16x32_bf16 v[40:43], v[144:147], v[164:167], v[40:43]
	v_mfma_f32_16x16x32_bf16 v[28:31], v[136:139], v[172:175], v[28:31]
	v_mfma_f32_16x16x32_bf16 v[24:27], v[144:147], v[172:175], v[24:27]
	v_mfma_f32_16x16x32_bf16 v[12:15], v[136:139], v[180:183], v[12:15]
	v_mfma_f32_16x16x32_bf16 v[8:11], v[144:147], v[180:183], v[8:11]
	v_mfma_f32_16x16x32_bf16 v[60:63], v[140:143], v[160:163], v[60:63]
	v_mfma_f32_16x16x32_bf16 v[56:59], v[148:151], v[160:163], v[56:59]
	v_mfma_f32_16x16x32_bf16 v[44:47], v[140:143], v[168:171], v[44:47]
	v_mfma_f32_16x16x32_bf16 v[40:43], v[148:151], v[168:171], v[40:43]
	v_mfma_f32_16x16x32_bf16 v[28:31], v[140:143], v[176:179], v[28:31]
	v_mfma_f32_16x16x32_bf16 v[24:27], v[148:151], v[176:179], v[24:27]
	v_mfma_f32_16x16x32_bf16 v[12:15], v[140:143], v[184:187], v[12:15]
	v_mfma_f32_16x16x32_bf16 v[8:11], v[148:151], v[184:187], v[8:11]
	v_mfma_f32_16x16x32_bf16 v[52:55], v[188:191], v[156:159], v[52:55]
	v_mfma_f32_16x16x32_bf16 v[48:51], v[196:199], v[156:159], v[48:51]
	s_add_i32 s54, s54, 2
	s_add_u32 s22, s22, 0x8000
	s_addc_u32 s23, s23, 0
	s_add_u32 s51, s51, 0x8000
	s_addc_u32 s52, s52, 0
	v_mfma_f32_16x16x32_bf16 v[36:39], v[188:191], v[164:167], v[36:39]
	v_mfma_f32_16x16x32_bf16 v[32:35], v[196:199], v[164:167], v[32:35]
	v_mfma_f32_16x16x32_bf16 v[20:23], v[188:191], v[172:175], v[20:23]
	v_mfma_f32_16x16x32_bf16 v[16:19], v[196:199], v[172:175], v[16:19]
	v_mfma_f32_16x16x32_bf16 v[4:7], v[188:191], v[180:183], v[4:7]
	v_mfma_f32_16x16x32_bf16 v[0:3], v[196:199], v[180:183], v[0:3]
	v_mfma_f32_16x16x32_bf16 v[52:55], v[192:195], v[160:163], v[52:55]
	v_mfma_f32_16x16x32_bf16 v[48:51], v[200:203], v[160:163], v[48:51]
	v_mfma_f32_16x16x32_bf16 v[36:39], v[192:195], v[168:171], v[36:39]
	v_mfma_f32_16x16x32_bf16 v[32:35], v[200:203], v[168:171], v[32:35]
	v_mfma_f32_16x16x32_bf16 v[20:23], v[192:195], v[176:179], v[20:23]
	v_mfma_f32_16x16x32_bf16 v[16:19], v[200:203], v[176:179], v[16:19]
	v_mfma_f32_16x16x32_bf16 v[4:7], v[192:195], v[184:187], v[4:7]
	s_cmp_gt_u32 s54, 29
	s_setprio 0
	v_mfma_f32_16x16x32_bf16 v[0:3], v[200:203], v[184:187], v[0:3]
	s_cbranch_scc1 .Lkexit_141
	s_barrier
	s_branch .LBB0_141
; __device__ __forceinline__ unsigned cvt_pk_bf16(float lo, float hi) { unsigned r; asm volatile("v_cvt_pk_bf16_f32 %0, %1, %2" : "=v"(r) : "v"(lo), "v"(hi)); return r; }
; #define PG8_MMA(ai, bj, At, Bt) do { __builtin_amdgcn_s_setprio(1); _Pragma("unroll") for (int m = 0; m < 4; ++m) _Pragma("unroll") for (int n = 0; n < 2; ++n) _Pragma("unroll") for (int k = 0; k < 2; ++k) \
;         acc[ai][bj][m][n] = __builtin_amdgcn_mfma_f32_16x16x32_bf16(Bt[n][k], At[m][k], acc[ai][bj][m][n], 0, 0, 0); __builtin_amdgcn_s_setprio(0); } while (0)
; #define PG8_WAIT_V(n) asm volatile("s_waitcnt vmcnt(" #n ")" ::: "memory")
; #define PG8_BAR __builtin_amdgcn_s_barrier()
; template <class Epi>
; __device__ __forceinline__ void gemm_phase(LAS unsigned char* lds, const Gemm g, const StaticOrder& S, const Epi& E) {
;     ...
;             PG8_WAIT_V(6); PG8_BAR; PG8_MMA(1, 1, At, B1); PG8_BAR;
;         }
;         E(acc, cur, wr, wc, fr, fq);
;     __device__ __forceinline__ void operator()(const f32x4 (&acc)[2][2][4][2], const Unit& u, int wr, int wc, int fr, int fq) const {
;         const int row0 = u.pm * BM + wr * 64 + fr, col0 = u.pn * BM + wc * 32 + 8 * fq;
; #pragma unroll
;         for (int ai = 0; ai < 2; ++ai)
; #pragma unroll
;             for (int m = 0; m < 4; ++m) {
;                 const int rowi = row0 + ai * HALF + m * 16;
; #pragma unroll
;                 for (int bj = 0; bj < 2; ++bj) {
;                     f32x4 v0 = acc[ai][bj][m][0], v1 = acc[ai][bj][m][1];
; #pragma unroll
;                     for (int j = 0; j < 4; ++j) { const float a = fmaxf(v0[j], 0.f), b = fmaxf(v1[j], 0.f); v0[j] = a * a; v1[j] = b * b; }
;                     u32x4 w; w.x = cvt_pk_bf16(v0[0], v0[1]); w.y = cvt_pk_bf16(v0[2], v0[3]); w.z = cvt_pk_bf16(v1[0], v1[1]); w.w = cvt_pk_bf16(v1[2], v1[3]);
;                     *(u32x4*)(O + tiled_off(rowi, col0 + bj * HALF, DFF / 64)) = w;
;                 }
.Lkexit_141:
	s_cmpk_gt_u32 s31, 0xff
	s_cbranch_scc1 .Lpeel_done_141
	s_barrier
.Lpeel_done_141:
	s_lshl_b32 s24, s20, 8
	s_lshl_b32 s5, s21, 8
	s_add_i32 s24, s24, s41
	s_or_b32 s5, s5, s42
	s_and_b32 s22, s24, 0xffffff80
	s_ashr_i32 s5, s5, 6
	s_add_i32 s20, s22, s5
	s_ashr_i32 s21, s20, 31
	v_max_f32_e32 v120, 0, v120
	s_lshl_b64 s[20:21], s[20:21], 14
	v_readlane_b32 s26, v252, 57
	v_or_b32_e32 v136, s24, v132
	v_mul_f32_e32 v140, v120, v120
	v_max_f32_e32 v121, 0, v121
	v_max_f32_e32 v122, 0, v122
	v_readlane_b32 s27, v252, 58
	s_add_u32 s20, s26, s20
	v_lshlrev_b32_e32 v137, 6, v136
	s_movk_i32 s28, 0x3c0
	v_lshlrev_b32_e32 v138, 2, v136
	v_max_f32_e32 v120, 0, v125
	v_mul_f32_e32 v125, v121, v121
	v_max_f32_e32 v121, v126, v126
	v_mul_f32_e32 v126, v122, v122
	s_addc_u32 s21, s27, s21
	s_or_b32 s15, s5, 2
	v_and_or_b32 v137, v137, s28, v133
	v_and_b32_e32 v138, 32, v138
	v_max_f32_e32 v124, 0, v124
	v_mul_f32_e32 v120, v120, v120
	v_max_f32_e32 v121, 0, v121
	v_max_f32_e32 v122, 0, v127
	v_max_f32_e32 v123, 0, v123
	s_add_i32 s22, s15, s22
	v_bitop3_b32 v139, v137, s46, v138 bitop3:0xde
	v_mul_f32_e32 v124, v124, v124
	v_mul_f32_e32 v121, v121, v121
	v_mul_f32_e32 v122, v122, v122
	v_mul_f32_e32 v123, v123, v123
	v_cvt_pk_bf16_f32 v120, v124, v120
	v_max_f32_e32 v112, 0, v112
	v_max_f32_e32 v113, 0, v113
	s_ashr_i32 s23, s22, 31
	v_cvt_pk_bf16_f32 v121, v121, v122
	v_cvt_pk_bf16_f32 v122, v140, v125
	v_cvt_pk_bf16_f32 v123, v126, v123
	global_store_dwordx4 v139, v[120:123], s[20:21]
	v_max_f32_e32 v114, 0, v114
	s_lshl_b64 s[22:23], s[22:23], 14
	v_mul_f32_e32 v120, v112, v112
	v_max_f32_e32 v112, v117, v117
	v_mul_f32_e32 v117, v113, v113
	v_max_f32_e32 v112, 0, v112
	v_max_f32_e32 v113, 0, v118
	v_mul_f32_e32 v118, v114, v114
	s_add_u32 s22, s26, s22
	v_max_f32_e32 v116, 0, v116
	v_mul_f32_e32 v112, v112, v112
	v_mul_f32_e32 v113, v113, v113
	v_max_f32_e32 v114, 0, v119
	v_max_f32_e32 v115, 0, v115
	s_addc_u32 s23, s27, s23
	s_or_b32 s25, s24, 16
	v_mul_f32_e32 v116, v116, v116
	v_mul_f32_e32 v114, v114, v114
	v_mul_f32_e32 v115, v115, v115
	v_cvt_pk_bf16_f32 v112, v116, v112
	v_cvt_pk_bf16_f32 v113, v113, v114
	s_lshr_b32 s25, s25, 3
	v_max_f32_e32 v104, 0, v104
	v_cvt_pk_bf16_f32 v114, v120, v117
	v_cvt_pk_bf16_f32 v115, v118, v115
	global_store_dwordx4 v139, v[112:115], s[22:23]
	s_and_b32 s25, s25, 10
	v_max_f32_e32 v105, 0, v105
	v_mul_f32_e32 v113, v104, v104
	v_max_f32_e32 v106, 0, v106
	s_or_b32 s25, s25, s45
	v_max_f32_e32 v104, 0, v109
	v_mul_f32_e32 v109, v105, v105
	v_max_f32_e32 v105, v110, v110
	v_mul_f32_e32 v110, v106, v106
	s_lshl_b32 s25, s25, 10
	v_max_f32_e32 v108, 0, v108
	v_mul_f32_e32 v104, v104, v104
	v_max_f32_e32 v105, 0, v105
	v_max_f32_e32 v106, 0, v111
	v_max_f32_e32 v107, 0, v107
	v_bitop3_b32 v112, v137, s25, v138 bitop3:0xde
	v_mul_f32_e32 v108, v108, v108
	v_mul_f32_e32 v105, v105, v105
	v_mul_f32_e32 v106, v106, v106
	v_mul_f32_e32 v107, v107, v107
	v_cvt_pk_bf16_f32 v104, v108, v104
	v_max_f32_e32 v96, 0, v96
	v_max_f32_e32 v97, 0, v97
	v_cvt_pk_bf16_f32 v105, v105, v106
	v_cvt_pk_bf16_f32 v106, v113, v109
	v_cvt_pk_bf16_f32 v107, v110, v107
	global_store_dwordx4 v112, v[104:107], s[20:21]
	s_nop 0
	v_max_f32_e32 v98, 0, v98
	v_mul_f32_e32 v104, v96, v96
	v_max_f32_e32 v96, v101, v101
	v_mul_f32_e32 v101, v97, v97
	v_max_f32_e32 v96, 0, v96
	v_max_f32_e32 v97, 0, v102
	v_mul_f32_e32 v102, v98, v98
	v_max_f32_e32 v100, 0, v100
	v_mul_f32_e32 v96, v96, v96
	v_mul_f32_e32 v97, v97, v97
	v_max_f32_e32 v98, 0, v103
	v_max_f32_e32 v99, 0, v99
	s_or_b32 s25, s24, 32
	v_mul_f32_e32 v100, v100, v100
	v_mul_f32_e32 v98, v98, v98
	v_mul_f32_e32 v99, v99, v99
	v_cvt_pk_bf16_f32 v96, v100, v96
	v_cvt_pk_bf16_f32 v97, v97, v98
	s_lshr_b32 s25, s25, 3
	v_max_f32_e32 v88, 0, v88
	v_cvt_pk_bf16_f32 v98, v104, v101
	v_cvt_pk_bf16_f32 v99, v102, v99
	global_store_dwordx4 v112, v[96:99], s[22:23]
	s_and_b32 s25, s25, 12
	v_max_f32_e32 v89, 0, v89
	v_mul_f32_e32 v97, v88, v88
	v_max_f32_e32 v90, 0, v90
	s_or_b32 s25, s25, s45
	v_max_f32_e32 v88, 0, v93
	v_mul_f32_e32 v93, v89, v89
	v_max_f32_e32 v89, v94, v94
	v_mul_f32_e32 v94, v90, v90
	s_lshl_b32 s25, s25, 10
	v_max_f32_e32 v92, 0, v92
	v_mul_f32_e32 v88, v88, v88
	v_max_f32_e32 v89, 0, v89
	v_max_f32_e32 v90, 0, v95
	v_max_f32_e32 v91, 0, v91
	v_bitop3_b32 v96, v137, s25, v138 bitop3:0xde
	v_mul_f32_e32 v92, v92, v92
	v_mul_f32_e32 v89, v89, v89
	v_mul_f32_e32 v90, v90, v90
	v_mul_f32_e32 v91, v91, v91
	v_cvt_pk_bf16_f32 v88, v92, v88
	v_max_f32_e32 v80, 0, v80
	v_max_f32_e32 v81, 0, v81
	v_cvt_pk_bf16_f32 v89, v89, v90
	v_cvt_pk_bf16_f32 v90, v97, v93
	v_cvt_pk_bf16_f32 v91, v94, v91
	global_store_dwordx4 v96, v[88:91], s[20:21]
	s_nop 0
	v_max_f32_e32 v82, 0, v82
	v_mul_f32_e32 v88, v80, v80
	v_max_f32_e32 v80, v85, v85
	v_mul_f32_e32 v85, v81, v81
	v_max_f32_e32 v80, 0, v80
	v_max_f32_e32 v81, 0, v86
	v_mul_f32_e32 v86, v82, v82
	v_max_f32_e32 v84, 0, v84
	v_mul_f32_e32 v80, v80, v80
	v_mul_f32_e32 v81, v81, v81
	v_max_f32_e32 v82, 0, v87
	v_max_f32_e32 v83, 0, v83
	s_or_b32 s24, s24, 48
	v_mul_f32_e32 v84, v84, v84
	v_mul_f32_e32 v82, v82, v82
	v_mul_f32_e32 v83, v83, v83
	v_cvt_pk_bf16_f32 v80, v84, v80
	v_cvt_pk_bf16_f32 v81, v81, v82
	s_lshr_b32 s24, s24, 3
	v_max_f32_e32 v72, 0, v72
	v_cvt_pk_bf16_f32 v82, v88, v85
	v_cvt_pk_bf16_f32 v83, v86, v83
	global_store_dwordx4 v96, v[80:83], s[22:23]
	s_and_b32 s24, s24, 14
	v_max_f32_e32 v73, 0, v73
	v_mul_f32_e32 v81, v72, v72
	v_max_f32_e32 v74, 0, v74
	s_or_b32 s24, s24, s45
	v_max_f32_e32 v72, 0, v77
	v_mul_f32_e32 v77, v73, v73
	v_max_f32_e32 v73, v78, v78
	v_mul_f32_e32 v78, v74, v74
	s_lshl_b32 s24, s24, 10
; __device__ __forceinline__ unsigned cvt_pk_bf16(float lo, float hi) { unsigned r; asm volatile("v_cvt_pk_bf16_f32 %0, %1, %2" : "=v"(r) : "v"(lo), "v"(hi)); return r; }
;     __device__ __forceinline__ void operator()(const f32x4 (&acc)[2][2][4][2], const Unit& u, int wr, int wc, int fr, int fq) const {
;     ...
;         for (int ai = 0; ai < 2; ++ai)
; #pragma unroll
;             for (int m = 0; m < 4; ++m) {
;                 const int rowi = row0 + ai * HALF + m * 16;
; #pragma unroll
;                 for (int bj = 0; bj < 2; ++bj) {
;                     f32x4 v0 = acc[ai][bj][m][0], v1 = acc[ai][bj][m][1];
; #pragma unroll
;                     for (int j = 0; j < 4; ++j) { const float a = fmaxf(v0[j], 0.f), b = fmaxf(v1[j], 0.f); v0[j] = a * a; v1[j] = b * b; }
;                     u32x4 w; w.x = cvt_pk_bf16(v0[0], v0[1]); w.y = cvt_pk_bf16(v0[2], v0[3]); w.z = cvt_pk_bf16(v1[0], v1[1]); w.w = cvt_pk_bf16(v1[2], v1[3]);
;                     *(u32x4*)(O + tiled_off(rowi, col0 + bj * HALF, DFF / 64)) = w;
;                 }
	v_max_f32_e32 v76, 0, v76
	v_mul_f32_e32 v72, v72, v72
	v_max_f32_e32 v73, 0, v73
	v_max_f32_e32 v74, 0, v79
	v_max_f32_e32 v75, 0, v75
	v_bitop3_b32 v80, v137, s24, v138 bitop3:0xde
	v_mul_f32_e32 v76, v76, v76
	v_mul_f32_e32 v73, v73, v73
	v_mul_f32_e32 v74, v74, v74
	v_mul_f32_e32 v75, v75, v75
	v_cvt_pk_bf16_f32 v72, v76, v72
	v_max_f32_e32 v64, 0, v64
	v_cvt_pk_bf16_f32 v73, v73, v74
	v_cvt_pk_bf16_f32 v74, v81, v77
	v_cvt_pk_bf16_f32 v75, v78, v75
	global_store_dwordx4 v80, v[72:75], s[20:21]
	v_max_f32_e32 v65, 0, v65
	v_max_f32_e32 v66, 0, v66
	v_mul_f32_e32 v72, v64, v64
	v_max_f32_e32 v64, 0, v69
	v_mul_f32_e32 v69, v65, v65
	v_max_f32_e32 v65, v70, v70
	v_mul_f32_e32 v70, v66, v66
	v_max_f32_e32 v68, 0, v68
	v_mul_f32_e32 v64, v64, v64
	v_max_f32_e32 v65, 0, v65
	v_max_f32_e32 v66, 0, v71
	v_max_f32_e32 v67, 0, v67
	v_mul_f32_e32 v68, v68, v68
	v_mul_f32_e32 v65, v65, v65
	v_mul_f32_e32 v66, v66, v66
	v_mul_f32_e32 v67, v67, v67
	v_cvt_pk_bf16_f32 v64, v68, v64
	v_cvt_pk_bf16_f32 v65, v65, v66
	v_cvt_pk_bf16_f32 v66, v72, v69
	v_cvt_pk_bf16_f32 v67, v70, v67
	global_store_dwordx4 v80, v[64:67], s[22:23]
	s_nop 0
	v_max_f32_e32 v56, 0, v56
	v_add_u32_e32 v64, 0x80, v136
	v_and_b32_e32 v65, 0xffffff80, v64
	v_lshlrev_b32_e32 v66, 6, v64
	v_lshlrev_b32_e32 v64, 2, v64
	v_and_or_b32 v66, v66, s28, v133
	v_and_b32_e32 v64, 32, v64
	v_bitop3_b32 v152, v66, s46, v64 bitop3:0xde
	v_mul_f32_e32 v64, v56, v56
	v_max_f32_e32 v57, 0, v57
	v_max_f32_e32 v58, 0, v58
	v_max_f32_e32 v60, 0, v60
	v_max_f32_e32 v56, 0, v61
	v_mul_f32_e32 v61, v57, v57
	v_max_f32_e32 v57, v62, v62
	v_mul_f32_e32 v62, v58, v58
	v_mul_f32_e32 v60, v60, v60
	v_mul_f32_e32 v56, v56, v56
	v_max_f32_e32 v57, 0, v57
	v_max_f32_e32 v58, 0, v63
	v_mul_f32_e32 v57, v57, v57
	v_mul_f32_e32 v58, v58, v58
	v_cvt_pk_bf16_f32 v56, v60, v56
	v_add_u32_e32 v60, s5, v65
	v_cvt_pk_bf16_f32 v57, v57, v58
	v_cvt_pk_bf16_f32 v58, v64, v61
	v_ashrrev_i32_e32 v61, 31, v60
	v_max_f32_e32 v59, 0, v59
	v_lshlrev_b64 v[60:61], 14, v[60:61]
	v_mul_f32_e32 v59, v59, v59
	v_lshl_add_u64 v[60:61], s[26:27], 0, v[60:61]
	v_cvt_pk_bf16_f32 v59, v62, v59
	v_lshl_add_u64 v[62:63], v[60:61], 0, v[152:153]
	v_max_f32_e32 v48, 0, v48
	global_store_dwordx4 v[62:63], v[56:59], off
	s_nop 0
	v_max_f32_e32 v49, 0, v49
	v_mul_f32_e32 v56, v48, v48
	v_max_f32_e32 v50, 0, v50
	v_max_f32_e32 v52, 0, v52
	v_max_f32_e32 v48, 0, v53
	v_mul_f32_e32 v53, v49, v49
	v_max_f32_e32 v49, v54, v54
	v_mul_f32_e32 v54, v50, v50
	v_mul_f32_e32 v52, v52, v52
	v_mul_f32_e32 v48, v48, v48
	v_max_f32_e32 v49, 0, v49
	v_max_f32_e32 v50, 0, v55
	v_mul_f32_e32 v49, v49, v49
	v_mul_f32_e32 v50, v50, v50
	v_cvt_pk_bf16_f32 v48, v52, v48
	v_add_u32_e32 v52, s15, v65
	v_cvt_pk_bf16_f32 v49, v49, v50
	v_cvt_pk_bf16_f32 v50, v56, v53
	v_ashrrev_i32_e32 v53, 31, v52
	v_max_f32_e32 v51, 0, v51
	v_lshlrev_b64 v[52:53], 14, v[52:53]
	v_mul_f32_e32 v51, v51, v51
	v_lshl_add_u64 v[52:53], s[26:27], 0, v[52:53]
	v_cvt_pk_bf16_f32 v51, v54, v51
	v_lshl_add_u64 v[54:55], v[52:53], 0, v[152:153]
	global_store_dwordx4 v[54:55], v[48:51], off
	s_nop 1
	v_add_u32_e32 v48, 0x90, v136
	v_lshrrev_b32_e32 v49, 3, v48
	v_and_or_b32 v49, v49, 10, s45
	v_lshlrev_b32_e32 v50, 6, v48
	v_lshlrev_b32_e32 v48, 2, v48
	v_and_or_b32 v50, v50, s28, v133
	v_lshlrev_b32_e32 v49, 10, v49
	v_and_b32_e32 v48, 32, v48
	v_max_f32_e32 v40, 0, v40
	v_max_f32_e32 v41, 0, v41
	v_max_f32_e32 v42, 0, v42
	v_bitop3_b32 v152, v50, v49, v48 bitop3:0xde
	v_mul_f32_e32 v48, v40, v40
	v_max_f32_e32 v40, v45, v45
	v_mul_f32_e32 v45, v41, v41
	v_max_f32_e32 v41, v46, v46
	v_mul_f32_e32 v46, v42, v42
	v_max_f32_e32 v44, 0, v44
	v_max_f32_e32 v40, 0, v40
	v_max_f32_e32 v41, 0, v41
	v_max_f32_e32 v42, 0, v47
	v_mul_f32_e32 v44, v44, v44
	v_mul_f32_e32 v40, v40, v40
	v_mul_f32_e32 v41, v41, v41
	v_max_f32_e32 v43, 0, v43
	v_mul_f32_e32 v42, v42, v42
	v_mul_f32_e32 v43, v43, v43
	v_cvt_pk_bf16_f32 v40, v44, v40
	v_cvt_pk_bf16_f32 v41, v41, v42
	v_cvt_pk_bf16_f32 v42, v48, v45
	v_lshl_add_u64 v[44:45], v[60:61], 0, v[152:153]
	v_max_f32_e32 v32, 0, v32
	v_max_f32_e32 v33, 0, v33
	v_max_f32_e32 v34, 0, v34
	v_cvt_pk_bf16_f32 v43, v46, v43
	global_store_dwordx4 v[44:45], v[40:43], off
	s_nop 0
	v_max_f32_e32 v36, 0, v36
	v_mul_f32_e32 v40, v32, v32
	v_max_f32_e32 v32, v37, v37
	v_mul_f32_e32 v37, v33, v33
	v_max_f32_e32 v33, v38, v38
; __device__ __forceinline__ unsigned cvt_pk_bf16(float lo, float hi) { unsigned r; asm volatile("v_cvt_pk_bf16_f32 %0, %1, %2" : "=v"(r) : "v"(lo), "v"(hi)); return r; }
; #define PG8_WAIT_V(n) asm volatile("s_waitcnt vmcnt(" #n ")" ::: "memory")
; #define PG8_BAR __builtin_amdgcn_s_barrier()
; template <class Epi>
; __device__ __forceinline__ void gemm_phase(LAS unsigned char* lds, const Gemm g, const StaticOrder& S, const Epi& E) {
;     ...
;         E(acc, cur, wr, wc, fr, fq);
;         if (!has_next) break;
; #pragma unroll
;         for (int a = 0; a < 2; ++a)
; #pragma unroll
;             for (int b = 0; b < 2; ++b)
; #pragma unroll
;                 for (int m = 0; m < 4; ++m)
; #pragma unroll
;                     for (int n = 0; n < 2; ++n) acc[a][b][m][n] = (f32x4){0.f, 0.f, 0.f, 0.f};
;         cur = nxt; cA = nA; cB = nB; ++ui;
;     }
;     PG8_WAIT_V(0);
;     if (wr == 0) PG8_BAR;
;     __device__ __forceinline__ void operator()(const f32x4 (&acc)[2][2][4][2], const Unit& u, int wr, int wc, int fr, int fq) const {
;     ...
;         for (int ai = 0; ai < 2; ++ai)
; #pragma unroll
;             for (int m = 0; m < 4; ++m) {
;                 const int rowi = row0 + ai * HALF + m * 16;
; #pragma unroll
;                 for (int bj = 0; bj < 2; ++bj) {
;                     f32x4 v0 = acc[ai][bj][m][0], v1 = acc[ai][bj][m][1];
; #pragma unroll
;                     for (int j = 0; j < 4; ++j) { const float a = fmaxf(v0[j], 0.f), b = fmaxf(v1[j], 0.f); v0[j] = a * a; v1[j] = b * b; }
;                     u32x4 w; w.x = cvt_pk_bf16(v0[0], v0[1]); w.y = cvt_pk_bf16(v0[2], v0[3]); w.z = cvt_pk_bf16(v1[0], v1[1]); w.w = cvt_pk_bf16(v1[2], v1[3]);
;                     *(u32x4*)(O + tiled_off(rowi, col0 + bj * HALF, DFF / 64)) = w;
;                 }
	v_mul_f32_e32 v38, v34, v34
	v_max_f32_e32 v32, 0, v32
	v_max_f32_e32 v33, 0, v33
	v_max_f32_e32 v34, 0, v39
	v_mul_f32_e32 v36, v36, v36
	v_mul_f32_e32 v32, v32, v32
	v_mul_f32_e32 v33, v33, v33
	v_max_f32_e32 v35, 0, v35
	v_mul_f32_e32 v34, v34, v34
	v_mul_f32_e32 v35, v35, v35
	v_cvt_pk_bf16_f32 v32, v36, v32
	v_cvt_pk_bf16_f32 v33, v33, v34
	v_cvt_pk_bf16_f32 v34, v40, v37
	v_lshl_add_u64 v[36:37], v[52:53], 0, v[152:153]
	v_cvt_pk_bf16_f32 v35, v38, v35
	global_store_dwordx4 v[36:37], v[32:35], off
	s_nop 1
	v_add_u32_e32 v32, 0xa0, v136
	v_lshrrev_b32_e32 v33, 3, v32
	v_and_or_b32 v33, v33, 12, s45
	v_lshlrev_b32_e32 v34, 6, v32
	v_lshlrev_b32_e32 v32, 2, v32
	v_and_or_b32 v34, v34, s28, v133
	v_lshlrev_b32_e32 v33, 10, v33
	v_and_b32_e32 v32, 32, v32
	v_max_f32_e32 v24, 0, v24
	v_max_f32_e32 v25, 0, v25
	v_max_f32_e32 v26, 0, v26
	v_bitop3_b32 v152, v34, v33, v32 bitop3:0xde
	v_mul_f32_e32 v32, v24, v24
	v_max_f32_e32 v24, v29, v29
	v_mul_f32_e32 v29, v25, v25
	v_max_f32_e32 v25, v30, v30
	v_mul_f32_e32 v30, v26, v26
	v_max_f32_e32 v28, 0, v28
	v_max_f32_e32 v24, 0, v24
	v_max_f32_e32 v25, 0, v25
	v_max_f32_e32 v26, 0, v31
	v_mul_f32_e32 v28, v28, v28
	v_mul_f32_e32 v24, v24, v24
	v_mul_f32_e32 v25, v25, v25
	v_max_f32_e32 v27, 0, v27
	v_mul_f32_e32 v26, v26, v26
	v_mul_f32_e32 v27, v27, v27
	v_cvt_pk_bf16_f32 v24, v28, v24
	v_cvt_pk_bf16_f32 v25, v25, v26
	v_cvt_pk_bf16_f32 v26, v32, v29
	v_lshl_add_u64 v[28:29], v[60:61], 0, v[152:153]
	v_max_f32_e32 v16, 0, v16
	v_max_f32_e32 v17, 0, v17
	v_max_f32_e32 v18, 0, v18
	v_cvt_pk_bf16_f32 v27, v30, v27
	global_store_dwordx4 v[28:29], v[24:27], off
	s_nop 0
	v_max_f32_e32 v20, 0, v20
	v_mul_f32_e32 v24, v16, v16
	v_max_f32_e32 v16, v21, v21
	v_mul_f32_e32 v21, v17, v17
	v_max_f32_e32 v17, v22, v22
	v_mul_f32_e32 v22, v18, v18
	v_max_f32_e32 v16, 0, v16
	v_max_f32_e32 v17, 0, v17
	v_max_f32_e32 v18, 0, v23
	v_mul_f32_e32 v20, v20, v20
	v_mul_f32_e32 v16, v16, v16
	v_mul_f32_e32 v17, v17, v17
	v_max_f32_e32 v19, 0, v19
	v_mul_f32_e32 v18, v18, v18
	v_mul_f32_e32 v19, v19, v19
	v_cvt_pk_bf16_f32 v16, v20, v16
	v_cvt_pk_bf16_f32 v17, v17, v18
	v_cvt_pk_bf16_f32 v18, v24, v21
	v_lshl_add_u64 v[20:21], v[52:53], 0, v[152:153]
	v_cvt_pk_bf16_f32 v19, v22, v19
	global_store_dwordx4 v[20:21], v[16:19], off
	s_nop 1
	v_add_u32_e32 v16, 0xb0, v136
	v_lshrrev_b32_e32 v17, 3, v16
	v_and_or_b32 v17, v17, 14, s45
	v_lshlrev_b32_e32 v18, 6, v16
	v_lshlrev_b32_e32 v16, 2, v16
	v_and_or_b32 v18, v18, s28, v133
	v_lshlrev_b32_e32 v17, 10, v17
	v_and_b32_e32 v16, 32, v16
	v_max_f32_e32 v8, 0, v8
	v_max_f32_e32 v9, 0, v9
	v_max_f32_e32 v10, 0, v10
	v_bitop3_b32 v152, v18, v17, v16 bitop3:0xde
	v_mul_f32_e32 v16, v8, v8
	v_max_f32_e32 v8, v13, v13
	v_mul_f32_e32 v13, v9, v9
	v_max_f32_e32 v9, v14, v14
	v_mul_f32_e32 v14, v10, v10
	v_max_f32_e32 v12, 0, v12
	v_max_f32_e32 v8, 0, v8
	v_max_f32_e32 v9, 0, v9
	v_max_f32_e32 v10, 0, v15
	v_mul_f32_e32 v12, v12, v12
	v_mul_f32_e32 v8, v8, v8
	v_mul_f32_e32 v9, v9, v9
	v_max_f32_e32 v11, 0, v11
	v_mul_f32_e32 v10, v10, v10
	v_mul_f32_e32 v11, v11, v11
	v_cvt_pk_bf16_f32 v8, v12, v8
	v_cvt_pk_bf16_f32 v9, v9, v10
	v_cvt_pk_bf16_f32 v10, v16, v13
	v_lshl_add_u64 v[12:13], v[60:61], 0, v[152:153]
	v_max_f32_e32 v0, 0, v0
	v_max_f32_e32 v1, 0, v1
	v_max_f32_e32 v2, 0, v2
	v_cvt_pk_bf16_f32 v11, v14, v11
	global_store_dwordx4 v[12:13], v[8:11], off
	s_nop 0
	v_max_f32_e32 v4, 0, v4
	v_mul_f32_e32 v8, v0, v0
	v_max_f32_e32 v0, v5, v5
	v_mul_f32_e32 v5, v1, v1
	v_max_f32_e32 v1, v6, v6
	v_mul_f32_e32 v6, v2, v2
	v_max_f32_e32 v0, 0, v0
	v_max_f32_e32 v1, 0, v1
	v_max_f32_e32 v2, 0, v7
	v_mul_f32_e32 v4, v4, v4
	v_mul_f32_e32 v0, v0, v0
	v_mul_f32_e32 v1, v1, v1
	v_max_f32_e32 v3, 0, v3
	v_mul_f32_e32 v2, v2, v2
	s_mov_b32 s54, 0xd00ab22c
	v_mul_f32_e32 v3, v3, v3
	v_cvt_pk_bf16_f32 v0, v4, v0
	v_cvt_pk_bf16_f32 v1, v1, v2
	v_cvt_pk_bf16_f32 v2, v8, v5
	v_lshl_add_u64 v[4:5], v[52:53], 0, v[152:153]
	s_and_b64 vcc, exec, s[0:1]
	s_mov_b32 s21, s4
	s_mov_b32 s20, s14
	s_mov_b64 s[24:25], s[18:19]
	s_mov_b64 s[22:23], s[16:17]
	s_mov_b32 s55, 0x3febb5fa
	v_cvt_pk_bf16_f32 v3, v6, v3
	global_store_dwordx4 v[4:5], v[0:3], off
	s_cmpk_gt_u32 s31, 0xff
	s_cbranch_scc0 .Lyb_141
	s_barrier
.Lyb_141:
	s_cbranch_vccz .LBB0_134
	s_waitcnt vmcnt(0)
	s_cmpk_gt_u32 s31, 0xff
	s_cbranch_scc1 .LBB0_145
	s_barrier

; __device__ __forceinline__ unsigned cvt_pk_bf16(float lo, float hi) { unsigned r; asm volatile("v_cvt_pk_bf16_f32 %0, %1, %2" : "=v"(r) : "v"(lo), "v"(hi)); return r; }
; __device__ __forceinline__ float bflo(unsigned w) { return __uint_as_float(w << 16); }
;     __device__ __forceinline__ void operator()(const f32x4 (&acc)[2][2][4][2], const Unit& u, int wr, int wc, int fr, int fq) const {
;     ...
;         for (int grp = 0; grp < 3; ++grp) {
;             u32x4 xv[8]; f32x4 cg[2][2], cl[2][2], cb[2][2];
;             if (grp == 0 || grp == 2) {
; #pragma unroll
;                 for (int m = 0; m < 4; ++m) st[m] = ln ? *(const f32x2*)(stats + 2 * (row0 + (grp ? HALF : 0) + m * 16)) : (f32x2){0.f, 1.f};
;             }
; #pragma unroll
;             for (int j = GB[grp]; j < GB[grp + 1]; ++j) {
;                 const int k = j >> 2, m = j & 3, ai = k >> 1, col = col0 + (k & 1) * HALF, kk = k - (GB[grp] >> 2);
;                 if (m == 0) {
; #pragma unroll
;                     for (int n = 0; n < 2; ++n) { cg[kk][n] = *(const f32x4*)(gb + col + 4 * n) + 1.0f; cl[kk][n] = (f32x4){1.f, 1.f, 1.f, 1.f}; cb[kk][n] = (f32x4){0.f, 0.f, 0.f, 0.f};
;                         if (ln) { cl[kk][n] = *(const f32x4*)(lng + col + 4 * n); cb[kk][n] = *(const f32x4*)(lnb + col + 4 * n); } }
;                 }
;                 xv[j - GB[grp]] = *(const u32x4*)(z + (size_t)(row0 + ai * HALF + m * 16) * DM + col);
;             }
; #pragma unroll
;             for (int j = GB[grp]; j < GB[grp + 1]; ++j) {
;                 const int k = j >> 2, m = j & 3, ai = k >> 1, bj = k & 1, col = col0 + bj * HALF, kk = k - (GB[grp] >> 2);
;                 const u32x4 r = xv[j - GB[grp]];
;                 f32x4 x0 = {bflo(r.x), bfhi(r.x), bflo(r.y), bfhi(r.y)}, x1 = {bflo(r.z), bfhi(r.z), bflo(r.w), bfhi(r.w)};
;                 x0 = (x0 - st[m].x) * st[m].y * cl[kk][0] + cb[kk][0]; x1 = (x1 - st[m].x) * st[m].y * cl[kk][1] + cb[kk][1];
;                 const f32x4 o0 = x0 * ALPHA + cg[kk][0] * acc[ai][bj][m][0], o1 = x1 * ALPHA + cg[kk][1] * acc[ai][bj][m][1];
;                 u32x4 w; w.x = cvt_pk_bf16(o0[0], o0[1]); w.y = cvt_pk_bf16(o0[2], o0[3]); w.z = cvt_pk_bf16(o1[0], o1[1]); w.w = cvt_pk_bf16(o1[2], o1[3]);
;                 *(u32x4*)(z + (size_t)(row0 + ai * HALF + m * 16) * DM + col) = w;
.LBB0_175:
	s_mov_b64 s[4:5], 0x80000
	v_lshl_add_u64 v[168:169], v[150:151], 0, s[4:5]
	s_waitcnt vmcnt(0)
	v_cndmask_b32_e64 v142, v142, v145, s[12:13]
	v_cndmask_b32_e64 v136, v136, v139, s[12:13]
	v_cndmask_b32_e64 v132, v132, v135, s[12:13]
	v_cndmask_b32_e64 v128, v128, v131, s[12:13]
	v_pk_add_f32 v[150:151], v[114:115], 1.0 op_sel_hi:[1,0]
	v_pk_add_f32 v[162:163], v[112:113], 1.0 op_sel_hi:[1,0]
	v_pk_add_f32 v[164:165], v[106:107], 1.0 op_sel_hi:[1,0]
	v_pk_add_f32 v[166:167], v[104:105], 1.0 op_sel_hi:[1,0]
	v_pk_add_f32 v[170:171], v[102:103], 1.0 op_sel_hi:[1,0]
	v_pk_add_f32 v[172:173], v[100:101], 1.0 op_sel_hi:[1,0]
	v_pk_add_f32 v[174:175], v[82:83], 1.0 op_sel_hi:[1,0]
	v_pk_add_f32 v[176:177], v[80:81], 1.0 op_sel_hi:[1,0]
	global_load_dwordx4 v[112:115], v[168:169], off offset:256
	global_load_dwordx4 v[104:107], v[148:149], off offset:256
	global_load_dwordx4 v[100:103], v[146:147], off offset:256
	global_load_dwordx4 v[80:83], v[140:141], off offset:256
	v_lshlrev_b32_e32 v129, 16, v124
	v_and_b32_e32 v131, 0xffff0000, v124
	v_lshlrev_b32_e32 v124, 16, v125
	v_and_b32_e32 v125, 0xffff0000, v125
	v_lshlrev_b32_e32 v133, 16, v126
	v_and_b32_e32 v135, 0xffff0000, v126
	v_lshlrev_b32_e32 v137, 16, v127
	v_and_b32_e32 v139, 0xffff0000, v127
	v_sub_f32_e32 v125, v125, v144
	v_sub_f32_e32 v124, v124, v144
	v_sub_f32_e32 v127, v131, v144
	v_sub_f32_e32 v126, v129, v144
	v_pk_mul_f32 v[126:127], v[142:143], v[126:127] op_sel_hi:[0,1]
	v_pk_mul_f32 v[124:125], v[142:143], v[124:125] op_sel_hi:[0,1]
	v_sub_f32_e32 v179, v139, v144
	v_sub_f32_e32 v178, v137, v144
	v_sub_f32_e32 v181, v135, v144
	v_sub_f32_e32 v180, v133, v144
	v_pk_fma_f32 v[124:125], v[94:95], v[124:125], v[98:99]
	v_pk_fma_f32 v[126:127], v[92:93], v[126:127], v[96:97]
	v_pk_mul_f32 v[180:181], v[142:143], v[180:181] op_sel_hi:[0,1]
	v_pk_mul_f32 v[178:179], v[142:143], v[178:179] op_sel_hi:[0,1]
	v_pk_fma_f32 v[178:179], v[86:87], v[178:179], v[90:91]
	v_pk_fma_f32 v[180:181], v[84:85], v[180:181], v[88:89]
	v_pk_mul_f32 v[126:127], v[126:127], s[22:23] op_sel_hi:[1,0]
	v_pk_mul_f32 v[124:125], v[124:125], s[22:23] op_sel_hi:[1,0]
	v_pk_fma_f32 v[60:61], v[60:61], v[176:177], v[126:127]
	v_pk_fma_f32 v[62:63], v[62:63], v[174:175], v[124:125]
	v_pk_mul_f32 v[124:125], v[180:181], s[22:23] op_sel_hi:[1,0]
	v_pk_mul_f32 v[126:127], v[178:179], s[22:23] op_sel_hi:[1,0]
	s_and_b64 vcc, exec, s[0:1]
	v_pk_fma_f32 v[126:127], v[58:59], v[170:171], v[126:127]
	v_pk_fma_f32 v[58:59], v[56:57], v[172:173], v[124:125]
	v_cvt_pk_bf16_f32 v56, v60, v61
	v_cvt_pk_bf16_f32 v57, v62, v63
	v_lshlrev_b32_e32 v62, 16, v122
	v_cvt_pk_bf16_f32 v58, v58, v59
	v_cvt_pk_bf16_f32 v59, v126, v127
	global_store_dwordx4 v[168:169], v[56:59], off
	v_and_b32_e32 v63, 0xffff0000, v122
	v_lshlrev_b32_e32 v60, 16, v123
	v_lshlrev_b32_e32 v58, 16, v120
	v_and_b32_e32 v59, 0xffff0000, v120
	v_lshlrev_b32_e32 v56, 16, v121
	v_and_b32_e32 v57, 0xffff0000, v121
	v_and_b32_e32 v61, 0xffff0000, v123
	v_sub_f32_e32 v57, v57, v138
	v_sub_f32_e32 v56, v56, v138
	v_sub_f32_e32 v59, v59, v138
	v_sub_f32_e32 v58, v58, v138
	v_pk_mul_f32 v[58:59], v[136:137], v[58:59] op_sel_hi:[0,1]
	v_pk_mul_f32 v[56:57], v[136:137], v[56:57] op_sel_hi:[0,1]
	v_sub_f32_e32 v61, v61, v138
	v_sub_f32_e32 v60, v60, v138
	v_sub_f32_e32 v63, v63, v138
	v_sub_f32_e32 v62, v62, v138
	v_pk_fma_f32 v[56:57], v[94:95], v[56:57], v[98:99]
	v_pk_fma_f32 v[58:59], v[92:93], v[58:59], v[96:97]
	v_pk_mul_f32 v[62:63], v[136:137], v[62:63] op_sel_hi:[0,1]
	v_pk_mul_f32 v[60:61], v[136:137], v[60:61] op_sel_hi:[0,1]
	v_pk_fma_f32 v[60:61], v[86:87], v[60:61], v[90:91]
	v_pk_fma_f32 v[62:63], v[84:85], v[62:63], v[88:89]
	v_pk_mul_f32 v[58:59], v[58:59], s[22:23] op_sel_hi:[1,0]
	v_pk_mul_f32 v[56:57], v[56:57], s[22:23] op_sel_hi:[1,0]
	v_pk_fma_f32 v[52:53], v[52:53], v[176:177], v[58:59]
	v_pk_fma_f32 v[54:55], v[54:55], v[174:175], v[56:57]
	v_pk_mul_f32 v[56:57], v[62:63], s[22:23] op_sel_hi:[1,0]
	v_pk_mul_f32 v[58:59], v[60:61], s[22:23] op_sel_hi:[1,0]
	s_mov_b32 s48, s46
	v_pk_fma_f32 v[58:59], v[50:51], v[170:171], v[58:59]
	v_pk_fma_f32 v[50:51], v[48:49], v[172:173], v[56:57]
	v_cvt_pk_bf16_f32 v48, v52, v53
	v_cvt_pk_bf16_f32 v49, v54, v55
	v_lshlrev_b32_e32 v54, 16, v118
	v_cvt_pk_bf16_f32 v50, v50, v51
	v_cvt_pk_bf16_f32 v51, v58, v59
	global_store_dwordx4 v[148:149], v[48:51], off
	v_and_b32_e32 v55, 0xffff0000, v118
	v_lshlrev_b32_e32 v52, 16, v119
	v_lshlrev_b32_e32 v50, 16, v116
	v_and_b32_e32 v51, 0xffff0000, v116
	v_lshlrev_b32_e32 v48, 16, v117
	v_and_b32_e32 v49, 0xffff0000, v117
	v_and_b32_e32 v53, 0xffff0000, v119
	v_sub_f32_e32 v49, v49, v134
	v_sub_f32_e32 v48, v48, v134
	v_sub_f32_e32 v51, v51, v134
	v_sub_f32_e32 v50, v50, v134
	v_pk_mul_f32 v[50:51], v[132:133], v[50:51] op_sel_hi:[0,1]
	v_pk_mul_f32 v[48:49], v[132:133], v[48:49] op_sel_hi:[0,1]
	v_sub_f32_e32 v53, v53, v134
	v_sub_f32_e32 v52, v52, v134
	v_sub_f32_e32 v55, v55, v134
	v_sub_f32_e32 v54, v54, v134
	v_pk_fma_f32 v[48:49], v[94:95], v[48:49], v[98:99]
	v_pk_fma_f32 v[50:51], v[92:93], v[50:51], v[96:97]
	v_pk_mul_f32 v[54:55], v[132:133], v[54:55] op_sel_hi:[0,1]
	v_pk_mul_f32 v[52:53], v[132:133], v[52:53] op_sel_hi:[0,1]
	v_pk_fma_f32 v[52:53], v[86:87], v[52:53], v[90:91]
	v_pk_fma_f32 v[54:55], v[84:85], v[54:55], v[88:89]
	v_pk_mul_f32 v[50:51], v[50:51], s[22:23] op_sel_hi:[1,0]
	v_pk_mul_f32 v[48:49], v[48:49], s[22:23] op_sel_hi:[1,0]
	v_pk_fma_f32 v[44:45], v[44:45], v[176:177], v[50:51]
	v_pk_fma_f32 v[46:47], v[46:47], v[174:175], v[48:49]
	v_pk_mul_f32 v[48:49], v[54:55], s[22:23] op_sel_hi:[1,0]
	v_pk_mul_f32 v[50:51], v[52:53], s[22:23] op_sel_hi:[1,0]
; __device__ __forceinline__ unsigned cvt_pk_bf16(float lo, float hi) { unsigned r; asm volatile("v_cvt_pk_bf16_f32 %0, %1, %2" : "=v"(r) : "v"(lo), "v"(hi)); return r; }
; __device__ __forceinline__ float bflo(unsigned w) { return __uint_as_float(w << 16); }
; __device__ __forceinline__ float bfhi(unsigned w) { return __uint_as_float(w & 0xffff0000u); }
;     __device__ __forceinline__ void operator()(const f32x4 (&acc)[2][2][4][2], const Unit& u, int wr, int wc, int fr, int fq) const {
;     ...
;             for (int j = GB[grp]; j < GB[grp + 1]; ++j) {
;                 const int k = j >> 2, m = j & 3, ai = k >> 1, bj = k & 1, col = col0 + bj * HALF, kk = k - (GB[grp] >> 2);
;                 const u32x4 r = xv[j - GB[grp]];
;                 f32x4 x0 = {bflo(r.x), bfhi(r.x), bflo(r.y), bfhi(r.y)}, x1 = {bflo(r.z), bfhi(r.z), bflo(r.w), bfhi(r.w)};
;                 x0 = (x0 - st[m].x) * st[m].y * cl[kk][0] + cb[kk][0]; x1 = (x1 - st[m].x) * st[m].y * cl[kk][1] + cb[kk][1];
;                 const f32x4 o0 = x0 * ALPHA + cg[kk][0] * acc[ai][bj][m][0], o1 = x1 * ALPHA + cg[kk][1] * acc[ai][bj][m][1];
;                 u32x4 w; w.x = cvt_pk_bf16(o0[0], o0[1]); w.y = cvt_pk_bf16(o0[2], o0[3]); w.z = cvt_pk_bf16(o1[0], o1[1]); w.w = cvt_pk_bf16(o1[2], o1[3]);
;                 *(u32x4*)(z + (size_t)(row0 + ai * HALF + m * 16) * DM + col) = w;
	s_mov_b32 s49, s47
	v_pk_fma_f32 v[50:51], v[42:43], v[170:171], v[50:51]
	v_pk_fma_f32 v[42:43], v[40:41], v[172:173], v[48:49]
	v_cvt_pk_bf16_f32 v40, v44, v45
	v_cvt_pk_bf16_f32 v41, v46, v47
	v_lshlrev_b32_e32 v46, 16, v110
	v_cvt_pk_bf16_f32 v42, v42, v43
	v_cvt_pk_bf16_f32 v43, v50, v51
	global_store_dwordx4 v[146:147], v[40:43], off
	v_and_b32_e32 v47, 0xffff0000, v110
	v_lshlrev_b32_e32 v44, 16, v111
	v_lshlrev_b32_e32 v42, 16, v108
	v_and_b32_e32 v43, 0xffff0000, v108
	v_lshlrev_b32_e32 v40, 16, v109
	v_and_b32_e32 v41, 0xffff0000, v109
	v_and_b32_e32 v45, 0xffff0000, v111
	v_sub_f32_e32 v41, v41, v130
	v_sub_f32_e32 v40, v40, v130
	v_sub_f32_e32 v43, v43, v130
	v_sub_f32_e32 v42, v42, v130
	v_pk_mul_f32 v[42:43], v[128:129], v[42:43] op_sel_hi:[0,1]
	v_pk_mul_f32 v[40:41], v[128:129], v[40:41] op_sel_hi:[0,1]
	v_sub_f32_e32 v45, v45, v130
	v_sub_f32_e32 v44, v44, v130
	v_sub_f32_e32 v47, v47, v130
	v_sub_f32_e32 v46, v46, v130
	v_pk_fma_f32 v[40:41], v[94:95], v[40:41], v[98:99]
	v_pk_fma_f32 v[42:43], v[92:93], v[42:43], v[96:97]
	v_pk_mul_f32 v[46:47], v[128:129], v[46:47] op_sel_hi:[0,1]
	v_pk_mul_f32 v[44:45], v[128:129], v[44:45] op_sel_hi:[0,1]
	v_pk_fma_f32 v[44:45], v[86:87], v[44:45], v[90:91]
	v_pk_fma_f32 v[46:47], v[84:85], v[46:47], v[88:89]
	v_pk_mul_f32 v[42:43], v[42:43], s[22:23] op_sel_hi:[1,0]
	v_pk_mul_f32 v[40:41], v[40:41], s[22:23] op_sel_hi:[1,0]
	v_pk_fma_f32 v[36:37], v[36:37], v[176:177], v[42:43]
	v_pk_fma_f32 v[38:39], v[38:39], v[174:175], v[40:41]
	v_pk_mul_f32 v[40:41], v[46:47], s[22:23] op_sel_hi:[1,0]
	v_pk_mul_f32 v[42:43], v[44:45], s[22:23] op_sel_hi:[1,0]
	s_mov_b64 s[24:25], s[6:7]
	v_pk_fma_f32 v[42:43], v[34:35], v[170:171], v[42:43]
	v_pk_fma_f32 v[34:35], v[32:33], v[172:173], v[40:41]
	v_cvt_pk_bf16_f32 v32, v36, v37
	v_cvt_pk_bf16_f32 v33, v38, v39
	s_waitcnt vmcnt(0)
; __device__ __forceinline__ unsigned cvt_pk_bf16(float lo, float hi) { unsigned r; asm volatile("v_cvt_pk_bf16_f32 %0, %1, %2" : "=v"(r) : "v"(lo), "v"(hi)); return r; }
; __device__ __forceinline__ float bflo(unsigned w) { return __uint_as_float(w << 16); }
; __device__ __forceinline__ float bfhi(unsigned w) { return __uint_as_float(w & 0xffff0000u); }
; template <class Epi>
; __device__ __forceinline__ void gemm_phase(LAS unsigned char* lds, const Gemm g, const StaticOrder& S, const Epi& E) {
;     ...
;         E(acc, cur, wr, wc, fr, fq);
;         if (!has_next) break;
;     __device__ __forceinline__ void operator()(const f32x4 (&acc)[2][2][4][2], const Unit& u, int wr, int wc, int fr, int fq) const {
;     ...
;             for (int j = GB[grp]; j < GB[grp + 1]; ++j) {
;                 const int k = j >> 2, m = j & 3, ai = k >> 1, bj = k & 1, col = col0 + bj * HALF, kk = k - (GB[grp] >> 2);
;                 const u32x4 r = xv[j - GB[grp]];
;                 f32x4 x0 = {bflo(r.x), bfhi(r.x), bflo(r.y), bfhi(r.y)}, x1 = {bflo(r.z), bfhi(r.z), bflo(r.w), bfhi(r.w)};
;                 x0 = (x0 - st[m].x) * st[m].y * cl[kk][0] + cb[kk][0]; x1 = (x1 - st[m].x) * st[m].y * cl[kk][1] + cb[kk][1];
;                 const f32x4 o0 = x0 * ALPHA + cg[kk][0] * acc[ai][bj][m][0], o1 = x1 * ALPHA + cg[kk][1] * acc[ai][bj][m][1];
;                 u32x4 w; w.x = cvt_pk_bf16(o0[0], o0[1]); w.y = cvt_pk_bf16(o0[2], o0[3]); w.z = cvt_pk_bf16(o1[0], o1[1]); w.w = cvt_pk_bf16(o1[2], o1[3]);
;                 *(u32x4*)(z + (size_t)(row0 + ai * HALF + m * 16) * DM + col) = w;
	v_lshlrev_b32_e32 v38, 16, v114
	v_cvt_pk_bf16_f32 v34, v34, v35
	v_cvt_pk_bf16_f32 v35, v42, v43
	global_store_dwordx4 v[140:141], v[32:35], off
	v_and_b32_e32 v39, 0xffff0000, v114
	v_lshlrev_b32_e32 v36, 16, v115
	v_lshlrev_b32_e32 v34, 16, v112
	v_and_b32_e32 v35, 0xffff0000, v112
	v_lshlrev_b32_e32 v32, 16, v113
	v_and_b32_e32 v33, 0xffff0000, v113
	v_and_b32_e32 v37, 0xffff0000, v115
	v_sub_f32_e32 v33, v33, v144
	v_sub_f32_e32 v32, v32, v144
	v_sub_f32_e32 v35, v35, v144
	v_sub_f32_e32 v34, v34, v144
	v_pk_mul_f32 v[34:35], v[142:143], v[34:35] op_sel_hi:[0,1]
	v_pk_mul_f32 v[32:33], v[142:143], v[32:33] op_sel_hi:[0,1]
	v_sub_f32_e32 v37, v37, v144
	v_sub_f32_e32 v36, v36, v144
	v_sub_f32_e32 v39, v39, v144
	v_sub_f32_e32 v38, v38, v144
	v_pk_fma_f32 v[32:33], v[74:75], v[32:33], v[78:79]
	v_pk_fma_f32 v[34:35], v[72:73], v[34:35], v[76:77]
	v_pk_mul_f32 v[38:39], v[142:143], v[38:39] op_sel_hi:[0,1]
	v_pk_mul_f32 v[36:37], v[142:143], v[36:37] op_sel_hi:[0,1]
	v_pk_fma_f32 v[36:37], v[66:67], v[36:37], v[70:71]
	v_pk_fma_f32 v[38:39], v[64:65], v[38:39], v[68:69]
	v_pk_mul_f32 v[34:35], v[34:35], s[22:23] op_sel_hi:[1,0]
	v_pk_mul_f32 v[32:33], v[32:33], s[22:23] op_sel_hi:[1,0]
	v_pk_fma_f32 v[28:29], v[28:29], v[166:167], v[34:35]
	v_pk_fma_f32 v[30:31], v[30:31], v[164:165], v[32:33]
	v_pk_mul_f32 v[32:33], v[38:39], s[22:23] op_sel_hi:[1,0]
	v_pk_mul_f32 v[34:35], v[36:37], s[22:23] op_sel_hi:[1,0]
	s_nop 0
	v_pk_fma_f32 v[34:35], v[26:27], v[150:151], v[34:35]
	v_pk_fma_f32 v[26:27], v[24:25], v[162:163], v[32:33]
	v_cvt_pk_bf16_f32 v24, v28, v29
	v_cvt_pk_bf16_f32 v25, v30, v31
	v_lshlrev_b32_e32 v30, 16, v106
	v_cvt_pk_bf16_f32 v26, v26, v27
	v_cvt_pk_bf16_f32 v27, v34, v35
	global_store_dwordx4 v[168:169], v[24:27], off offset:256
	v_and_b32_e32 v31, 0xffff0000, v106
	v_lshlrev_b32_e32 v28, 16, v107
	v_lshlrev_b32_e32 v26, 16, v104
	v_and_b32_e32 v27, 0xffff0000, v104
	v_lshlrev_b32_e32 v24, 16, v105
	v_and_b32_e32 v25, 0xffff0000, v105
	v_and_b32_e32 v29, 0xffff0000, v107
	v_sub_f32_e32 v25, v25, v138
	v_sub_f32_e32 v24, v24, v138
	v_sub_f32_e32 v27, v27, v138
	v_sub_f32_e32 v26, v26, v138
	v_pk_mul_f32 v[26:27], v[136:137], v[26:27] op_sel_hi:[0,1]
	v_pk_mul_f32 v[24:25], v[136:137], v[24:25] op_sel_hi:[0,1]
	v_sub_f32_e32 v29, v29, v138
	v_sub_f32_e32 v28, v28, v138
	v_sub_f32_e32 v31, v31, v138
	v_sub_f32_e32 v30, v30, v138
	v_pk_fma_f32 v[24:25], v[74:75], v[24:25], v[78:79]
	v_pk_fma_f32 v[26:27], v[72:73], v[26:27], v[76:77]
	v_pk_mul_f32 v[30:31], v[136:137], v[30:31] op_sel_hi:[0,1]
	v_pk_mul_f32 v[28:29], v[136:137], v[28:29] op_sel_hi:[0,1]
	v_pk_fma_f32 v[28:29], v[66:67], v[28:29], v[70:71]
	v_pk_fma_f32 v[30:31], v[64:65], v[30:31], v[68:69]
	v_pk_mul_f32 v[26:27], v[26:27], s[22:23] op_sel_hi:[1,0]
	v_pk_mul_f32 v[24:25], v[24:25], s[22:23] op_sel_hi:[1,0]
	v_pk_fma_f32 v[20:21], v[20:21], v[166:167], v[26:27]
	v_pk_fma_f32 v[22:23], v[22:23], v[164:165], v[24:25]
	v_pk_mul_f32 v[24:25], v[30:31], s[22:23] op_sel_hi:[1,0]
	v_pk_mul_f32 v[26:27], v[28:29], s[22:23] op_sel_hi:[1,0]
	s_nop 0
	v_pk_fma_f32 v[26:27], v[18:19], v[150:151], v[26:27]
	v_pk_fma_f32 v[18:19], v[16:17], v[162:163], v[24:25]
	v_cvt_pk_bf16_f32 v16, v20, v21
	v_cvt_pk_bf16_f32 v17, v22, v23
	v_lshlrev_b32_e32 v22, 16, v102
	v_cvt_pk_bf16_f32 v18, v18, v19
	v_cvt_pk_bf16_f32 v19, v26, v27
	global_store_dwordx4 v[148:149], v[16:19], off offset:256
	v_and_b32_e32 v23, 0xffff0000, v102
	v_lshlrev_b32_e32 v20, 16, v103
	v_lshlrev_b32_e32 v18, 16, v100
	v_and_b32_e32 v19, 0xffff0000, v100
	v_lshlrev_b32_e32 v16, 16, v101
	v_and_b32_e32 v17, 0xffff0000, v101
	v_and_b32_e32 v21, 0xffff0000, v103
	v_sub_f32_e32 v17, v17, v134
	v_sub_f32_e32 v16, v16, v134
	v_sub_f32_e32 v19, v19, v134
	v_sub_f32_e32 v18, v18, v134
	v_pk_mul_f32 v[18:19], v[132:133], v[18:19] op_sel_hi:[0,1]
	v_pk_mul_f32 v[16:17], v[132:133], v[16:17] op_sel_hi:[0,1]
	v_sub_f32_e32 v21, v21, v134
	v_sub_f32_e32 v20, v20, v134
	v_sub_f32_e32 v23, v23, v134
	v_sub_f32_e32 v22, v22, v134
	v_pk_fma_f32 v[16:17], v[74:75], v[16:17], v[78:79]
	v_pk_fma_f32 v[18:19], v[72:73], v[18:19], v[76:77]
	v_pk_mul_f32 v[22:23], v[132:133], v[22:23] op_sel_hi:[0,1]
	v_pk_mul_f32 v[20:21], v[132:133], v[20:21] op_sel_hi:[0,1]
	v_pk_fma_f32 v[20:21], v[66:67], v[20:21], v[70:71]
	v_pk_fma_f32 v[22:23], v[64:65], v[22:23], v[68:69]
	v_pk_mul_f32 v[18:19], v[18:19], s[22:23] op_sel_hi:[1,0]
	v_pk_mul_f32 v[16:17], v[16:17], s[22:23] op_sel_hi:[1,0]
	v_pk_fma_f32 v[12:13], v[12:13], v[166:167], v[18:19]
	v_pk_fma_f32 v[14:15], v[14:15], v[164:165], v[16:17]
	v_pk_mul_f32 v[16:17], v[22:23], s[22:23] op_sel_hi:[1,0]
	v_pk_mul_f32 v[18:19], v[20:21], s[22:23] op_sel_hi:[1,0]
	s_nop 0
	v_pk_fma_f32 v[18:19], v[10:11], v[150:151], v[18:19]
	v_pk_fma_f32 v[10:11], v[8:9], v[162:163], v[16:17]
	v_cvt_pk_bf16_f32 v8, v12, v13
	v_cvt_pk_bf16_f32 v9, v14, v15
	v_lshlrev_b32_e32 v14, 16, v82
	v_cvt_pk_bf16_f32 v10, v10, v11
	v_cvt_pk_bf16_f32 v11, v18, v19
	global_store_dwordx4 v[146:147], v[8:11], off offset:256
	v_and_b32_e32 v15, 0xffff0000, v82
	v_lshlrev_b32_e32 v12, 16, v83
	v_lshlrev_b32_e32 v10, 16, v80
	v_and_b32_e32 v11, 0xffff0000, v80
	v_lshlrev_b32_e32 v8, 16, v81
	v_and_b32_e32 v9, 0xffff0000, v81
	v_and_b32_e32 v13, 0xffff0000, v83
	v_sub_f32_e32 v9, v9, v130
	v_sub_f32_e32 v8, v8, v130
	v_sub_f32_e32 v11, v11, v130
	v_sub_f32_e32 v10, v10, v130
	v_pk_mul_f32 v[10:11], v[128:129], v[10:11] op_sel_hi:[0,1]
	v_pk_mul_f32 v[8:9], v[128:129], v[8:9] op_sel_hi:[0,1]
	v_sub_f32_e32 v13, v13, v130
	v_sub_f32_e32 v12, v12, v130
	v_sub_f32_e32 v15, v15, v130
	v_sub_f32_e32 v14, v14, v130
	v_pk_fma_f32 v[8:9], v[74:75], v[8:9], v[78:79]
	v_pk_fma_f32 v[10:11], v[72:73], v[10:11], v[76:77]
	v_pk_mul_f32 v[14:15], v[128:129], v[14:15] op_sel_hi:[0,1]
	v_pk_mul_f32 v[12:13], v[128:129], v[12:13] op_sel_hi:[0,1]
	v_pk_fma_f32 v[12:13], v[66:67], v[12:13], v[70:71]
	v_pk_fma_f32 v[14:15], v[64:65], v[14:15], v[68:69]
	v_pk_mul_f32 v[10:11], v[10:11], s[22:23] op_sel_hi:[1,0]
	v_pk_mul_f32 v[8:9], v[8:9], s[22:23] op_sel_hi:[1,0]
	v_pk_fma_f32 v[4:5], v[4:5], v[166:167], v[10:11]
	v_pk_fma_f32 v[6:7], v[6:7], v[164:165], v[8:9]
	v_pk_mul_f32 v[8:9], v[14:15], s[22:23] op_sel_hi:[1,0]
	v_pk_mul_f32 v[10:11], v[12:13], s[22:23] op_sel_hi:[1,0]
	s_mov_b64 s[22:23], s[20:21]
	v_pk_fma_f32 v[10:11], v[2:3], v[150:151], v[10:11]
	v_pk_fma_f32 v[2:3], v[0:1], v[162:163], v[8:9]
	v_cvt_pk_bf16_f32 v0, v4, v5
	v_cvt_pk_bf16_f32 v1, v6, v7
	s_nop 0
	v_cvt_pk_bf16_f32 v2, v2, v3
	v_cvt_pk_bf16_f32 v3, v10, v11
	global_store_dwordx4 v[140:141], v[0:3], off offset:256
	s_cmpk_gt_u32 s29, 0xff
	s_cbranch_scc0 .Lyb_187
	s_barrier
.Lyb_187:
	s_cbranch_vccnz .LBB0_220

; #define PG8_STAGE(bufoff, gbase, voff) do { _Pragma("unroll") for (int _i = 0; _i < 2; ++_i) \
;         __builtin_amdgcn_global_load_lds((const unsigned*)((const char*)(gbase) + (voff)[_i]), (LAS unsigned*)(lds + (bufoff) + ldsw + _i * 8192), 16, 0, 0); } while (0)
; #define PG8_LDA(dst, b, h) do { _Pragma("unroll") for (int m = 0; m < 4; ++m) _Pragma("unroll") for (int k = 0; k < 2; ++k) dst[m][k] = *(const LAS bf16x8*)(lds + PG8_SA(b, h) + aoff + m * 2048 + k * 1024); } while (0)
; #define PG8_LDB(dst, b, h) do { _Pragma("unroll") for (int n = 0; n < 2; ++n) _Pragma("unroll") for (int k = 0; k < 2; ++k) dst[n][k] = *(const LAS bf16x8*)(lds + PG8_SB(b, h) + boff + n * 2048 + k * 1024); } while (0)
; #define PG8_WAIT_V(n) asm volatile("s_waitcnt vmcnt(" #n ")" ::: "memory")
; #define PG8_WAIT_L(n) asm volatile("s_waitcnt lgkmcnt(" #n ")" ::: "memory")
; #define PG8_BAR __builtin_amdgcn_s_barrier()
; #define PG8_SCHED __builtin_amdgcn_sched_barrier(0)
; template <class Epi>
; __device__ __forceinline__ void gemm_phase(LAS unsigned char* lds, const Gemm g, const StaticOrder& S, const Epi& E) {
;     ...
;         const bool has_next = S.next(ui + 1, nxt);
;         const char* nA = has_next ? (const char*)g.A + (size_t)nxt.pm * tstepA : cA; const char* nB = has_next ? (const char*)g.Bt + (size_t)nxt.pn * tstepB : cB;
;         for (int t = 0; t < nt; t += 2) {
;             const bool last = (t == nt - 2);
;             const char* a1 = cA + (size_t)(t + 1) * kstep;
;             const char* a2 = last ? nA : cA + (size_t)(t + 2) * kstep; const char* b2 = last ? nB : cB + (size_t)(t + 2) * kstep;
;             const char* a3 = a2 + kstep; const char* b3 = b2 + kstep;
;             PG8_LDB(B0, 0, 0); PG8_SCHED; PG8_LDA(At, 0, 0); PG8_STAGE(PG8_SA(1, 1), a1 + hstepA, voffA);
;             PG8_WAIT_L(8); PG8_BAR; PG8_WAIT_L(0); PG8_MMA(0, 0, At, B0); PG8_BAR; PG8_SCHED;
;             PG8_LDB(B1, 0, 1); PG8_STAGE(PG8_SB(0, 0), b2, voffB);
;             PG8_BAR; PG8_WAIT_L(0); PG8_MMA(0, 1, At, B1); PG8_BAR;
;             PG8_LDA(At, 0, 1); PG8_STAGE(PG8_SA(0, 0), a2, voffA);
;             PG8_BAR; PG8_WAIT_L(0); PG8_MMA(1, 0, At, B0); PG8_BAR; PG8_SCHED;
;             PG8_STAGE(PG8_SB(0, 1), b2 + hstepB, voffB);
;             PG8_WAIT_V(6); PG8_BAR; PG8_MMA(1, 1, At, B1); PG8_BAR;
.LBB0_186:
	s_add_u32 s4, s24, 0x4000
	s_addc_u32 s5, s25, 0
	s_add_u32 s50, s22, 0x8000
	s_addc_u32 s51, s23, 0
	s_mov_b32 s22, 0
	s_add_i32 s54, s22, 2
	s_add_u32 s23, s4, 0x4000
	s_addc_u32 s24, s5, 0
	s_cmp_eq_u32 s40, s22
	s_cselect_b32 s26, s6, s23
	s_cselect_b32 s27, s7, s24
	s_cselect_b32 s24, s20, s50
	s_cselect_b32 s25, s21, s51
	s_add_u32 s22, s26, 0x4000
	s_addc_u32 s23, s27, 0
	s_add_i32 m0, s33, 0xc000
	v_lshl_add_u64 v[186:187], s[4:5], 0, v[158:159]
	global_load_lds_dwordx4 v[186:187], off
	s_add_i32 m0, s33, 0xe000
	v_lshl_add_u64 v[186:187], s[4:5], 0, v[160:161]
	global_load_lds_dwordx4 v[186:187], off
	s_mov_b32 s55, 0x10000
	v_add_u32_e32 v140, s55, v207
	ds_read_b128 v[128:131], v140
	ds_read_b128 v[136:139], v140 offset:2048
	ds_read_b128 v[132:135], v140 offset:1024
	ds_read_b128 v[140:143], v140 offset:3072
	ds_read_b128 v[144:147], v209
	ds_read_b128 v[162:165], v209 offset:2048
	ds_read_b128 v[170:173], v209 offset:4096
	ds_read_b128 v[178:181], v209 offset:6144
	ds_read_b128 v[148:151], v209 offset:1024
	ds_read_b128 v[166:169], v209 offset:3072
	ds_read_b128 v[174:177], v209 offset:5120
	ds_read_b128 v[182:185], v209 offset:7168
	s_mov_b32 s58, 0x14000
	s_add_i32 s55, s55, s31
	v_add_u32_e32 v198, s58, v207
	ds_read_b128 v[186:189], v198
	ds_read_b128 v[194:197], v198 offset:2048
	ds_read_b128 v[190:193], v198 offset:1024
	ds_read_b128 v[198:201], v198 offset:3072
	s_waitcnt lgkmcnt(0)
	s_barrier
	v_mfma_f32_16x16x32_bf16 v[124:127], v[128:131], v[144:147], 0
	s_setprio 1
	v_mfma_f32_16x16x32_bf16 v[120:123], v[136:139], v[144:147], 0
	v_mfma_f32_16x16x32_bf16 v[116:119], v[128:131], v[162:165], 0
	v_mfma_f32_16x16x32_bf16 v[112:115], v[136:139], v[162:165], 0
	v_mfma_f32_16x16x32_bf16 v[108:111], v[128:131], v[170:173], 0
	v_mfma_f32_16x16x32_bf16 v[104:107], v[136:139], v[170:173], 0
	v_mfma_f32_16x16x32_bf16 v[100:103], v[128:131], v[178:181], 0
	v_mfma_f32_16x16x32_bf16 v[96:99], v[136:139], v[178:181], 0
	v_mfma_f32_16x16x32_bf16 v[124:127], v[132:135], v[148:151], v[124:127]
	v_mfma_f32_16x16x32_bf16 v[120:123], v[140:143], v[148:151], v[120:123]
	v_mfma_f32_16x16x32_bf16 v[116:119], v[132:135], v[166:169], v[116:119]
	v_mfma_f32_16x16x32_bf16 v[112:115], v[140:143], v[166:169], v[112:115]
	v_mfma_f32_16x16x32_bf16 v[108:111], v[132:135], v[174:177], v[108:111]
	v_mfma_f32_16x16x32_bf16 v[104:107], v[140:143], v[174:177], v[104:107]
	v_mfma_f32_16x16x32_bf16 v[100:103], v[132:135], v[182:185], v[100:103]
	v_mfma_f32_16x16x32_bf16 v[96:99], v[140:143], v[182:185], v[96:99]
	v_mfma_f32_16x16x32_bf16 v[92:95], v[186:189], v[144:147], 0
	v_mfma_f32_16x16x32_bf16 v[88:91], v[194:197], v[144:147], 0
	v_mfma_f32_16x16x32_bf16 v[84:87], v[186:189], v[162:165], 0
	v_mfma_f32_16x16x32_bf16 v[80:83], v[194:197], v[162:165], 0
	v_mfma_f32_16x16x32_bf16 v[76:79], v[186:189], v[170:173], 0
	v_mfma_f32_16x16x32_bf16 v[72:75], v[194:197], v[170:173], 0
	v_mfma_f32_16x16x32_bf16 v[68:71], v[186:189], v[178:181], 0
	v_mfma_f32_16x16x32_bf16 v[64:67], v[194:197], v[178:181], 0
	v_mfma_f32_16x16x32_bf16 v[92:95], v[190:193], v[148:151], v[92:95]
	v_mfma_f32_16x16x32_bf16 v[88:91], v[198:201], v[148:151], v[88:91]
	v_mfma_f32_16x16x32_bf16 v[84:87], v[190:193], v[166:169], v[84:87]
	v_mfma_f32_16x16x32_bf16 v[80:83], v[198:201], v[166:169], v[80:83]
	v_mfma_f32_16x16x32_bf16 v[76:79], v[190:193], v[174:177], v[76:79]
	v_mfma_f32_16x16x32_bf16 v[72:75], v[198:201], v[174:177], v[72:75]
	v_mfma_f32_16x16x32_bf16 v[68:71], v[190:193], v[182:185], v[68:71]
	s_setprio 0
	v_mfma_f32_16x16x32_bf16 v[64:67], v[198:201], v[182:185], v[64:67]
	s_barrier
	s_mov_b32 m0, s55
	v_lshl_add_u64 v[202:203], s[24:25], 0, v[152:153]
	global_load_lds_dwordx4 v[202:203], off
	s_add_i32 m0, s55, 0x2000
	v_lshl_add_u64 v[202:203], s[24:25], 0, v[156:157]
	global_load_lds_dwordx4 v[202:203], off
	s_mov_b32 m0, s33
	v_lshl_add_u64 v[202:203], s[26:27], 0, v[152:153]
	global_load_lds_dwordx4 v[202:203], off
	s_mov_b32 m0, s34
	v_lshl_add_u64 v[202:203], s[26:27], 0, v[156:157]
	global_load_lds_dwordx4 v[202:203], off
	s_add_u32 s56, s24, s52
	s_addc_u32 s57, s25, 0
	s_add_i32 s55, s58, s31
	s_mov_b32 m0, s55
	v_lshl_add_u64 v[202:203], s[56:57], 0, v[152:153]
	global_load_lds_dwordx4 v[202:203], off
	s_add_i32 m0, s55, 0x2000
	v_lshl_add_u64 v[202:203], s[56:57], 0, v[156:157]
	global_load_lds_dwordx4 v[202:203], off
	ds_read_b128 v[144:147], v209 offset:16384
	ds_read_b128 v[162:165], v209 offset:18432
	ds_read_b128 v[170:173], v209 offset:20480
	ds_read_b128 v[178:181], v209 offset:22528
	ds_read_b128 v[148:151], v209 offset:17408
	ds_read_b128 v[166:169], v209 offset:19456
	ds_read_b128 v[174:177], v209 offset:21504
	ds_read_b128 v[182:185], v209 offset:23552
	s_waitcnt vmcnt(6)
	s_waitcnt lgkmcnt(0)
	s_barrier
; #define PG8_STAGE(bufoff, gbase, voff) do { _Pragma("unroll") for (int _i = 0; _i < 2; ++_i) \
;         __builtin_amdgcn_global_load_lds((const unsigned*)((const char*)(gbase) + (voff)[_i]), (LAS unsigned*)(lds + (bufoff) + ldsw + _i * 8192), 16, 0, 0); } while (0)
; #define PG8_LDA(dst, b, h) do { _Pragma("unroll") for (int m = 0; m < 4; ++m) _Pragma("unroll") for (int k = 0; k < 2; ++k) dst[m][k] = *(const LAS bf16x8*)(lds + PG8_SA(b, h) + aoff + m * 2048 + k * 1024); } while (0)
; #define PG8_LDB(dst, b, h) do { _Pragma("unroll") for (int n = 0; n < 2; ++n) _Pragma("unroll") for (int k = 0; k < 2; ++k) dst[n][k] = *(const LAS bf16x8*)(lds + PG8_SB(b, h) + boff + n * 2048 + k * 1024); } while (0)
; #define PG8_MMA(ai, bj, At, Bt) do { __builtin_amdgcn_s_setprio(1); _Pragma("unroll") for (int m = 0; m < 4; ++m) _Pragma("unroll") for (int n = 0; n < 2; ++n) _Pragma("unroll") for (int k = 0; k < 2; ++k) \
;         acc[ai][bj][m][n] = __builtin_amdgcn_mfma_f32_16x16x32_bf16(Bt[n][k], At[m][k], acc[ai][bj][m][n], 0, 0, 0); __builtin_amdgcn_s_setprio(0); } while (0)
; #define PG8_WAIT_V(n) asm volatile("s_waitcnt vmcnt(" #n ")" ::: "memory")
; #define PG8_WAIT_L(n) asm volatile("s_waitcnt lgkmcnt(" #n ")" ::: "memory")
; #define PG8_BAR __builtin_amdgcn_s_barrier()
; #define PG8_SCHED __builtin_amdgcn_sched_barrier(0)
; template <class Epi>
; __device__ __forceinline__ void gemm_phase(LAS unsigned char* lds, const Gemm g, const StaticOrder& S, const Epi& E) {
;     ...
;             PG8_BAR; PG8_WAIT_L(0); PG8_MMA(1, 0, At, B0); PG8_BAR; PG8_SCHED;
;             PG8_STAGE(PG8_SB(0, 1), b2 + hstepB, voffB);
;             PG8_WAIT_V(6); PG8_BAR; PG8_MMA(1, 1, At, B1); PG8_BAR;
;             PG8_LDB(B0, 1, 0); PG8_SCHED; PG8_LDA(At, 1, 0); PG8_STAGE(PG8_SA(0, 1), a2 + hstepA, voffA);
;             PG8_WAIT_L(8); PG8_BAR; PG8_WAIT_L(0); PG8_MMA(0, 0, At, B0); PG8_BAR; PG8_SCHED;
;             PG8_LDB(B1, 1, 1); PG8_STAGE(PG8_SB(1, 0), b3, voffB);
;             PG8_BAR; PG8_WAIT_L(0); PG8_MMA(0, 1, At, B1); PG8_BAR;
	v_mfma_f32_16x16x32_bf16 v[60:63], v[128:131], v[144:147], 0
	s_setprio 1
	v_mfma_f32_16x16x32_bf16 v[56:59], v[136:139], v[144:147], 0
	v_mfma_f32_16x16x32_bf16 v[52:55], v[128:131], v[162:165], 0
	v_mfma_f32_16x16x32_bf16 v[48:51], v[136:139], v[162:165], 0
	v_mfma_f32_16x16x32_bf16 v[44:47], v[128:131], v[170:173], 0
	v_mfma_f32_16x16x32_bf16 v[40:43], v[136:139], v[170:173], 0
	v_mfma_f32_16x16x32_bf16 v[36:39], v[128:131], v[178:181], 0
	v_mfma_f32_16x16x32_bf16 v[32:35], v[136:139], v[178:181], 0
	v_mfma_f32_16x16x32_bf16 v[60:63], v[132:135], v[148:151], v[60:63]
	v_mfma_f32_16x16x32_bf16 v[56:59], v[140:143], v[148:151], v[56:59]
	v_mfma_f32_16x16x32_bf16 v[52:55], v[132:135], v[166:169], v[52:55]
	v_mfma_f32_16x16x32_bf16 v[48:51], v[140:143], v[166:169], v[48:51]
	v_mfma_f32_16x16x32_bf16 v[44:47], v[132:135], v[174:177], v[44:47]
	v_mfma_f32_16x16x32_bf16 v[40:43], v[140:143], v[174:177], v[40:43]
	v_mfma_f32_16x16x32_bf16 v[36:39], v[132:135], v[182:185], v[36:39]
	v_mfma_f32_16x16x32_bf16 v[32:35], v[140:143], v[182:185], v[32:35]
	v_mfma_f32_16x16x32_bf16 v[28:31], v[186:189], v[144:147], 0
	v_mfma_f32_16x16x32_bf16 v[24:27], v[194:197], v[144:147], 0
	s_add_i32 s55, 0, 0x18000
	v_add_u32_e32 v140, s55, v207
	v_mfma_f32_16x16x32_bf16 v[20:23], v[186:189], v[162:165], 0
	v_mfma_f32_16x16x32_bf16 v[16:19], v[194:197], v[162:165], 0
	v_mfma_f32_16x16x32_bf16 v[12:15], v[186:189], v[170:173], 0
	v_mfma_f32_16x16x32_bf16 v[8:11], v[194:197], v[170:173], 0
	v_mfma_f32_16x16x32_bf16 v[4:7], v[186:189], v[178:181], 0
	v_mfma_f32_16x16x32_bf16 v[0:3], v[194:197], v[178:181], 0
	v_mfma_f32_16x16x32_bf16 v[28:31], v[190:193], v[148:151], v[28:31]
	v_mfma_f32_16x16x32_bf16 v[24:27], v[198:201], v[148:151], v[24:27]
	v_mfma_f32_16x16x32_bf16 v[20:23], v[190:193], v[166:169], v[20:23]
	v_mfma_f32_16x16x32_bf16 v[16:19], v[198:201], v[166:169], v[16:19]
	v_mfma_f32_16x16x32_bf16 v[12:15], v[190:193], v[174:177], v[12:15]
	v_mfma_f32_16x16x32_bf16 v[8:11], v[198:201], v[174:177], v[8:11]
	v_mfma_f32_16x16x32_bf16 v[4:7], v[190:193], v[182:185], v[4:7]
	s_setprio 0
	v_mfma_f32_16x16x32_bf16 v[0:3], v[198:201], v[182:185], v[0:3]
	s_barrier
	s_add_u32 s26, s26, s52
	s_addc_u32 s27, s27, 0
	s_mov_b32 m0, s35
	v_lshl_add_u64 v[186:187], s[26:27], 0, v[152:153]
	global_load_lds_dwordx4 v[186:187], off
	s_mov_b32 m0, s36
	v_lshl_add_u64 v[186:187], s[26:27], 0, v[156:157]
	global_load_lds_dwordx4 v[186:187], off
	ds_read_b128 v[128:131], v140
	ds_read_b128 v[136:139], v140 offset:2048
	ds_read_b128 v[132:135], v140 offset:1024
	ds_read_b128 v[140:143], v140 offset:3072
	ds_read_b128 v[144:147], v209 offset:32768
	ds_read_b128 v[162:165], v209 offset:34816
	ds_read_b128 v[170:173], v209 offset:36864
	ds_read_b128 v[178:181], v209 offset:38912
	ds_read_b128 v[148:151], v209 offset:33792
	ds_read_b128 v[166:169], v209 offset:35840
	ds_read_b128 v[174:177], v209 offset:37888
	ds_read_b128 v[182:185], v209 offset:39936
	s_mov_b32 s26, 0x1c000
	s_add_u32 s24, s24, 0x4000
	s_addc_u32 s25, s25, 0
	s_add_i32 s27, s55, s31
	v_add_u32_e32 v198, s26, v207
	ds_read_b128 v[186:189], v198
	ds_read_b128 v[194:197], v198 offset:2048
	ds_read_b128 v[190:193], v198 offset:1024
	ds_read_b128 v[198:201], v198 offset:3072
	s_waitcnt lgkmcnt(0)
	s_barrier
	v_mfma_f32_16x16x32_bf16 v[124:127], v[128:131], v[144:147], v[124:127]
	s_setprio 1
	v_mfma_f32_16x16x32_bf16 v[120:123], v[136:139], v[144:147], v[120:123]
	v_mfma_f32_16x16x32_bf16 v[116:119], v[128:131], v[162:165], v[116:119]
	v_mfma_f32_16x16x32_bf16 v[112:115], v[136:139], v[162:165], v[112:115]
	v_mfma_f32_16x16x32_bf16 v[108:111], v[128:131], v[170:173], v[108:111]
	v_mfma_f32_16x16x32_bf16 v[104:107], v[136:139], v[170:173], v[104:107]
	v_mfma_f32_16x16x32_bf16 v[100:103], v[128:131], v[178:181], v[100:103]
	v_mfma_f32_16x16x32_bf16 v[96:99], v[136:139], v[178:181], v[96:99]
	v_mfma_f32_16x16x32_bf16 v[124:127], v[132:135], v[148:151], v[124:127]
	v_mfma_f32_16x16x32_bf16 v[120:123], v[140:143], v[148:151], v[120:123]
	v_mfma_f32_16x16x32_bf16 v[116:119], v[132:135], v[166:169], v[116:119]
	v_mfma_f32_16x16x32_bf16 v[112:115], v[140:143], v[166:169], v[112:115]
	v_mfma_f32_16x16x32_bf16 v[108:111], v[132:135], v[174:177], v[108:111]
	v_mfma_f32_16x16x32_bf16 v[104:107], v[140:143], v[174:177], v[104:107]
	v_mfma_f32_16x16x32_bf16 v[100:103], v[132:135], v[182:185], v[100:103]
	v_mfma_f32_16x16x32_bf16 v[96:99], v[140:143], v[182:185], v[96:99]
	v_mfma_f32_16x16x32_bf16 v[92:95], v[186:189], v[144:147], v[92:95]
	v_mfma_f32_16x16x32_bf16 v[88:91], v[194:197], v[144:147], v[88:91]
	v_mfma_f32_16x16x32_bf16 v[84:87], v[186:189], v[162:165], v[84:87]
	v_mfma_f32_16x16x32_bf16 v[80:83], v[194:197], v[162:165], v[80:83]
	v_mfma_f32_16x16x32_bf16 v[76:79], v[186:189], v[170:173], v[76:79]
	v_mfma_f32_16x16x32_bf16 v[72:75], v[194:197], v[170:173], v[72:75]
	v_mfma_f32_16x16x32_bf16 v[68:71], v[186:189], v[178:181], v[68:71]
	v_mfma_f32_16x16x32_bf16 v[64:67], v[194:197], v[178:181], v[64:67]
	v_mfma_f32_16x16x32_bf16 v[92:95], v[190:193], v[148:151], v[92:95]
	v_mfma_f32_16x16x32_bf16 v[88:91], v[198:201], v[148:151], v[88:91]
	v_mfma_f32_16x16x32_bf16 v[84:87], v[190:193], v[166:169], v[84:87]
	v_mfma_f32_16x16x32_bf16 v[80:83], v[198:201], v[166:169], v[80:83]
	v_mfma_f32_16x16x32_bf16 v[76:79], v[190:193], v[174:177], v[76:79]
	v_mfma_f32_16x16x32_bf16 v[72:75], v[198:201], v[174:177], v[72:75]
	v_mfma_f32_16x16x32_bf16 v[68:71], v[190:193], v[182:185], v[68:71]
	s_setprio 0
	v_mfma_f32_16x16x32_bf16 v[64:67], v[198:201], v[182:185], v[64:67]
	s_barrier
; #define PG8_STAGE(bufoff, gbase, voff) do { _Pragma("unroll") for (int _i = 0; _i < 2; ++_i) \
;         __builtin_amdgcn_global_load_lds((const unsigned*)((const char*)(gbase) + (voff)[_i]), (LAS unsigned*)(lds + (bufoff) + ldsw + _i * 8192), 16, 0, 0); } while (0)
; #define PG8_LDA(dst, b, h) do { _Pragma("unroll") for (int m = 0; m < 4; ++m) _Pragma("unroll") for (int k = 0; k < 2; ++k) dst[m][k] = *(const LAS bf16x8*)(lds + PG8_SA(b, h) + aoff + m * 2048 + k * 1024); } while (0)
; #define PG8_WAIT_V(n) asm volatile("s_waitcnt vmcnt(" #n ")" ::: "memory")
; #define PG8_WAIT_L(n) asm volatile("s_waitcnt lgkmcnt(" #n ")" ::: "memory")
; template <class Epi>
; __device__ __forceinline__ void gemm_phase(LAS unsigned char* lds, const Gemm g, const StaticOrder& S, const Epi& E) {
;     ...
;         for (int t = 0; t < nt; t += 2) {
;             const bool last = (t == nt - 2);
;             const char* a1 = cA + (size_t)(t + 1) * kstep;
;             const char* a2 = last ? nA : cA + (size_t)(t + 2) * kstep; const char* b2 = last ? nB : cB + (size_t)(t + 2) * kstep;
;             const char* a3 = a2 + kstep; const char* b3 = b2 + kstep;
;             PG8_LDB(B0, 0, 0); PG8_SCHED; PG8_LDA(At, 0, 0); PG8_STAGE(PG8_SA(1, 1), a1 + hstepA, voffA);
;             PG8_WAIT_L(8); PG8_BAR; PG8_WAIT_L(0); PG8_MMA(0, 0, At, B0); PG8_BAR; PG8_SCHED;
;             PG8_LDB(B1, 0, 1); PG8_STAGE(PG8_SB(0, 0), b2, voffB);
;             PG8_BAR; PG8_WAIT_L(0); PG8_MMA(0, 1, At, B1); PG8_BAR;
;             PG8_LDA(At, 0, 1); PG8_STAGE(PG8_SA(0, 0), a2, voffA);
;             PG8_BAR; PG8_WAIT_L(0); PG8_MMA(1, 0, At, B0); PG8_BAR; PG8_SCHED;
;             PG8_STAGE(PG8_SB(0, 1), b2 + hstepB, voffB);
;             PG8_WAIT_V(6); PG8_BAR; PG8_MMA(1, 1, At, B1); PG8_BAR;
;             PG8_LDB(B0, 1, 0); PG8_SCHED; PG8_LDA(At, 1, 0); PG8_STAGE(PG8_SA(0, 1), a2 + hstepA, voffA);
;             PG8_WAIT_L(8); PG8_BAR; PG8_WAIT_L(0); PG8_MMA(0, 0, At, B0); PG8_BAR; PG8_SCHED;
;             PG8_LDB(B1, 1, 1); PG8_STAGE(PG8_SB(1, 0), b3, voffB);
;             PG8_BAR; PG8_WAIT_L(0); PG8_MMA(0, 1, At, B1); PG8_BAR;
;             PG8_LDA(At, 1, 1); PG8_STAGE(PG8_SA(1, 0), a3, voffA);
;             PG8_BAR; PG8_WAIT_L(0); PG8_MMA(1, 0, At, B0); PG8_BAR; PG8_SCHED;
;             PG8_STAGE(PG8_SB(1, 1), b3 + hstepB, voffB);
;             PG8_WAIT_V(6); PG8_BAR; PG8_MMA(1, 1, At, B1); PG8_BAR;
	s_mov_b32 m0, s27
	v_lshl_add_u64 v[202:203], s[24:25], 0, v[152:153]
	global_load_lds_dwordx4 v[202:203], off
	s_add_i32 m0, s27, 0x2000
	v_lshl_add_u64 v[202:203], s[24:25], 0, v[156:157]
	global_load_lds_dwordx4 v[202:203], off
	s_mov_b32 m0, s38
	v_lshl_add_u64 v[202:203], s[22:23], 0, v[152:153]
	global_load_lds_dwordx4 v[202:203], off
	s_mov_b32 m0, s39
	v_lshl_add_u64 v[202:203], s[22:23], 0, v[156:157]
	global_load_lds_dwordx4 v[202:203], off
	s_add_u32 s22, s24, s52
	s_addc_u32 s23, s25, 0
	s_add_i32 s24, s26, s31
	s_mov_b32 m0, s24
	v_lshl_add_u64 v[202:203], s[22:23], 0, v[152:153]
	global_load_lds_dwordx4 v[202:203], off
	s_add_i32 m0, s24, 0x2000
	v_lshl_add_u64 v[202:203], s[22:23], 0, v[156:157]
	global_load_lds_dwordx4 v[202:203], off
	ds_read_b128 v[144:147], v209 offset:49152
	ds_read_b128 v[162:165], v209 offset:51200
	ds_read_b128 v[170:173], v209 offset:53248
	ds_read_b128 v[178:181], v209 offset:55296
	ds_read_b128 v[148:151], v209 offset:50176
	ds_read_b128 v[166:169], v209 offset:52224
	ds_read_b128 v[174:177], v209 offset:54272
	ds_read_b128 v[182:185], v209 offset:56320
	s_waitcnt vmcnt(6)
	s_waitcnt lgkmcnt(0)
	s_barrier
	v_mfma_f32_16x16x32_bf16 v[60:63], v[128:131], v[144:147], v[60:63]
	s_setprio 1
	v_mfma_f32_16x16x32_bf16 v[56:59], v[136:139], v[144:147], v[56:59]
	v_mfma_f32_16x16x32_bf16 v[52:55], v[128:131], v[162:165], v[52:55]
	v_mfma_f32_16x16x32_bf16 v[48:51], v[136:139], v[162:165], v[48:51]
	v_mfma_f32_16x16x32_bf16 v[44:47], v[128:131], v[170:173], v[44:47]
	v_mfma_f32_16x16x32_bf16 v[40:43], v[136:139], v[170:173], v[40:43]
	v_mfma_f32_16x16x32_bf16 v[36:39], v[128:131], v[178:181], v[36:39]
	v_mfma_f32_16x16x32_bf16 v[32:35], v[136:139], v[178:181], v[32:35]
	v_mfma_f32_16x16x32_bf16 v[60:63], v[132:135], v[148:151], v[60:63]
	v_mfma_f32_16x16x32_bf16 v[56:59], v[140:143], v[148:151], v[56:59]
	v_mfma_f32_16x16x32_bf16 v[52:55], v[132:135], v[166:169], v[52:55]
	v_mfma_f32_16x16x32_bf16 v[48:51], v[140:143], v[166:169], v[48:51]
	v_mfma_f32_16x16x32_bf16 v[44:47], v[132:135], v[174:177], v[44:47]
	v_mfma_f32_16x16x32_bf16 v[40:43], v[140:143], v[174:177], v[40:43]
	v_mfma_f32_16x16x32_bf16 v[36:39], v[132:135], v[182:185], v[36:39]
	v_mfma_f32_16x16x32_bf16 v[32:35], v[140:143], v[182:185], v[32:35]
	v_mfma_f32_16x16x32_bf16 v[28:31], v[186:189], v[144:147], v[28:31]
	v_mfma_f32_16x16x32_bf16 v[24:27], v[194:197], v[144:147], v[24:27]
	s_add_u32 s4, s4, 0x8000
	s_addc_u32 s5, s5, 0
	s_add_u32 s50, s50, 0x8000
	s_addc_u32 s51, s51, 0
	v_mfma_f32_16x16x32_bf16 v[20:23], v[186:189], v[162:165], v[20:23]
	v_mfma_f32_16x16x32_bf16 v[16:19], v[194:197], v[162:165], v[16:19]
	v_mfma_f32_16x16x32_bf16 v[12:15], v[186:189], v[170:173], v[12:15]
	v_mfma_f32_16x16x32_bf16 v[8:11], v[194:197], v[170:173], v[8:11]
	v_mfma_f32_16x16x32_bf16 v[4:7], v[186:189], v[178:181], v[4:7]
	v_mfma_f32_16x16x32_bf16 v[0:3], v[194:197], v[178:181], v[0:3]
	v_mfma_f32_16x16x32_bf16 v[28:31], v[190:193], v[148:151], v[28:31]
	v_mfma_f32_16x16x32_bf16 v[24:27], v[198:201], v[148:151], v[24:27]
	v_mfma_f32_16x16x32_bf16 v[20:23], v[190:193], v[166:169], v[20:23]
	v_mfma_f32_16x16x32_bf16 v[16:19], v[198:201], v[166:169], v[16:19]
	v_mfma_f32_16x16x32_bf16 v[12:15], v[190:193], v[174:177], v[12:15]
	v_mfma_f32_16x16x32_bf16 v[8:11], v[198:201], v[174:177], v[8:11]
	v_mfma_f32_16x16x32_bf16 v[4:7], v[190:193], v[182:185], v[4:7]
	s_cmp_ge_u32 s54, s28
	s_mov_b32 s22, s54
	s_setprio 0
	v_mfma_f32_16x16x32_bf16 v[0:3], v[198:201], v[182:185], v[0:3]
	s_cbranch_scc1 .Lkexit_187
	s_barrier
.LBB0_187:
	s_add_i32 s54, s22, 2
	s_add_u32 s23, s4, 0x4000
	s_addc_u32 s24, s5, 0
	s_cmp_eq_u32 s40, s22
	s_cselect_b32 s26, s6, s23
	s_cselect_b32 s27, s7, s24
	s_cselect_b32 s24, s20, s50
	s_cselect_b32 s25, s21, s51
	s_add_u32 s22, s26, 0x4000
	s_addc_u32 s23, s27, 0
	s_add_i32 m0, s33, 0xc000
	v_lshl_add_u64 v[186:187], s[4:5], 0, v[158:159]
	global_load_lds_dwordx4 v[186:187], off
	s_add_i32 m0, s33, 0xe000
	v_lshl_add_u64 v[186:187], s[4:5], 0, v[160:161]
	global_load_lds_dwordx4 v[186:187], off
	s_mov_b32 s55, 0x10000
	v_add_u32_e32 v140, s55, v207
	ds_read_b128 v[128:131], v140
	ds_read_b128 v[136:139], v140 offset:2048
	ds_read_b128 v[132:135], v140 offset:1024
	ds_read_b128 v[140:143], v140 offset:3072
	ds_read_b128 v[144:147], v209
	ds_read_b128 v[162:165], v209 offset:2048
	ds_read_b128 v[170:173], v209 offset:4096
	ds_read_b128 v[178:181], v209 offset:6144
	ds_read_b128 v[148:151], v209 offset:1024
	ds_read_b128 v[166:169], v209 offset:3072
	ds_read_b128 v[174:177], v209 offset:5120
	ds_read_b128 v[182:185], v209 offset:7168
	s_mov_b32 s58, 0x14000
	s_add_i32 s55, s55, s31
	v_add_u32_e32 v198, s58, v207
	ds_read_b128 v[186:189], v198
	ds_read_b128 v[194:197], v198 offset:2048
	ds_read_b128 v[190:193], v198 offset:1024
	ds_read_b128 v[198:201], v198 offset:3072
	s_waitcnt lgkmcnt(0)
	s_barrier
; #define PG8_STAGE(bufoff, gbase, voff) do { _Pragma("unroll") for (int _i = 0; _i < 2; ++_i) \
;         __builtin_amdgcn_global_load_lds((const unsigned*)((const char*)(gbase) + (voff)[_i]), (LAS unsigned*)(lds + (bufoff) + ldsw + _i * 8192), 16, 0, 0); } while (0)
; #define PG8_LDA(dst, b, h) do { _Pragma("unroll") for (int m = 0; m < 4; ++m) _Pragma("unroll") for (int k = 0; k < 2; ++k) dst[m][k] = *(const LAS bf16x8*)(lds + PG8_SA(b, h) + aoff + m * 2048 + k * 1024); } while (0)
; #define PG8_LDB(dst, b, h) do { _Pragma("unroll") for (int n = 0; n < 2; ++n) _Pragma("unroll") for (int k = 0; k < 2; ++k) dst[n][k] = *(const LAS bf16x8*)(lds + PG8_SB(b, h) + boff + n * 2048 + k * 1024); } while (0)
; #define PG8_MMA(ai, bj, At, Bt) do { __builtin_amdgcn_s_setprio(1); _Pragma("unroll") for (int m = 0; m < 4; ++m) _Pragma("unroll") for (int n = 0; n < 2; ++n) _Pragma("unroll") for (int k = 0; k < 2; ++k) \
;         acc[ai][bj][m][n] = __builtin_amdgcn_mfma_f32_16x16x32_bf16(Bt[n][k], At[m][k], acc[ai][bj][m][n], 0, 0, 0); __builtin_amdgcn_s_setprio(0); } while (0)
; #define PG8_WAIT_V(n) asm volatile("s_waitcnt vmcnt(" #n ")" ::: "memory")
; #define PG8_WAIT_L(n) asm volatile("s_waitcnt lgkmcnt(" #n ")" ::: "memory")
; #define PG8_BAR __builtin_amdgcn_s_barrier()
; #define PG8_SCHED __builtin_amdgcn_sched_barrier(0)
; template <class Epi>
; __device__ __forceinline__ void gemm_phase(LAS unsigned char* lds, const Gemm g, const StaticOrder& S, const Epi& E) {
;     ...
;             PG8_WAIT_L(8); PG8_BAR; PG8_WAIT_L(0); PG8_MMA(0, 0, At, B0); PG8_BAR; PG8_SCHED;
;             PG8_LDB(B1, 0, 1); PG8_STAGE(PG8_SB(0, 0), b2, voffB);
;             PG8_BAR; PG8_WAIT_L(0); PG8_MMA(0, 1, At, B1); PG8_BAR;
;             PG8_LDA(At, 0, 1); PG8_STAGE(PG8_SA(0, 0), a2, voffA);
;             PG8_BAR; PG8_WAIT_L(0); PG8_MMA(1, 0, At, B0); PG8_BAR; PG8_SCHED;
;             PG8_STAGE(PG8_SB(0, 1), b2 + hstepB, voffB);
;             PG8_WAIT_V(6); PG8_BAR; PG8_MMA(1, 1, At, B1); PG8_BAR;
;             PG8_LDB(B0, 1, 0); PG8_SCHED; PG8_LDA(At, 1, 0); PG8_STAGE(PG8_SA(0, 1), a2 + hstepA, voffA);
;             PG8_WAIT_L(8); PG8_BAR; PG8_WAIT_L(0); PG8_MMA(0, 0, At, B0); PG8_BAR; PG8_SCHED;
	v_mfma_f32_16x16x32_bf16 v[124:127], v[128:131], v[144:147], v[124:127]
	s_setprio 1
	v_mfma_f32_16x16x32_bf16 v[120:123], v[136:139], v[144:147], v[120:123]
	v_mfma_f32_16x16x32_bf16 v[116:119], v[128:131], v[162:165], v[116:119]
	v_mfma_f32_16x16x32_bf16 v[112:115], v[136:139], v[162:165], v[112:115]
	v_mfma_f32_16x16x32_bf16 v[108:111], v[128:131], v[170:173], v[108:111]
	v_mfma_f32_16x16x32_bf16 v[104:107], v[136:139], v[170:173], v[104:107]
	v_mfma_f32_16x16x32_bf16 v[100:103], v[128:131], v[178:181], v[100:103]
	v_mfma_f32_16x16x32_bf16 v[96:99], v[136:139], v[178:181], v[96:99]
	v_mfma_f32_16x16x32_bf16 v[124:127], v[132:135], v[148:151], v[124:127]
	v_mfma_f32_16x16x32_bf16 v[120:123], v[140:143], v[148:151], v[120:123]
	v_mfma_f32_16x16x32_bf16 v[116:119], v[132:135], v[166:169], v[116:119]
	v_mfma_f32_16x16x32_bf16 v[112:115], v[140:143], v[166:169], v[112:115]
	v_mfma_f32_16x16x32_bf16 v[108:111], v[132:135], v[174:177], v[108:111]
	v_mfma_f32_16x16x32_bf16 v[104:107], v[140:143], v[174:177], v[104:107]
	v_mfma_f32_16x16x32_bf16 v[100:103], v[132:135], v[182:185], v[100:103]
	v_mfma_f32_16x16x32_bf16 v[96:99], v[140:143], v[182:185], v[96:99]
	v_mfma_f32_16x16x32_bf16 v[92:95], v[186:189], v[144:147], v[92:95]
	v_mfma_f32_16x16x32_bf16 v[88:91], v[194:197], v[144:147], v[88:91]
	v_mfma_f32_16x16x32_bf16 v[84:87], v[186:189], v[162:165], v[84:87]
	v_mfma_f32_16x16x32_bf16 v[80:83], v[194:197], v[162:165], v[80:83]
	v_mfma_f32_16x16x32_bf16 v[76:79], v[186:189], v[170:173], v[76:79]
	v_mfma_f32_16x16x32_bf16 v[72:75], v[194:197], v[170:173], v[72:75]
	v_mfma_f32_16x16x32_bf16 v[68:71], v[186:189], v[178:181], v[68:71]
	v_mfma_f32_16x16x32_bf16 v[64:67], v[194:197], v[178:181], v[64:67]
	v_mfma_f32_16x16x32_bf16 v[92:95], v[190:193], v[148:151], v[92:95]
	v_mfma_f32_16x16x32_bf16 v[88:91], v[198:201], v[148:151], v[88:91]
	v_mfma_f32_16x16x32_bf16 v[84:87], v[190:193], v[166:169], v[84:87]
	v_mfma_f32_16x16x32_bf16 v[80:83], v[198:201], v[166:169], v[80:83]
	v_mfma_f32_16x16x32_bf16 v[76:79], v[190:193], v[174:177], v[76:79]
	v_mfma_f32_16x16x32_bf16 v[72:75], v[198:201], v[174:177], v[72:75]
	v_mfma_f32_16x16x32_bf16 v[68:71], v[190:193], v[182:185], v[68:71]
	s_setprio 0
	v_mfma_f32_16x16x32_bf16 v[64:67], v[198:201], v[182:185], v[64:67]
	s_barrier
	s_mov_b32 m0, s55
	v_lshl_add_u64 v[202:203], s[24:25], 0, v[152:153]
	global_load_lds_dwordx4 v[202:203], off
	s_add_i32 m0, s55, 0x2000
	v_lshl_add_u64 v[202:203], s[24:25], 0, v[156:157]
	global_load_lds_dwordx4 v[202:203], off
	s_mov_b32 m0, s33
	v_lshl_add_u64 v[202:203], s[26:27], 0, v[152:153]
	global_load_lds_dwordx4 v[202:203], off
	s_mov_b32 m0, s34
	v_lshl_add_u64 v[202:203], s[26:27], 0, v[156:157]
	global_load_lds_dwordx4 v[202:203], off
	s_add_u32 s56, s24, s52
	s_addc_u32 s57, s25, 0
	s_add_i32 s55, s58, s31
	s_mov_b32 m0, s55
	v_lshl_add_u64 v[202:203], s[56:57], 0, v[152:153]
	global_load_lds_dwordx4 v[202:203], off
	s_add_i32 m0, s55, 0x2000
	v_lshl_add_u64 v[202:203], s[56:57], 0, v[156:157]
	global_load_lds_dwordx4 v[202:203], off
	ds_read_b128 v[144:147], v209 offset:16384
	ds_read_b128 v[162:165], v209 offset:18432
	ds_read_b128 v[170:173], v209 offset:20480
	ds_read_b128 v[178:181], v209 offset:22528
	ds_read_b128 v[148:151], v209 offset:17408
	ds_read_b128 v[166:169], v209 offset:19456
	ds_read_b128 v[174:177], v209 offset:21504
	ds_read_b128 v[182:185], v209 offset:23552
	s_waitcnt vmcnt(6)
	s_waitcnt lgkmcnt(0)
	s_barrier
	v_mfma_f32_16x16x32_bf16 v[60:63], v[128:131], v[144:147], v[60:63]
	s_setprio 1
	v_mfma_f32_16x16x32_bf16 v[56:59], v[136:139], v[144:147], v[56:59]
	v_mfma_f32_16x16x32_bf16 v[52:55], v[128:131], v[162:165], v[52:55]
	v_mfma_f32_16x16x32_bf16 v[48:51], v[136:139], v[162:165], v[48:51]
	v_mfma_f32_16x16x32_bf16 v[44:47], v[128:131], v[170:173], v[44:47]
	v_mfma_f32_16x16x32_bf16 v[40:43], v[136:139], v[170:173], v[40:43]
	v_mfma_f32_16x16x32_bf16 v[36:39], v[128:131], v[178:181], v[36:39]
	v_mfma_f32_16x16x32_bf16 v[32:35], v[136:139], v[178:181], v[32:35]
	v_mfma_f32_16x16x32_bf16 v[60:63], v[132:135], v[148:151], v[60:63]
	v_mfma_f32_16x16x32_bf16 v[56:59], v[140:143], v[148:151], v[56:59]
	v_mfma_f32_16x16x32_bf16 v[52:55], v[132:135], v[166:169], v[52:55]
	v_mfma_f32_16x16x32_bf16 v[48:51], v[140:143], v[166:169], v[48:51]
	v_mfma_f32_16x16x32_bf16 v[44:47], v[132:135], v[174:177], v[44:47]
	v_mfma_f32_16x16x32_bf16 v[40:43], v[140:143], v[174:177], v[40:43]
	v_mfma_f32_16x16x32_bf16 v[36:39], v[132:135], v[182:185], v[36:39]
	v_mfma_f32_16x16x32_bf16 v[32:35], v[140:143], v[182:185], v[32:35]
	v_mfma_f32_16x16x32_bf16 v[28:31], v[186:189], v[144:147], v[28:31]
	v_mfma_f32_16x16x32_bf16 v[24:27], v[194:197], v[144:147], v[24:27]
	s_add_i32 s55, 0, 0x18000
	v_add_u32_e32 v140, s55, v207
	v_mfma_f32_16x16x32_bf16 v[20:23], v[186:189], v[162:165], v[20:23]
	v_mfma_f32_16x16x32_bf16 v[16:19], v[194:197], v[162:165], v[16:19]
	v_mfma_f32_16x16x32_bf16 v[12:15], v[186:189], v[170:173], v[12:15]
	v_mfma_f32_16x16x32_bf16 v[8:11], v[194:197], v[170:173], v[8:11]
	v_mfma_f32_16x16x32_bf16 v[4:7], v[186:189], v[178:181], v[4:7]
	v_mfma_f32_16x16x32_bf16 v[0:3], v[194:197], v[178:181], v[0:3]
	v_mfma_f32_16x16x32_bf16 v[28:31], v[190:193], v[148:151], v[28:31]
	v_mfma_f32_16x16x32_bf16 v[24:27], v[198:201], v[148:151], v[24:27]
	v_mfma_f32_16x16x32_bf16 v[20:23], v[190:193], v[166:169], v[20:23]
	v_mfma_f32_16x16x32_bf16 v[16:19], v[198:201], v[166:169], v[16:19]
	v_mfma_f32_16x16x32_bf16 v[12:15], v[190:193], v[174:177], v[12:15]
	v_mfma_f32_16x16x32_bf16 v[8:11], v[198:201], v[174:177], v[8:11]
	v_mfma_f32_16x16x32_bf16 v[4:7], v[190:193], v[182:185], v[4:7]
	s_setprio 0
	v_mfma_f32_16x16x32_bf16 v[0:3], v[198:201], v[182:185], v[0:3]
	s_barrier
; #define PG8_STAGE(bufoff, gbase, voff) do { _Pragma("unroll") for (int _i = 0; _i < 2; ++_i) \
;         __builtin_amdgcn_global_load_lds((const unsigned*)((const char*)(gbase) + (voff)[_i]), (LAS unsigned*)(lds + (bufoff) + ldsw + _i * 8192), 16, 0, 0); } while (0)
; #define PG8_LDA(dst, b, h) do { _Pragma("unroll") for (int m = 0; m < 4; ++m) _Pragma("unroll") for (int k = 0; k < 2; ++k) dst[m][k] = *(const LAS bf16x8*)(lds + PG8_SA(b, h) + aoff + m * 2048 + k * 1024); } while (0)
; #define PG8_LDB(dst, b, h) do { _Pragma("unroll") for (int n = 0; n < 2; ++n) _Pragma("unroll") for (int k = 0; k < 2; ++k) dst[n][k] = *(const LAS bf16x8*)(lds + PG8_SB(b, h) + boff + n * 2048 + k * 1024); } while (0)
; #define PG8_MMA(ai, bj, At, Bt) do { __builtin_amdgcn_s_setprio(1); _Pragma("unroll") for (int m = 0; m < 4; ++m) _Pragma("unroll") for (int n = 0; n < 2; ++n) _Pragma("unroll") for (int k = 0; k < 2; ++k) \
;         acc[ai][bj][m][n] = __builtin_amdgcn_mfma_f32_16x16x32_bf16(Bt[n][k], At[m][k], acc[ai][bj][m][n], 0, 0, 0); __builtin_amdgcn_s_setprio(0); } while (0)
; #define PG8_BAR __builtin_amdgcn_s_barrier()
; template <class Epi>
; __device__ __forceinline__ void gemm_phase(LAS unsigned char* lds, const Gemm g, const StaticOrder& S, const Epi& E) {
;     ...
;         for (int t = 0; t < nt; t += 2) {
;             const bool last = (t == nt - 2);
;             const char* a1 = cA + (size_t)(t + 1) * kstep;
;             const char* a2 = last ? nA : cA + (size_t)(t + 2) * kstep; const char* b2 = last ? nB : cB + (size_t)(t + 2) * kstep;
;             const char* a3 = a2 + kstep; const char* b3 = b2 + kstep;
;             PG8_LDB(B0, 0, 0); PG8_SCHED; PG8_LDA(At, 0, 0); PG8_STAGE(PG8_SA(1, 1), a1 + hstepA, voffA);
;             PG8_WAIT_L(8); PG8_BAR; PG8_WAIT_L(0); PG8_MMA(0, 0, At, B0); PG8_BAR; PG8_SCHED;
;             PG8_LDB(B1, 0, 1); PG8_STAGE(PG8_SB(0, 0), b2, voffB);
;             PG8_BAR; PG8_WAIT_L(0); PG8_MMA(0, 1, At, B1); PG8_BAR;
;     ...
;             PG8_LDB(B1, 1, 1); PG8_STAGE(PG8_SB(1, 0), b3, voffB);
;             PG8_BAR; PG8_WAIT_L(0); PG8_MMA(0, 1, At, B1); PG8_BAR;
;             PG8_LDA(At, 1, 1); PG8_STAGE(PG8_SA(1, 0), a3, voffA);
;             PG8_BAR; PG8_WAIT_L(0); PG8_MMA(1, 0, At, B0); PG8_BAR; PG8_SCHED;
;             PG8_STAGE(PG8_SB(1, 1), b3 + hstepB, voffB);
;             PG8_WAIT_V(6); PG8_BAR; PG8_MMA(1, 1, At, B1); PG8_BAR;
	s_add_u32 s26, s26, s52
	s_addc_u32 s27, s27, 0
	s_mov_b32 m0, s35
	v_lshl_add_u64 v[186:187], s[26:27], 0, v[152:153]
	global_load_lds_dwordx4 v[186:187], off
	s_mov_b32 m0, s36
	v_lshl_add_u64 v[186:187], s[26:27], 0, v[156:157]
	global_load_lds_dwordx4 v[186:187], off
	ds_read_b128 v[128:131], v140
	ds_read_b128 v[136:139], v140 offset:2048
	ds_read_b128 v[132:135], v140 offset:1024
	ds_read_b128 v[140:143], v140 offset:3072
	ds_read_b128 v[144:147], v209 offset:32768
	ds_read_b128 v[162:165], v209 offset:34816
	ds_read_b128 v[170:173], v209 offset:36864
	ds_read_b128 v[178:181], v209 offset:38912
	ds_read_b128 v[148:151], v209 offset:33792
	ds_read_b128 v[166:169], v209 offset:35840
	ds_read_b128 v[174:177], v209 offset:37888
	ds_read_b128 v[182:185], v209 offset:39936
	s_mov_b32 s26, 0x1c000
	s_add_u32 s24, s24, 0x4000
	s_addc_u32 s25, s25, 0
	s_add_i32 s27, s55, s31
	v_add_u32_e32 v198, s26, v207
	ds_read_b128 v[186:189], v198
	ds_read_b128 v[194:197], v198 offset:2048
	ds_read_b128 v[190:193], v198 offset:1024
	ds_read_b128 v[198:201], v198 offset:3072
	s_waitcnt lgkmcnt(0)
	s_barrier
	v_mfma_f32_16x16x32_bf16 v[124:127], v[128:131], v[144:147], v[124:127]
	s_setprio 1
	v_mfma_f32_16x16x32_bf16 v[120:123], v[136:139], v[144:147], v[120:123]
	v_mfma_f32_16x16x32_bf16 v[116:119], v[128:131], v[162:165], v[116:119]
	v_mfma_f32_16x16x32_bf16 v[112:115], v[136:139], v[162:165], v[112:115]
	v_mfma_f32_16x16x32_bf16 v[108:111], v[128:131], v[170:173], v[108:111]
	v_mfma_f32_16x16x32_bf16 v[104:107], v[136:139], v[170:173], v[104:107]
	v_mfma_f32_16x16x32_bf16 v[100:103], v[128:131], v[178:181], v[100:103]
	v_mfma_f32_16x16x32_bf16 v[96:99], v[136:139], v[178:181], v[96:99]
	v_mfma_f32_16x16x32_bf16 v[124:127], v[132:135], v[148:151], v[124:127]
	v_mfma_f32_16x16x32_bf16 v[120:123], v[140:143], v[148:151], v[120:123]
	v_mfma_f32_16x16x32_bf16 v[116:119], v[132:135], v[166:169], v[116:119]
	v_mfma_f32_16x16x32_bf16 v[112:115], v[140:143], v[166:169], v[112:115]
	v_mfma_f32_16x16x32_bf16 v[108:111], v[132:135], v[174:177], v[108:111]
	v_mfma_f32_16x16x32_bf16 v[104:107], v[140:143], v[174:177], v[104:107]
	v_mfma_f32_16x16x32_bf16 v[100:103], v[132:135], v[182:185], v[100:103]
	v_mfma_f32_16x16x32_bf16 v[96:99], v[140:143], v[182:185], v[96:99]
	v_mfma_f32_16x16x32_bf16 v[92:95], v[186:189], v[144:147], v[92:95]
	v_mfma_f32_16x16x32_bf16 v[88:91], v[194:197], v[144:147], v[88:91]
	v_mfma_f32_16x16x32_bf16 v[84:87], v[186:189], v[162:165], v[84:87]
	v_mfma_f32_16x16x32_bf16 v[80:83], v[194:197], v[162:165], v[80:83]
	v_mfma_f32_16x16x32_bf16 v[76:79], v[186:189], v[170:173], v[76:79]
	v_mfma_f32_16x16x32_bf16 v[72:75], v[194:197], v[170:173], v[72:75]
	v_mfma_f32_16x16x32_bf16 v[68:71], v[186:189], v[178:181], v[68:71]
	v_mfma_f32_16x16x32_bf16 v[64:67], v[194:197], v[178:181], v[64:67]
	v_mfma_f32_16x16x32_bf16 v[92:95], v[190:193], v[148:151], v[92:95]
	v_mfma_f32_16x16x32_bf16 v[88:91], v[198:201], v[148:151], v[88:91]
	v_mfma_f32_16x16x32_bf16 v[84:87], v[190:193], v[166:169], v[84:87]
	v_mfma_f32_16x16x32_bf16 v[80:83], v[198:201], v[166:169], v[80:83]
	v_mfma_f32_16x16x32_bf16 v[76:79], v[190:193], v[174:177], v[76:79]
	v_mfma_f32_16x16x32_bf16 v[72:75], v[198:201], v[174:177], v[72:75]
	v_mfma_f32_16x16x32_bf16 v[68:71], v[190:193], v[182:185], v[68:71]
	s_setprio 0
	v_mfma_f32_16x16x32_bf16 v[64:67], v[198:201], v[182:185], v[64:67]
	s_barrier
	s_mov_b32 m0, s27
	v_lshl_add_u64 v[202:203], s[24:25], 0, v[152:153]
	global_load_lds_dwordx4 v[202:203], off
	s_add_i32 m0, s27, 0x2000
	v_lshl_add_u64 v[202:203], s[24:25], 0, v[156:157]
	global_load_lds_dwordx4 v[202:203], off
	s_mov_b32 m0, s38
	v_lshl_add_u64 v[202:203], s[22:23], 0, v[152:153]
	global_load_lds_dwordx4 v[202:203], off
	s_mov_b32 m0, s39
	v_lshl_add_u64 v[202:203], s[22:23], 0, v[156:157]
	global_load_lds_dwordx4 v[202:203], off
	s_add_u32 s22, s24, s52
	s_addc_u32 s23, s25, 0
	s_add_i32 s24, s26, s31
	s_mov_b32 m0, s24
	v_lshl_add_u64 v[202:203], s[22:23], 0, v[152:153]
	global_load_lds_dwordx4 v[202:203], off
	s_add_i32 m0, s24, 0x2000
	v_lshl_add_u64 v[202:203], s[22:23], 0, v[156:157]
	global_load_lds_dwordx4 v[202:203], off
	ds_read_b128 v[144:147], v209 offset:49152
	ds_read_b128 v[162:165], v209 offset:51200
	ds_read_b128 v[170:173], v209 offset:53248
	ds_read_b128 v[178:181], v209 offset:55296
	ds_read_b128 v[148:151], v209 offset:50176
	ds_read_b128 v[166:169], v209 offset:52224
	ds_read_b128 v[174:177], v209 offset:54272
	ds_read_b128 v[182:185], v209 offset:56320
	s_waitcnt vmcnt(6)
	s_waitcnt lgkmcnt(0)
	s_barrier
	v_mfma_f32_16x16x32_bf16 v[60:63], v[128:131], v[144:147], v[60:63]
	s_setprio 1
	v_mfma_f32_16x16x32_bf16 v[56:59], v[136:139], v[144:147], v[56:59]
	v_mfma_f32_16x16x32_bf16 v[52:55], v[128:131], v[162:165], v[52:55]
	v_mfma_f32_16x16x32_bf16 v[48:51], v[136:139], v[162:165], v[48:51]
	v_mfma_f32_16x16x32_bf16 v[44:47], v[128:131], v[170:173], v[44:47]
	v_mfma_f32_16x16x32_bf16 v[40:43], v[136:139], v[170:173], v[40:43]
	v_mfma_f32_16x16x32_bf16 v[36:39], v[128:131], v[178:181], v[36:39]
	v_mfma_f32_16x16x32_bf16 v[32:35], v[136:139], v[178:181], v[32:35]
	v_mfma_f32_16x16x32_bf16 v[60:63], v[132:135], v[148:151], v[60:63]
	v_mfma_f32_16x16x32_bf16 v[56:59], v[140:143], v[148:151], v[56:59]
	v_mfma_f32_16x16x32_bf16 v[52:55], v[132:135], v[166:169], v[52:55]
	v_mfma_f32_16x16x32_bf16 v[48:51], v[140:143], v[166:169], v[48:51]
	v_mfma_f32_16x16x32_bf16 v[44:47], v[132:135], v[174:177], v[44:47]
	v_mfma_f32_16x16x32_bf16 v[40:43], v[140:143], v[174:177], v[40:43]
	v_mfma_f32_16x16x32_bf16 v[36:39], v[132:135], v[182:185], v[36:39]
	v_mfma_f32_16x16x32_bf16 v[32:35], v[140:143], v[182:185], v[32:35]
	v_mfma_f32_16x16x32_bf16 v[28:31], v[186:189], v[144:147], v[28:31]
	v_mfma_f32_16x16x32_bf16 v[24:27], v[194:197], v[144:147], v[24:27]
	s_add_u32 s4, s4, 0x8000
	s_addc_u32 s5, s5, 0
	s_add_u32 s50, s50, 0x8000
	s_addc_u32 s51, s51, 0
	v_mfma_f32_16x16x32_bf16 v[20:23], v[186:189], v[162:165], v[20:23]
	v_mfma_f32_16x16x32_bf16 v[16:19], v[194:197], v[162:165], v[16:19]
	v_mfma_f32_16x16x32_bf16 v[12:15], v[186:189], v[170:173], v[12:15]
	v_mfma_f32_16x16x32_bf16 v[8:11], v[194:197], v[170:173], v[8:11]
	v_mfma_f32_16x16x32_bf16 v[4:7], v[186:189], v[178:181], v[4:7]
	v_mfma_f32_16x16x32_bf16 v[0:3], v[194:197], v[178:181], v[0:3]
	v_mfma_f32_16x16x32_bf16 v[28:31], v[190:193], v[148:151], v[28:31]
	v_mfma_f32_16x16x32_bf16 v[24:27], v[198:201], v[148:151], v[24:27]
	v_mfma_f32_16x16x32_bf16 v[20:23], v[190:193], v[166:169], v[20:23]
	v_mfma_f32_16x16x32_bf16 v[16:19], v[198:201], v[166:169], v[16:19]
	v_mfma_f32_16x16x32_bf16 v[12:15], v[190:193], v[174:177], v[12:15]
	v_mfma_f32_16x16x32_bf16 v[8:11], v[198:201], v[174:177], v[8:11]
	v_mfma_f32_16x16x32_bf16 v[4:7], v[190:193], v[182:185], v[4:7]
	s_cmp_ge_u32 s54, s28
	s_mov_b32 s22, s54
	s_setprio 0
	v_mfma_f32_16x16x32_bf16 v[0:3], v[198:201], v[182:185], v[0:3]
	s_cbranch_scc1 .Lkexit_187
	s_barrier
	s_branch .LBB0_187
; #define PG8_MMA(ai, bj, At, Bt) do { __builtin_amdgcn_s_setprio(1); _Pragma("unroll") for (int m = 0; m < 4; ++m) _Pragma("unroll") for (int n = 0; n < 2; ++n) _Pragma("unroll") for (int k = 0; k < 2; ++k) \
;         acc[ai][bj][m][n] = __builtin_amdgcn_mfma_f32_16x16x32_bf16(Bt[n][k], At[m][k], acc[ai][bj][m][n], 0, 0, 0); __builtin_amdgcn_s_setprio(0); } while (0)
; #define PG8_WAIT_V(n) asm volatile("s_waitcnt vmcnt(" #n ")" ::: "memory")
; #define PG8_BAR __builtin_amdgcn_s_barrier()
; template <class Epi>
; __device__ __forceinline__ void gemm_phase(LAS unsigned char* lds, const Gemm g, const StaticOrder& S, const Epi& E) {
;     ...
;             PG8_WAIT_V(6); PG8_BAR; PG8_MMA(1, 1, At, B1); PG8_BAR;
;         }
;         E(acc, cur, wr, wc, fr, fq);
;         if (!has_next) break;
.Lkexit_187:
	s_cmpk_gt_u32 s29, 0xff
	s_cbranch_scc1 .Lpeel_done_187
	s_barrier

; __device__ __forceinline__ unsigned cvt_pk_bf16(float lo, float hi) { unsigned r; asm volatile("v_cvt_pk_bf16_f32 %0, %1, %2" : "=v"(r) : "v"(lo), "v"(hi)); return r; }
; template <class Epi>
; __device__ __forceinline__ void gemm_phase(LAS unsigned char* lds, const Gemm g, const StaticOrder& S, const Epi& E) {
;     ...
;         cur = nxt; cA = nA; cB = nB; ++ui;
;     __device__ __forceinline__ void operator()(const f32x4 (&acc)[2][2][4][2], const Unit& u, int wr, int wc, int fr, int fq) const {
;     ...
;                         u32x2 w1, w2; w1.x = cvt_pk_bf16(o1[0], o1[1]); w1.y = cvt_pk_bf16(o1[2], o1[3]); w2.x = cvt_pk_bf16(o2[0], o2[1]); w2.y = cvt_pk_bf16(o2[2], o2[3]);
;                         *(u32x2*)(rowp + bj * HALF) = w1; *(u32x2*)(rowp + bj * HALF + 64) = w2;
;                     }
.LBB0_243:
	s_and_b64 vcc, exec, s[0:1]
	s_mov_b32 s34, s2
	s_mov_b32 s10, s4
	s_mov_b64 s[14:15], s[8:9]
	s_mov_b64 s[12:13], s[6:7]
	global_store_dwordx2 v[128:129], v[130:131], off offset:256
	global_store_dwordx2 v[128:129], v[132:133], off offset:384
	s_cmpk_gt_u32 s20, 0xff
	s_cbranch_scc0 .Lyb_247
	s_barrier

; #define PG8_STAGE(bufoff, gbase, voff) do { _Pragma("unroll") for (int _i = 0; _i < 2; ++_i) \
;         __builtin_amdgcn_global_load_lds((const unsigned*)((const char*)(gbase) + (voff)[_i]), (LAS unsigned*)(lds + (bufoff) + ldsw + _i * 8192), 16, 0, 0); } while (0)
; #define PG8_LDA(dst, b, h) do { _Pragma("unroll") for (int m = 0; m < 4; ++m) _Pragma("unroll") for (int k = 0; k < 2; ++k) dst[m][k] = *(const LAS bf16x8*)(lds + PG8_SA(b, h) + aoff + m * 2048 + k * 1024); } while (0)
; #define PG8_LDB(dst, b, h) do { _Pragma("unroll") for (int n = 0; n < 2; ++n) _Pragma("unroll") for (int k = 0; k < 2; ++k) dst[n][k] = *(const LAS bf16x8*)(lds + PG8_SB(b, h) + boff + n * 2048 + k * 1024); } while (0)
; #define PG8_WAIT_V(n) asm volatile("s_waitcnt vmcnt(" #n ")" ::: "memory")
; #define PG8_WAIT_L(n) asm volatile("s_waitcnt lgkmcnt(" #n ")" ::: "memory")
; #define PG8_BAR __builtin_amdgcn_s_barrier()
; #define PG8_SCHED __builtin_amdgcn_sched_barrier(0)
; template <class Epi>
; __device__ __forceinline__ void gemm_phase(LAS unsigned char* lds, const Gemm g, const StaticOrder& S, const Epi& E) {
;     ...
;         const bool has_next = S.next(ui + 1, nxt);
;         const char* nA = has_next ? (const char*)g.A + (size_t)nxt.pm * tstepA : cA; const char* nB = has_next ? (const char*)g.Bt + (size_t)nxt.pn * tstepB : cB;
;         for (int t = 0; t < nt; t += 2) {
;             const bool last = (t == nt - 2);
;             const char* a1 = cA + (size_t)(t + 1) * kstep;
;             const char* a2 = last ? nA : cA + (size_t)(t + 2) * kstep; const char* b2 = last ? nB : cB + (size_t)(t + 2) * kstep;
;             const char* a3 = a2 + kstep; const char* b3 = b2 + kstep;
;             PG8_LDB(B0, 0, 0); PG8_SCHED; PG8_LDA(At, 0, 0); PG8_STAGE(PG8_SA(1, 1), a1 + hstepA, voffA);
;             PG8_WAIT_L(8); PG8_BAR; PG8_WAIT_L(0); PG8_MMA(0, 0, At, B0); PG8_BAR; PG8_SCHED;
;             PG8_LDB(B1, 0, 1); PG8_STAGE(PG8_SB(0, 0), b2, voffB);
;             PG8_BAR; PG8_WAIT_L(0); PG8_MMA(0, 1, At, B1); PG8_BAR;
;             PG8_LDA(At, 0, 1); PG8_STAGE(PG8_SA(0, 0), a2, voffA);
;             PG8_BAR; PG8_WAIT_L(0); PG8_MMA(1, 0, At, B0); PG8_BAR; PG8_SCHED;
;             PG8_STAGE(PG8_SB(0, 1), b2 + hstepB, voffB);
;             PG8_WAIT_V(6); PG8_BAR; PG8_MMA(1, 1, At, B1); PG8_BAR;
.LBB0_246:
	s_ashr_i32 s5, s4, 31
	v_cmp_lt_i64_e32 vcc, s[6:7], v[154:155]
	s_lshl_b64 s[6:7], s[4:5], 20
	v_readlane_b32 s8, v252, 53
	v_readlane_b32 s9, v252, 54
	s_add_u32 s6, s8, s6
	s_addc_u32 s7, s9, s7
	s_and_b64 s[8:9], vcc, exec
	s_cselect_b32 s5, s7, s13
	s_cselect_b32 s11, s6, s12
	s_ashr_i32 s3, s2, 31
	s_lshl_b64 s[8:9], s[2:3], 20
	s_add_u32 s8, s21, s8
	s_addc_u32 s9, s22, s9
	s_and_b64 s[16:17], vcc, exec
	s_cselect_b32 s3, s9, s15
	s_cselect_b32 s35, s8, s14
	s_add_u32 s12, s12, 0x84000
	s_addc_u32 s13, s13, 0
	s_add_u32 s36, s14, 0x8000
	s_addc_u32 s37, s15, 0
	s_mov_b32 s38, -2
	s_add_u32 s14, s12, 0xfff84000
	s_addc_u32 s15, s13, -1
	s_cmp_eq_u32 s38, 28
	s_cselect_b32 s18, s11, s14
	s_cselect_b32 s19, s5, s15
	s_cselect_b32 s14, s35, s36
	s_cselect_b32 s15, s3, s37
	s_add_u32 s16, s18, 0x4000
	s_addc_u32 s17, s19, 0
	s_add_i32 m0, s25, 0xc000
	v_lshl_add_u64 v[194:195], s[12:13], 0, v[156:157]
	global_load_lds_dwordx4 v[194:195], off
	s_add_i32 m0, s25, 0xe000
	v_lshl_add_u64 v[194:195], s[12:13], 0, v[158:159]
	global_load_lds_dwordx4 v[194:195], off
	s_mov_b32 s39, 0x10000
	v_add_u32_e32 v140, s39, v170
	ds_read_b128 v[128:131], v140
	ds_read_b128 v[136:139], v140 offset:2048
	ds_read_b128 v[132:135], v140 offset:1024
	ds_read_b128 v[140:143], v140 offset:3072
	ds_read_b128 v[144:147], v172
	ds_read_b128 v[166:169], v172 offset:2048
	ds_read_b128 v[178:181], v172 offset:4096
	ds_read_b128 v[186:189], v172 offset:6144
	ds_read_b128 v[148:151], v172 offset:1024
	ds_read_b128 v[174:177], v172 offset:3072
	ds_read_b128 v[182:185], v172 offset:5120
	ds_read_b128 v[190:193], v172 offset:7168
	s_mov_b32 s42, 0x14000
	s_add_i32 s39, s39, s23
	v_add_u32_e32 v152, s42, v170
	ds_read_b128 v[194:197], v152
	ds_read_b128 v[202:205], v152 offset:2048
	ds_read_b128 v[198:201], v152 offset:1024
	ds_read_b128 v[206:209], v152 offset:3072
	s_waitcnt lgkmcnt(0)
	s_barrier
	v_mfma_f32_16x16x32_bf16 v[124:127], v[128:131], v[144:147], 0
	s_setprio 1
	v_mfma_f32_16x16x32_bf16 v[120:123], v[136:139], v[144:147], 0
	v_mfma_f32_16x16x32_bf16 v[108:111], v[128:131], v[166:169], 0
	v_mfma_f32_16x16x32_bf16 v[104:107], v[136:139], v[166:169], 0
	v_mfma_f32_16x16x32_bf16 v[92:95], v[128:131], v[178:181], 0
	v_mfma_f32_16x16x32_bf16 v[88:91], v[136:139], v[178:181], 0
	v_mfma_f32_16x16x32_bf16 v[76:79], v[128:131], v[186:189], 0
	v_mfma_f32_16x16x32_bf16 v[72:75], v[136:139], v[186:189], 0
	v_mfma_f32_16x16x32_bf16 v[124:127], v[132:135], v[148:151], v[124:127]
	v_mfma_f32_16x16x32_bf16 v[120:123], v[140:143], v[148:151], v[120:123]
	v_mfma_f32_16x16x32_bf16 v[108:111], v[132:135], v[174:177], v[108:111]
	v_mfma_f32_16x16x32_bf16 v[104:107], v[140:143], v[174:177], v[104:107]
	v_mfma_f32_16x16x32_bf16 v[92:95], v[132:135], v[182:185], v[92:95]
	v_mfma_f32_16x16x32_bf16 v[88:91], v[140:143], v[182:185], v[88:91]
	v_mfma_f32_16x16x32_bf16 v[76:79], v[132:135], v[190:193], v[76:79]
	v_mfma_f32_16x16x32_bf16 v[72:75], v[140:143], v[190:193], v[72:75]
	v_mfma_f32_16x16x32_bf16 v[116:119], v[194:197], v[144:147], 0
	v_mfma_f32_16x16x32_bf16 v[112:115], v[202:205], v[144:147], 0
	v_mfma_f32_16x16x32_bf16 v[100:103], v[194:197], v[166:169], 0
	v_mfma_f32_16x16x32_bf16 v[96:99], v[202:205], v[166:169], 0
	v_mfma_f32_16x16x32_bf16 v[84:87], v[194:197], v[178:181], 0
	v_mfma_f32_16x16x32_bf16 v[80:83], v[202:205], v[178:181], 0
	v_mfma_f32_16x16x32_bf16 v[68:71], v[194:197], v[186:189], 0
	v_mfma_f32_16x16x32_bf16 v[64:67], v[202:205], v[186:189], 0
	v_mfma_f32_16x16x32_bf16 v[116:119], v[198:201], v[148:151], v[116:119]
	v_mfma_f32_16x16x32_bf16 v[112:115], v[206:209], v[148:151], v[112:115]
	v_mfma_f32_16x16x32_bf16 v[100:103], v[198:201], v[174:177], v[100:103]
	v_mfma_f32_16x16x32_bf16 v[96:99], v[206:209], v[174:177], v[96:99]
	v_mfma_f32_16x16x32_bf16 v[84:87], v[198:201], v[182:185], v[84:87]
	v_mfma_f32_16x16x32_bf16 v[80:83], v[206:209], v[182:185], v[80:83]
	v_mfma_f32_16x16x32_bf16 v[68:71], v[198:201], v[190:193], v[68:71]
	s_setprio 0
	v_mfma_f32_16x16x32_bf16 v[64:67], v[206:209], v[190:193], v[64:67]
	s_barrier
	s_mov_b32 m0, s39
	v_lshl_add_u64 v[210:211], s[14:15], 0, v[156:157]
	global_load_lds_dwordx4 v[210:211], off
	s_add_i32 m0, s39, 0x2000
	v_lshl_add_u64 v[210:211], s[14:15], 0, v[158:159]
	global_load_lds_dwordx4 v[210:211], off
	s_mov_b32 m0, s25
	v_lshl_add_u64 v[210:211], s[18:19], 0, v[156:157]
	global_load_lds_dwordx4 v[210:211], off
	s_mov_b32 m0, s26
	v_lshl_add_u64 v[210:211], s[18:19], 0, v[158:159]
	global_load_lds_dwordx4 v[210:211], off
	s_add_u32 s40, s14, 0x80000
	s_addc_u32 s41, s15, 0
	s_add_i32 s39, s42, s23
	s_mov_b32 m0, s39
	v_lshl_add_u64 v[210:211], s[40:41], 0, v[156:157]
	global_load_lds_dwordx4 v[210:211], off
	s_add_i32 m0, s39, 0x2000
	v_lshl_add_u64 v[210:211], s[40:41], 0, v[158:159]
	global_load_lds_dwordx4 v[210:211], off
	ds_read_b128 v[144:147], v172 offset:16384
	ds_read_b128 v[166:169], v172 offset:18432
	ds_read_b128 v[178:181], v172 offset:20480
	ds_read_b128 v[186:189], v172 offset:22528
	ds_read_b128 v[148:151], v172 offset:17408
	ds_read_b128 v[174:177], v172 offset:19456
	ds_read_b128 v[182:185], v172 offset:21504
	ds_read_b128 v[190:193], v172 offset:23552
	s_waitcnt vmcnt(6)
	s_waitcnt lgkmcnt(0)
	s_barrier
; #define PG8_STAGE(bufoff, gbase, voff) do { _Pragma("unroll") for (int _i = 0; _i < 2; ++_i) \
;         __builtin_amdgcn_global_load_lds((const unsigned*)((const char*)(gbase) + (voff)[_i]), (LAS unsigned*)(lds + (bufoff) + ldsw + _i * 8192), 16, 0, 0); } while (0)
; #define PG8_LDA(dst, b, h) do { _Pragma("unroll") for (int m = 0; m < 4; ++m) _Pragma("unroll") for (int k = 0; k < 2; ++k) dst[m][k] = *(const LAS bf16x8*)(lds + PG8_SA(b, h) + aoff + m * 2048 + k * 1024); } while (0)
; #define PG8_LDB(dst, b, h) do { _Pragma("unroll") for (int n = 0; n < 2; ++n) _Pragma("unroll") for (int k = 0; k < 2; ++k) dst[n][k] = *(const LAS bf16x8*)(lds + PG8_SB(b, h) + boff + n * 2048 + k * 1024); } while (0)
; #define PG8_MMA(ai, bj, At, Bt) do { __builtin_amdgcn_s_setprio(1); _Pragma("unroll") for (int m = 0; m < 4; ++m) _Pragma("unroll") for (int n = 0; n < 2; ++n) _Pragma("unroll") for (int k = 0; k < 2; ++k) \
;         acc[ai][bj][m][n] = __builtin_amdgcn_mfma_f32_16x16x32_bf16(Bt[n][k], At[m][k], acc[ai][bj][m][n], 0, 0, 0); __builtin_amdgcn_s_setprio(0); } while (0)
; #define PG8_WAIT_V(n) asm volatile("s_waitcnt vmcnt(" #n ")" ::: "memory")
; #define PG8_WAIT_L(n) asm volatile("s_waitcnt lgkmcnt(" #n ")" ::: "memory")
; #define PG8_BAR __builtin_amdgcn_s_barrier()
; #define PG8_SCHED __builtin_amdgcn_sched_barrier(0)
; template <class Epi>
; __device__ __forceinline__ void gemm_phase(LAS unsigned char* lds, const Gemm g, const StaticOrder& S, const Epi& E) {
;     ...
;             PG8_BAR; PG8_WAIT_L(0); PG8_MMA(1, 0, At, B0); PG8_BAR; PG8_SCHED;
;             PG8_STAGE(PG8_SB(0, 1), b2 + hstepB, voffB);
;             PG8_WAIT_V(6); PG8_BAR; PG8_MMA(1, 1, At, B1); PG8_BAR;
;             PG8_LDB(B0, 1, 0); PG8_SCHED; PG8_LDA(At, 1, 0); PG8_STAGE(PG8_SA(0, 1), a2 + hstepA, voffA);
;             PG8_WAIT_L(8); PG8_BAR; PG8_WAIT_L(0); PG8_MMA(0, 0, At, B0); PG8_BAR; PG8_SCHED;
;             PG8_LDB(B1, 1, 1); PG8_STAGE(PG8_SB(1, 0), b3, voffB);
;             PG8_BAR; PG8_WAIT_L(0); PG8_MMA(0, 1, At, B1); PG8_BAR;
;             PG8_LDA(At, 1, 1); PG8_STAGE(PG8_SA(1, 0), a3, voffA);
;             PG8_BAR; PG8_WAIT_L(0); PG8_MMA(1, 0, At, B0); PG8_BAR; PG8_SCHED;
	v_mfma_f32_16x16x32_bf16 v[60:63], v[128:131], v[144:147], 0
	s_setprio 1
	v_mfma_f32_16x16x32_bf16 v[56:59], v[136:139], v[144:147], 0
	v_mfma_f32_16x16x32_bf16 v[44:47], v[128:131], v[166:169], 0
	v_mfma_f32_16x16x32_bf16 v[40:43], v[136:139], v[166:169], 0
	v_mfma_f32_16x16x32_bf16 v[28:31], v[128:131], v[178:181], 0
	v_mfma_f32_16x16x32_bf16 v[24:27], v[136:139], v[178:181], 0
	v_mfma_f32_16x16x32_bf16 v[12:15], v[128:131], v[186:189], 0
	v_mfma_f32_16x16x32_bf16 v[8:11], v[136:139], v[186:189], 0
	v_mfma_f32_16x16x32_bf16 v[60:63], v[132:135], v[148:151], v[60:63]
	v_mfma_f32_16x16x32_bf16 v[56:59], v[140:143], v[148:151], v[56:59]
	v_mfma_f32_16x16x32_bf16 v[44:47], v[132:135], v[174:177], v[44:47]
	v_mfma_f32_16x16x32_bf16 v[40:43], v[140:143], v[174:177], v[40:43]
	v_mfma_f32_16x16x32_bf16 v[28:31], v[132:135], v[182:185], v[28:31]
	v_mfma_f32_16x16x32_bf16 v[24:27], v[140:143], v[182:185], v[24:27]
	v_mfma_f32_16x16x32_bf16 v[12:15], v[132:135], v[190:193], v[12:15]
	v_mfma_f32_16x16x32_bf16 v[8:11], v[140:143], v[190:193], v[8:11]
	v_mfma_f32_16x16x32_bf16 v[52:55], v[194:197], v[144:147], 0
	v_mfma_f32_16x16x32_bf16 v[48:51], v[202:205], v[144:147], 0
	s_add_i32 s39, 0, 0x18000
	v_add_u32_e32 v140, s39, v170
	v_mfma_f32_16x16x32_bf16 v[36:39], v[194:197], v[166:169], 0
	v_mfma_f32_16x16x32_bf16 v[32:35], v[202:205], v[166:169], 0
	v_mfma_f32_16x16x32_bf16 v[20:23], v[194:197], v[178:181], 0
	v_mfma_f32_16x16x32_bf16 v[16:19], v[202:205], v[178:181], 0
	v_mfma_f32_16x16x32_bf16 v[4:7], v[194:197], v[186:189], 0
	v_mfma_f32_16x16x32_bf16 v[0:3], v[202:205], v[186:189], 0
	v_mfma_f32_16x16x32_bf16 v[52:55], v[198:201], v[148:151], v[52:55]
	v_mfma_f32_16x16x32_bf16 v[48:51], v[206:209], v[148:151], v[48:51]
	v_mfma_f32_16x16x32_bf16 v[36:39], v[198:201], v[174:177], v[36:39]
	v_mfma_f32_16x16x32_bf16 v[32:35], v[206:209], v[174:177], v[32:35]
	v_mfma_f32_16x16x32_bf16 v[20:23], v[198:201], v[182:185], v[20:23]
	v_mfma_f32_16x16x32_bf16 v[16:19], v[206:209], v[182:185], v[16:19]
	v_mfma_f32_16x16x32_bf16 v[4:7], v[198:201], v[190:193], v[4:7]
	s_setprio 0
	v_mfma_f32_16x16x32_bf16 v[0:3], v[206:209], v[190:193], v[0:3]
	s_barrier
	s_add_u32 s18, s18, 0x80000
	s_addc_u32 s19, s19, 0
	s_mov_b32 m0, s27
	v_lshl_add_u64 v[194:195], s[18:19], 0, v[156:157]
	global_load_lds_dwordx4 v[194:195], off
	s_mov_b32 m0, s28
	v_lshl_add_u64 v[194:195], s[18:19], 0, v[158:159]
	global_load_lds_dwordx4 v[194:195], off
	ds_read_b128 v[128:131], v140
	ds_read_b128 v[136:139], v140 offset:2048
	ds_read_b128 v[132:135], v140 offset:1024
	ds_read_b128 v[140:143], v140 offset:3072
	ds_read_b128 v[144:147], v172 offset:32768
	ds_read_b128 v[166:169], v172 offset:34816
	ds_read_b128 v[178:181], v172 offset:36864
	ds_read_b128 v[186:189], v172 offset:38912
	ds_read_b128 v[148:151], v172 offset:33792
	ds_read_b128 v[174:177], v172 offset:35840
	ds_read_b128 v[182:185], v172 offset:37888
	ds_read_b128 v[190:193], v172 offset:39936
	s_mov_b32 s40, 0x1c000
	s_add_u32 s18, s14, 0x4000
	s_addc_u32 s19, s15, 0
	s_add_i32 s39, s39, s23
	v_add_u32_e32 v152, s40, v170
	ds_read_b128 v[194:197], v152
	ds_read_b128 v[202:205], v152 offset:2048
	ds_read_b128 v[198:201], v152 offset:1024
	ds_read_b128 v[206:209], v152 offset:3072
	s_waitcnt lgkmcnt(0)
	s_barrier
	v_mfma_f32_16x16x32_bf16 v[124:127], v[128:131], v[144:147], v[124:127]
	s_setprio 1
	v_mfma_f32_16x16x32_bf16 v[120:123], v[136:139], v[144:147], v[120:123]
	v_mfma_f32_16x16x32_bf16 v[108:111], v[128:131], v[166:169], v[108:111]
	v_mfma_f32_16x16x32_bf16 v[104:107], v[136:139], v[166:169], v[104:107]
	v_mfma_f32_16x16x32_bf16 v[92:95], v[128:131], v[178:181], v[92:95]
	v_mfma_f32_16x16x32_bf16 v[88:91], v[136:139], v[178:181], v[88:91]
	v_mfma_f32_16x16x32_bf16 v[76:79], v[128:131], v[186:189], v[76:79]
	v_mfma_f32_16x16x32_bf16 v[72:75], v[136:139], v[186:189], v[72:75]
	v_mfma_f32_16x16x32_bf16 v[124:127], v[132:135], v[148:151], v[124:127]
	v_mfma_f32_16x16x32_bf16 v[120:123], v[140:143], v[148:151], v[120:123]
	v_mfma_f32_16x16x32_bf16 v[108:111], v[132:135], v[174:177], v[108:111]
	v_mfma_f32_16x16x32_bf16 v[104:107], v[140:143], v[174:177], v[104:107]
	v_mfma_f32_16x16x32_bf16 v[92:95], v[132:135], v[182:185], v[92:95]
	v_mfma_f32_16x16x32_bf16 v[88:91], v[140:143], v[182:185], v[88:91]
	v_mfma_f32_16x16x32_bf16 v[76:79], v[132:135], v[190:193], v[76:79]
	v_mfma_f32_16x16x32_bf16 v[72:75], v[140:143], v[190:193], v[72:75]
	v_mfma_f32_16x16x32_bf16 v[116:119], v[194:197], v[144:147], v[116:119]
	v_mfma_f32_16x16x32_bf16 v[112:115], v[202:205], v[144:147], v[112:115]
	v_mfma_f32_16x16x32_bf16 v[100:103], v[194:197], v[166:169], v[100:103]
	v_mfma_f32_16x16x32_bf16 v[96:99], v[202:205], v[166:169], v[96:99]
	v_mfma_f32_16x16x32_bf16 v[84:87], v[194:197], v[178:181], v[84:87]
	v_mfma_f32_16x16x32_bf16 v[80:83], v[202:205], v[178:181], v[80:83]
	v_mfma_f32_16x16x32_bf16 v[68:71], v[194:197], v[186:189], v[68:71]
	v_mfma_f32_16x16x32_bf16 v[64:67], v[202:205], v[186:189], v[64:67]
	v_mfma_f32_16x16x32_bf16 v[116:119], v[198:201], v[148:151], v[116:119]
	v_mfma_f32_16x16x32_bf16 v[112:115], v[206:209], v[148:151], v[112:115]
	v_mfma_f32_16x16x32_bf16 v[100:103], v[198:201], v[174:177], v[100:103]
	v_mfma_f32_16x16x32_bf16 v[96:99], v[206:209], v[174:177], v[96:99]
	v_mfma_f32_16x16x32_bf16 v[84:87], v[198:201], v[182:185], v[84:87]
	v_mfma_f32_16x16x32_bf16 v[80:83], v[206:209], v[182:185], v[80:83]
	v_mfma_f32_16x16x32_bf16 v[68:71], v[198:201], v[190:193], v[68:71]
	s_setprio 0
	v_mfma_f32_16x16x32_bf16 v[64:67], v[206:209], v[190:193], v[64:67]
	s_barrier
; #define PG8_STAGE(bufoff, gbase, voff) do { _Pragma("unroll") for (int _i = 0; _i < 2; ++_i) \
;         __builtin_amdgcn_global_load_lds((const unsigned*)((const char*)(gbase) + (voff)[_i]), (LAS unsigned*)(lds + (bufoff) + ldsw + _i * 8192), 16, 0, 0); } while (0)
; #define PG8_LDA(dst, b, h) do { _Pragma("unroll") for (int m = 0; m < 4; ++m) _Pragma("unroll") for (int k = 0; k < 2; ++k) dst[m][k] = *(const LAS bf16x8*)(lds + PG8_SA(b, h) + aoff + m * 2048 + k * 1024); } while (0)
; #define PG8_LDB(dst, b, h) do { _Pragma("unroll") for (int n = 0; n < 2; ++n) _Pragma("unroll") for (int k = 0; k < 2; ++k) dst[n][k] = *(const LAS bf16x8*)(lds + PG8_SB(b, h) + boff + n * 2048 + k * 1024); } while (0)
; #define PG8_MMA(ai, bj, At, Bt) do { __builtin_amdgcn_s_setprio(1); _Pragma("unroll") for (int m = 0; m < 4; ++m) _Pragma("unroll") for (int n = 0; n < 2; ++n) _Pragma("unroll") for (int k = 0; k < 2; ++k) \
;         acc[ai][bj][m][n] = __builtin_amdgcn_mfma_f32_16x16x32_bf16(Bt[n][k], At[m][k], acc[ai][bj][m][n], 0, 0, 0); __builtin_amdgcn_s_setprio(0); } while (0)
; #define PG8_WAIT_V(n) asm volatile("s_waitcnt vmcnt(" #n ")" ::: "memory")
; #define PG8_WAIT_L(n) asm volatile("s_waitcnt lgkmcnt(" #n ")" ::: "memory")
; #define PG8_BAR __builtin_amdgcn_s_barrier()
; #define PG8_SCHED __builtin_amdgcn_sched_barrier(0)
; template <class Epi>
; __device__ __forceinline__ void gemm_phase(LAS unsigned char* lds, const Gemm g, const StaticOrder& S, const Epi& E) {
;     ...
;         for (int t = 0; t < nt; t += 2) {
;             const bool last = (t == nt - 2);
;             const char* a1 = cA + (size_t)(t + 1) * kstep;
;             const char* a2 = last ? nA : cA + (size_t)(t + 2) * kstep; const char* b2 = last ? nB : cB + (size_t)(t + 2) * kstep;
;             const char* a3 = a2 + kstep; const char* b3 = b2 + kstep;
;             PG8_LDB(B0, 0, 0); PG8_SCHED; PG8_LDA(At, 0, 0); PG8_STAGE(PG8_SA(1, 1), a1 + hstepA, voffA);
;             PG8_WAIT_L(8); PG8_BAR; PG8_WAIT_L(0); PG8_MMA(0, 0, At, B0); PG8_BAR; PG8_SCHED;
;     ...
;             PG8_BAR; PG8_WAIT_L(0); PG8_MMA(0, 1, At, B1); PG8_BAR;
;             PG8_LDA(At, 1, 1); PG8_STAGE(PG8_SA(1, 0), a3, voffA);
;             PG8_BAR; PG8_WAIT_L(0); PG8_MMA(1, 0, At, B0); PG8_BAR; PG8_SCHED;
;             PG8_STAGE(PG8_SB(1, 1), b3 + hstepB, voffB);
;             PG8_WAIT_V(6); PG8_BAR; PG8_MMA(1, 1, At, B1); PG8_BAR;
	s_mov_b32 m0, s39
	v_lshl_add_u64 v[210:211], s[18:19], 0, v[156:157]
	global_load_lds_dwordx4 v[210:211], off
	s_add_i32 m0, s39, 0x2000
	v_lshl_add_u64 v[210:211], s[18:19], 0, v[158:159]
	global_load_lds_dwordx4 v[210:211], off
	s_mov_b32 m0, s29
	v_lshl_add_u64 v[210:211], s[16:17], 0, v[156:157]
	global_load_lds_dwordx4 v[210:211], off
	s_mov_b32 m0, s30
	v_lshl_add_u64 v[210:211], s[16:17], 0, v[158:159]
	global_load_lds_dwordx4 v[210:211], off
	s_add_u32 s14, s14, 0x84000
	s_addc_u32 s15, s15, 0
	s_add_i32 s16, s40, s23
	s_mov_b32 m0, s16
	v_lshl_add_u64 v[210:211], s[14:15], 0, v[156:157]
	global_load_lds_dwordx4 v[210:211], off
	s_add_i32 m0, s16, 0x2000
	v_lshl_add_u64 v[210:211], s[14:15], 0, v[158:159]
	global_load_lds_dwordx4 v[210:211], off
	ds_read_b128 v[144:147], v172 offset:49152
	ds_read_b128 v[166:169], v172 offset:51200
	ds_read_b128 v[178:181], v172 offset:53248
	ds_read_b128 v[186:189], v172 offset:55296
	ds_read_b128 v[148:151], v172 offset:50176
	ds_read_b128 v[174:177], v172 offset:52224
	ds_read_b128 v[182:185], v172 offset:54272
	ds_read_b128 v[190:193], v172 offset:56320
	s_waitcnt vmcnt(6)
	s_waitcnt lgkmcnt(0)
	s_barrier
	v_mfma_f32_16x16x32_bf16 v[60:63], v[128:131], v[144:147], v[60:63]
	s_setprio 1
	v_mfma_f32_16x16x32_bf16 v[56:59], v[136:139], v[144:147], v[56:59]
	v_mfma_f32_16x16x32_bf16 v[44:47], v[128:131], v[166:169], v[44:47]
	v_mfma_f32_16x16x32_bf16 v[40:43], v[136:139], v[166:169], v[40:43]
	v_mfma_f32_16x16x32_bf16 v[28:31], v[128:131], v[178:181], v[28:31]
	v_mfma_f32_16x16x32_bf16 v[24:27], v[136:139], v[178:181], v[24:27]
	v_mfma_f32_16x16x32_bf16 v[12:15], v[128:131], v[186:189], v[12:15]
	v_mfma_f32_16x16x32_bf16 v[8:11], v[136:139], v[186:189], v[8:11]
	v_mfma_f32_16x16x32_bf16 v[60:63], v[132:135], v[148:151], v[60:63]
	v_mfma_f32_16x16x32_bf16 v[56:59], v[140:143], v[148:151], v[56:59]
	v_mfma_f32_16x16x32_bf16 v[44:47], v[132:135], v[174:177], v[44:47]
	v_mfma_f32_16x16x32_bf16 v[40:43], v[140:143], v[174:177], v[40:43]
	v_mfma_f32_16x16x32_bf16 v[28:31], v[132:135], v[182:185], v[28:31]
	v_mfma_f32_16x16x32_bf16 v[24:27], v[140:143], v[182:185], v[24:27]
	v_mfma_f32_16x16x32_bf16 v[12:15], v[132:135], v[190:193], v[12:15]
	v_mfma_f32_16x16x32_bf16 v[8:11], v[140:143], v[190:193], v[8:11]
	v_mfma_f32_16x16x32_bf16 v[52:55], v[194:197], v[144:147], v[52:55]
	v_mfma_f32_16x16x32_bf16 v[48:51], v[202:205], v[144:147], v[48:51]
	s_add_i32 s38, s38, 2
	s_add_u32 s12, s12, 0x8000
	s_addc_u32 s13, s13, 0
	s_add_u32 s36, s36, 0x8000
	s_addc_u32 s37, s37, 0
	v_mfma_f32_16x16x32_bf16 v[36:39], v[194:197], v[166:169], v[36:39]
	v_mfma_f32_16x16x32_bf16 v[32:35], v[202:205], v[166:169], v[32:35]
	v_mfma_f32_16x16x32_bf16 v[20:23], v[194:197], v[178:181], v[20:23]
	v_mfma_f32_16x16x32_bf16 v[16:19], v[202:205], v[178:181], v[16:19]
	v_mfma_f32_16x16x32_bf16 v[4:7], v[194:197], v[186:189], v[4:7]
	v_mfma_f32_16x16x32_bf16 v[0:3], v[202:205], v[186:189], v[0:3]
	v_mfma_f32_16x16x32_bf16 v[52:55], v[198:201], v[148:151], v[52:55]
	v_mfma_f32_16x16x32_bf16 v[48:51], v[206:209], v[148:151], v[48:51]
	v_mfma_f32_16x16x32_bf16 v[36:39], v[198:201], v[174:177], v[36:39]
	v_mfma_f32_16x16x32_bf16 v[32:35], v[206:209], v[174:177], v[32:35]
	v_mfma_f32_16x16x32_bf16 v[20:23], v[198:201], v[182:185], v[20:23]
	v_mfma_f32_16x16x32_bf16 v[16:19], v[206:209], v[182:185], v[16:19]
	v_mfma_f32_16x16x32_bf16 v[4:7], v[198:201], v[190:193], v[4:7]
	s_cmp_gt_u32 s38, 29
	s_setprio 0
	v_mfma_f32_16x16x32_bf16 v[0:3], v[206:209], v[190:193], v[0:3]
	s_cbranch_scc1 .Lkexit_247
	s_barrier
.LBB0_247:
	s_add_u32 s14, s12, 0xfff84000
	s_addc_u32 s15, s13, -1
	s_cmp_eq_u32 s38, 28
	s_cselect_b32 s18, s11, s14
	s_cselect_b32 s19, s5, s15
	s_cselect_b32 s14, s35, s36
	s_cselect_b32 s15, s3, s37
	s_add_u32 s16, s18, 0x4000
	s_addc_u32 s17, s19, 0
	s_add_i32 m0, s25, 0xc000
	v_lshl_add_u64 v[194:195], s[12:13], 0, v[156:157]
	global_load_lds_dwordx4 v[194:195], off
	s_add_i32 m0, s25, 0xe000
	v_lshl_add_u64 v[194:195], s[12:13], 0, v[158:159]
	global_load_lds_dwordx4 v[194:195], off
	s_mov_b32 s39, 0x10000
	v_add_u32_e32 v140, s39, v170
	ds_read_b128 v[128:131], v140
	ds_read_b128 v[136:139], v140 offset:2048
	ds_read_b128 v[132:135], v140 offset:1024
	ds_read_b128 v[140:143], v140 offset:3072
	ds_read_b128 v[144:147], v172
	ds_read_b128 v[166:169], v172 offset:2048
	ds_read_b128 v[178:181], v172 offset:4096
	ds_read_b128 v[186:189], v172 offset:6144
	ds_read_b128 v[148:151], v172 offset:1024
	ds_read_b128 v[174:177], v172 offset:3072
	ds_read_b128 v[182:185], v172 offset:5120
	ds_read_b128 v[190:193], v172 offset:7168
	s_mov_b32 s42, 0x14000
	s_add_i32 s39, s39, s23
	v_add_u32_e32 v152, s42, v170
	ds_read_b128 v[194:197], v152
	ds_read_b128 v[202:205], v152 offset:2048
	ds_read_b128 v[198:201], v152 offset:1024
	ds_read_b128 v[206:209], v152 offset:3072
	s_waitcnt lgkmcnt(0)
	s_barrier
; #define PG8_STAGE(bufoff, gbase, voff) do { _Pragma("unroll") for (int _i = 0; _i < 2; ++_i) \
;         __builtin_amdgcn_global_load_lds((const unsigned*)((const char*)(gbase) + (voff)[_i]), (LAS unsigned*)(lds + (bufoff) + ldsw + _i * 8192), 16, 0, 0); } while (0)
; #define PG8_LDA(dst, b, h) do { _Pragma("unroll") for (int m = 0; m < 4; ++m) _Pragma("unroll") for (int k = 0; k < 2; ++k) dst[m][k] = *(const LAS bf16x8*)(lds + PG8_SA(b, h) + aoff + m * 2048 + k * 1024); } while (0)
; #define PG8_LDB(dst, b, h) do { _Pragma("unroll") for (int n = 0; n < 2; ++n) _Pragma("unroll") for (int k = 0; k < 2; ++k) dst[n][k] = *(const LAS bf16x8*)(lds + PG8_SB(b, h) + boff + n * 2048 + k * 1024); } while (0)
; #define PG8_MMA(ai, bj, At, Bt) do { __builtin_amdgcn_s_setprio(1); _Pragma("unroll") for (int m = 0; m < 4; ++m) _Pragma("unroll") for (int n = 0; n < 2; ++n) _Pragma("unroll") for (int k = 0; k < 2; ++k) \
;         acc[ai][bj][m][n] = __builtin_amdgcn_mfma_f32_16x16x32_bf16(Bt[n][k], At[m][k], acc[ai][bj][m][n], 0, 0, 0); __builtin_amdgcn_s_setprio(0); } while (0)
; #define PG8_WAIT_V(n) asm volatile("s_waitcnt vmcnt(" #n ")" ::: "memory")
; #define PG8_WAIT_L(n) asm volatile("s_waitcnt lgkmcnt(" #n ")" ::: "memory")
; #define PG8_BAR __builtin_amdgcn_s_barrier()
; #define PG8_SCHED __builtin_amdgcn_sched_barrier(0)
; template <class Epi>
; __device__ __forceinline__ void gemm_phase(LAS unsigned char* lds, const Gemm g, const StaticOrder& S, const Epi& E) {
;     ...
;             PG8_WAIT_L(8); PG8_BAR; PG8_WAIT_L(0); PG8_MMA(0, 0, At, B0); PG8_BAR; PG8_SCHED;
;             PG8_LDB(B1, 0, 1); PG8_STAGE(PG8_SB(0, 0), b2, voffB);
;             PG8_BAR; PG8_WAIT_L(0); PG8_MMA(0, 1, At, B1); PG8_BAR;
;             PG8_LDA(At, 0, 1); PG8_STAGE(PG8_SA(0, 0), a2, voffA);
;             PG8_BAR; PG8_WAIT_L(0); PG8_MMA(1, 0, At, B0); PG8_BAR; PG8_SCHED;
;             PG8_STAGE(PG8_SB(0, 1), b2 + hstepB, voffB);
;             PG8_WAIT_V(6); PG8_BAR; PG8_MMA(1, 1, At, B1); PG8_BAR;
;             PG8_LDB(B0, 1, 0); PG8_SCHED; PG8_LDA(At, 1, 0); PG8_STAGE(PG8_SA(0, 1), a2 + hstepA, voffA);
;             PG8_WAIT_L(8); PG8_BAR; PG8_WAIT_L(0); PG8_MMA(0, 0, At, B0); PG8_BAR; PG8_SCHED;
	v_mfma_f32_16x16x32_bf16 v[124:127], v[128:131], v[144:147], v[124:127]
	s_setprio 1
	v_mfma_f32_16x16x32_bf16 v[120:123], v[136:139], v[144:147], v[120:123]
	v_mfma_f32_16x16x32_bf16 v[108:111], v[128:131], v[166:169], v[108:111]
	v_mfma_f32_16x16x32_bf16 v[104:107], v[136:139], v[166:169], v[104:107]
	v_mfma_f32_16x16x32_bf16 v[92:95], v[128:131], v[178:181], v[92:95]
	v_mfma_f32_16x16x32_bf16 v[88:91], v[136:139], v[178:181], v[88:91]
	v_mfma_f32_16x16x32_bf16 v[76:79], v[128:131], v[186:189], v[76:79]
	v_mfma_f32_16x16x32_bf16 v[72:75], v[136:139], v[186:189], v[72:75]
	v_mfma_f32_16x16x32_bf16 v[124:127], v[132:135], v[148:151], v[124:127]
	v_mfma_f32_16x16x32_bf16 v[120:123], v[140:143], v[148:151], v[120:123]
	v_mfma_f32_16x16x32_bf16 v[108:111], v[132:135], v[174:177], v[108:111]
	v_mfma_f32_16x16x32_bf16 v[104:107], v[140:143], v[174:177], v[104:107]
	v_mfma_f32_16x16x32_bf16 v[92:95], v[132:135], v[182:185], v[92:95]
	v_mfma_f32_16x16x32_bf16 v[88:91], v[140:143], v[182:185], v[88:91]
	v_mfma_f32_16x16x32_bf16 v[76:79], v[132:135], v[190:193], v[76:79]
	v_mfma_f32_16x16x32_bf16 v[72:75], v[140:143], v[190:193], v[72:75]
	v_mfma_f32_16x16x32_bf16 v[116:119], v[194:197], v[144:147], v[116:119]
	v_mfma_f32_16x16x32_bf16 v[112:115], v[202:205], v[144:147], v[112:115]
	v_mfma_f32_16x16x32_bf16 v[100:103], v[194:197], v[166:169], v[100:103]
	v_mfma_f32_16x16x32_bf16 v[96:99], v[202:205], v[166:169], v[96:99]
	v_mfma_f32_16x16x32_bf16 v[84:87], v[194:197], v[178:181], v[84:87]
	v_mfma_f32_16x16x32_bf16 v[80:83], v[202:205], v[178:181], v[80:83]
	v_mfma_f32_16x16x32_bf16 v[68:71], v[194:197], v[186:189], v[68:71]
	v_mfma_f32_16x16x32_bf16 v[64:67], v[202:205], v[186:189], v[64:67]
	v_mfma_f32_16x16x32_bf16 v[116:119], v[198:201], v[148:151], v[116:119]
	v_mfma_f32_16x16x32_bf16 v[112:115], v[206:209], v[148:151], v[112:115]
	v_mfma_f32_16x16x32_bf16 v[100:103], v[198:201], v[174:177], v[100:103]
	v_mfma_f32_16x16x32_bf16 v[96:99], v[206:209], v[174:177], v[96:99]
	v_mfma_f32_16x16x32_bf16 v[84:87], v[198:201], v[182:185], v[84:87]
	v_mfma_f32_16x16x32_bf16 v[80:83], v[206:209], v[182:185], v[80:83]
	v_mfma_f32_16x16x32_bf16 v[68:71], v[198:201], v[190:193], v[68:71]
	s_setprio 0
	v_mfma_f32_16x16x32_bf16 v[64:67], v[206:209], v[190:193], v[64:67]
	s_barrier
	s_mov_b32 m0, s39
	v_lshl_add_u64 v[210:211], s[14:15], 0, v[156:157]
	global_load_lds_dwordx4 v[210:211], off
	s_add_i32 m0, s39, 0x2000
	v_lshl_add_u64 v[210:211], s[14:15], 0, v[158:159]
	global_load_lds_dwordx4 v[210:211], off
	s_mov_b32 m0, s25
	v_lshl_add_u64 v[210:211], s[18:19], 0, v[156:157]
	global_load_lds_dwordx4 v[210:211], off
	s_mov_b32 m0, s26
	v_lshl_add_u64 v[210:211], s[18:19], 0, v[158:159]
	global_load_lds_dwordx4 v[210:211], off
	s_add_u32 s40, s14, 0x80000
	s_addc_u32 s41, s15, 0
	s_add_i32 s39, s42, s23
	s_mov_b32 m0, s39
	v_lshl_add_u64 v[210:211], s[40:41], 0, v[156:157]
	global_load_lds_dwordx4 v[210:211], off
	s_add_i32 m0, s39, 0x2000
	v_lshl_add_u64 v[210:211], s[40:41], 0, v[158:159]
	global_load_lds_dwordx4 v[210:211], off
	ds_read_b128 v[144:147], v172 offset:16384
	ds_read_b128 v[166:169], v172 offset:18432
	ds_read_b128 v[178:181], v172 offset:20480
	ds_read_b128 v[186:189], v172 offset:22528
	ds_read_b128 v[148:151], v172 offset:17408
	ds_read_b128 v[174:177], v172 offset:19456
	ds_read_b128 v[182:185], v172 offset:21504
	ds_read_b128 v[190:193], v172 offset:23552
	s_waitcnt vmcnt(6)
	s_waitcnt lgkmcnt(0)
	s_barrier
	v_mfma_f32_16x16x32_bf16 v[60:63], v[128:131], v[144:147], v[60:63]
	s_setprio 1
	v_mfma_f32_16x16x32_bf16 v[56:59], v[136:139], v[144:147], v[56:59]
	v_mfma_f32_16x16x32_bf16 v[44:47], v[128:131], v[166:169], v[44:47]
	v_mfma_f32_16x16x32_bf16 v[40:43], v[136:139], v[166:169], v[40:43]
	v_mfma_f32_16x16x32_bf16 v[28:31], v[128:131], v[178:181], v[28:31]
	v_mfma_f32_16x16x32_bf16 v[24:27], v[136:139], v[178:181], v[24:27]
	v_mfma_f32_16x16x32_bf16 v[12:15], v[128:131], v[186:189], v[12:15]
	v_mfma_f32_16x16x32_bf16 v[8:11], v[136:139], v[186:189], v[8:11]
	v_mfma_f32_16x16x32_bf16 v[60:63], v[132:135], v[148:151], v[60:63]
	v_mfma_f32_16x16x32_bf16 v[56:59], v[140:143], v[148:151], v[56:59]
	v_mfma_f32_16x16x32_bf16 v[44:47], v[132:135], v[174:177], v[44:47]
	v_mfma_f32_16x16x32_bf16 v[40:43], v[140:143], v[174:177], v[40:43]
	v_mfma_f32_16x16x32_bf16 v[28:31], v[132:135], v[182:185], v[28:31]
	v_mfma_f32_16x16x32_bf16 v[24:27], v[140:143], v[182:185], v[24:27]
	v_mfma_f32_16x16x32_bf16 v[12:15], v[132:135], v[190:193], v[12:15]
	v_mfma_f32_16x16x32_bf16 v[8:11], v[140:143], v[190:193], v[8:11]
	v_mfma_f32_16x16x32_bf16 v[52:55], v[194:197], v[144:147], v[52:55]
	v_mfma_f32_16x16x32_bf16 v[48:51], v[202:205], v[144:147], v[48:51]
	s_add_i32 s39, 0, 0x18000
	v_add_u32_e32 v140, s39, v170
	v_mfma_f32_16x16x32_bf16 v[36:39], v[194:197], v[166:169], v[36:39]
	v_mfma_f32_16x16x32_bf16 v[32:35], v[202:205], v[166:169], v[32:35]
	v_mfma_f32_16x16x32_bf16 v[20:23], v[194:197], v[178:181], v[20:23]
	v_mfma_f32_16x16x32_bf16 v[16:19], v[202:205], v[178:181], v[16:19]
	v_mfma_f32_16x16x32_bf16 v[4:7], v[194:197], v[186:189], v[4:7]
	v_mfma_f32_16x16x32_bf16 v[0:3], v[202:205], v[186:189], v[0:3]
	v_mfma_f32_16x16x32_bf16 v[52:55], v[198:201], v[148:151], v[52:55]
	v_mfma_f32_16x16x32_bf16 v[48:51], v[206:209], v[148:151], v[48:51]
	v_mfma_f32_16x16x32_bf16 v[36:39], v[198:201], v[174:177], v[36:39]
	v_mfma_f32_16x16x32_bf16 v[32:35], v[206:209], v[174:177], v[32:35]
	v_mfma_f32_16x16x32_bf16 v[20:23], v[198:201], v[182:185], v[20:23]
	v_mfma_f32_16x16x32_bf16 v[16:19], v[206:209], v[182:185], v[16:19]
	v_mfma_f32_16x16x32_bf16 v[4:7], v[198:201], v[190:193], v[4:7]
	s_setprio 0
	v_mfma_f32_16x16x32_bf16 v[0:3], v[206:209], v[190:193], v[0:3]
	s_barrier
; #define PG8_STAGE(bufoff, gbase, voff) do { _Pragma("unroll") for (int _i = 0; _i < 2; ++_i) \
;         __builtin_amdgcn_global_load_lds((const unsigned*)((const char*)(gbase) + (voff)[_i]), (LAS unsigned*)(lds + (bufoff) + ldsw + _i * 8192), 16, 0, 0); } while (0)
; #define PG8_LDA(dst, b, h) do { _Pragma("unroll") for (int m = 0; m < 4; ++m) _Pragma("unroll") for (int k = 0; k < 2; ++k) dst[m][k] = *(const LAS bf16x8*)(lds + PG8_SA(b, h) + aoff + m * 2048 + k * 1024); } while (0)
; #define PG8_LDB(dst, b, h) do { _Pragma("unroll") for (int n = 0; n < 2; ++n) _Pragma("unroll") for (int k = 0; k < 2; ++k) dst[n][k] = *(const LAS bf16x8*)(lds + PG8_SB(b, h) + boff + n * 2048 + k * 1024); } while (0)
; #define PG8_MMA(ai, bj, At, Bt) do { __builtin_amdgcn_s_setprio(1); _Pragma("unroll") for (int m = 0; m < 4; ++m) _Pragma("unroll") for (int n = 0; n < 2; ++n) _Pragma("unroll") for (int k = 0; k < 2; ++k) \
;         acc[ai][bj][m][n] = __builtin_amdgcn_mfma_f32_16x16x32_bf16(Bt[n][k], At[m][k], acc[ai][bj][m][n], 0, 0, 0); __builtin_amdgcn_s_setprio(0); } while (0)
; #define PG8_WAIT_V(n) asm volatile("s_waitcnt vmcnt(" #n ")" ::: "memory")
; #define PG8_WAIT_L(n) asm volatile("s_waitcnt lgkmcnt(" #n ")" ::: "memory")
; #define PG8_BAR __builtin_amdgcn_s_barrier()
; #define PG8_SCHED __builtin_amdgcn_sched_barrier(0)
; template <class Epi>
; __device__ __forceinline__ void gemm_phase(LAS unsigned char* lds, const Gemm g, const StaticOrder& S, const Epi& E) {
;     ...
;             PG8_LDB(B1, 1, 1); PG8_STAGE(PG8_SB(1, 0), b3, voffB);
;             PG8_BAR; PG8_WAIT_L(0); PG8_MMA(0, 1, At, B1); PG8_BAR;
;             PG8_LDA(At, 1, 1); PG8_STAGE(PG8_SA(1, 0), a3, voffA);
;             PG8_BAR; PG8_WAIT_L(0); PG8_MMA(1, 0, At, B0); PG8_BAR; PG8_SCHED;
;             PG8_STAGE(PG8_SB(1, 1), b3 + hstepB, voffB);
;             PG8_WAIT_V(6); PG8_BAR; PG8_MMA(1, 1, At, B1); PG8_BAR;
	s_add_u32 s18, s18, 0x80000
	s_addc_u32 s19, s19, 0
	s_mov_b32 m0, s27
	v_lshl_add_u64 v[194:195], s[18:19], 0, v[156:157]
	global_load_lds_dwordx4 v[194:195], off
	s_mov_b32 m0, s28
	v_lshl_add_u64 v[194:195], s[18:19], 0, v[158:159]
	global_load_lds_dwordx4 v[194:195], off
	ds_read_b128 v[128:131], v140
	ds_read_b128 v[136:139], v140 offset:2048
	ds_read_b128 v[132:135], v140 offset:1024
	ds_read_b128 v[140:143], v140 offset:3072
	ds_read_b128 v[144:147], v172 offset:32768
	ds_read_b128 v[166:169], v172 offset:34816
	ds_read_b128 v[178:181], v172 offset:36864
	ds_read_b128 v[186:189], v172 offset:38912
	ds_read_b128 v[148:151], v172 offset:33792
	ds_read_b128 v[174:177], v172 offset:35840
	ds_read_b128 v[182:185], v172 offset:37888
	ds_read_b128 v[190:193], v172 offset:39936
	s_mov_b32 s40, 0x1c000
	s_add_u32 s18, s14, 0x4000
	s_addc_u32 s19, s15, 0
	s_add_i32 s39, s39, s23
	v_add_u32_e32 v152, s40, v170
	ds_read_b128 v[194:197], v152
	ds_read_b128 v[202:205], v152 offset:2048
	ds_read_b128 v[198:201], v152 offset:1024
	ds_read_b128 v[206:209], v152 offset:3072
	s_waitcnt lgkmcnt(0)
	s_barrier
	v_mfma_f32_16x16x32_bf16 v[124:127], v[128:131], v[144:147], v[124:127]
	s_setprio 1
	v_mfma_f32_16x16x32_bf16 v[120:123], v[136:139], v[144:147], v[120:123]
	v_mfma_f32_16x16x32_bf16 v[108:111], v[128:131], v[166:169], v[108:111]
	v_mfma_f32_16x16x32_bf16 v[104:107], v[136:139], v[166:169], v[104:107]
	v_mfma_f32_16x16x32_bf16 v[92:95], v[128:131], v[178:181], v[92:95]
	v_mfma_f32_16x16x32_bf16 v[88:91], v[136:139], v[178:181], v[88:91]
	v_mfma_f32_16x16x32_bf16 v[76:79], v[128:131], v[186:189], v[76:79]
	v_mfma_f32_16x16x32_bf16 v[72:75], v[136:139], v[186:189], v[72:75]
	v_mfma_f32_16x16x32_bf16 v[124:127], v[132:135], v[148:151], v[124:127]
	v_mfma_f32_16x16x32_bf16 v[120:123], v[140:143], v[148:151], v[120:123]
	v_mfma_f32_16x16x32_bf16 v[108:111], v[132:135], v[174:177], v[108:111]
	v_mfma_f32_16x16x32_bf16 v[104:107], v[140:143], v[174:177], v[104:107]
	v_mfma_f32_16x16x32_bf16 v[92:95], v[132:135], v[182:185], v[92:95]
	v_mfma_f32_16x16x32_bf16 v[88:91], v[140:143], v[182:185], v[88:91]
	v_mfma_f32_16x16x32_bf16 v[76:79], v[132:135], v[190:193], v[76:79]
	v_mfma_f32_16x16x32_bf16 v[72:75], v[140:143], v[190:193], v[72:75]
	v_mfma_f32_16x16x32_bf16 v[116:119], v[194:197], v[144:147], v[116:119]
	v_mfma_f32_16x16x32_bf16 v[112:115], v[202:205], v[144:147], v[112:115]
	v_mfma_f32_16x16x32_bf16 v[100:103], v[194:197], v[166:169], v[100:103]
	v_mfma_f32_16x16x32_bf16 v[96:99], v[202:205], v[166:169], v[96:99]
	v_mfma_f32_16x16x32_bf16 v[84:87], v[194:197], v[178:181], v[84:87]
	v_mfma_f32_16x16x32_bf16 v[80:83], v[202:205], v[178:181], v[80:83]
	v_mfma_f32_16x16x32_bf16 v[68:71], v[194:197], v[186:189], v[68:71]
	v_mfma_f32_16x16x32_bf16 v[64:67], v[202:205], v[186:189], v[64:67]
	v_mfma_f32_16x16x32_bf16 v[116:119], v[198:201], v[148:151], v[116:119]
	v_mfma_f32_16x16x32_bf16 v[112:115], v[206:209], v[148:151], v[112:115]
	v_mfma_f32_16x16x32_bf16 v[100:103], v[198:201], v[174:177], v[100:103]
	v_mfma_f32_16x16x32_bf16 v[96:99], v[206:209], v[174:177], v[96:99]
	v_mfma_f32_16x16x32_bf16 v[84:87], v[198:201], v[182:185], v[84:87]
	v_mfma_f32_16x16x32_bf16 v[80:83], v[206:209], v[182:185], v[80:83]
	v_mfma_f32_16x16x32_bf16 v[68:71], v[198:201], v[190:193], v[68:71]
	s_setprio 0
	v_mfma_f32_16x16x32_bf16 v[64:67], v[206:209], v[190:193], v[64:67]
	s_barrier
	s_mov_b32 m0, s39
	v_lshl_add_u64 v[210:211], s[18:19], 0, v[156:157]
	global_load_lds_dwordx4 v[210:211], off
	s_add_i32 m0, s39, 0x2000
	v_lshl_add_u64 v[210:211], s[18:19], 0, v[158:159]
	global_load_lds_dwordx4 v[210:211], off
	s_mov_b32 m0, s29
	v_lshl_add_u64 v[210:211], s[16:17], 0, v[156:157]
	global_load_lds_dwordx4 v[210:211], off
	s_mov_b32 m0, s30
	v_lshl_add_u64 v[210:211], s[16:17], 0, v[158:159]
	global_load_lds_dwordx4 v[210:211], off
	s_add_u32 s14, s14, 0x84000
	s_addc_u32 s15, s15, 0
	s_add_i32 s16, s40, s23
	s_mov_b32 m0, s16
	v_lshl_add_u64 v[210:211], s[14:15], 0, v[156:157]
	global_load_lds_dwordx4 v[210:211], off
	s_add_i32 m0, s16, 0x2000
	v_lshl_add_u64 v[210:211], s[14:15], 0, v[158:159]
	global_load_lds_dwordx4 v[210:211], off
	ds_read_b128 v[144:147], v172 offset:49152
	ds_read_b128 v[166:169], v172 offset:51200
	ds_read_b128 v[178:181], v172 offset:53248
	ds_read_b128 v[186:189], v172 offset:55296
	ds_read_b128 v[148:151], v172 offset:50176
	ds_read_b128 v[174:177], v172 offset:52224
	ds_read_b128 v[182:185], v172 offset:54272
	ds_read_b128 v[190:193], v172 offset:56320
	s_waitcnt vmcnt(6)
	s_waitcnt lgkmcnt(0)
	s_barrier
	v_mfma_f32_16x16x32_bf16 v[60:63], v[128:131], v[144:147], v[60:63]
	s_setprio 1
	v_mfma_f32_16x16x32_bf16 v[56:59], v[136:139], v[144:147], v[56:59]
	v_mfma_f32_16x16x32_bf16 v[44:47], v[128:131], v[166:169], v[44:47]
	v_mfma_f32_16x16x32_bf16 v[40:43], v[136:139], v[166:169], v[40:43]
	v_mfma_f32_16x16x32_bf16 v[28:31], v[128:131], v[178:181], v[28:31]
	v_mfma_f32_16x16x32_bf16 v[24:27], v[136:139], v[178:181], v[24:27]
	v_mfma_f32_16x16x32_bf16 v[12:15], v[128:131], v[186:189], v[12:15]
	v_mfma_f32_16x16x32_bf16 v[8:11], v[136:139], v[186:189], v[8:11]
	v_mfma_f32_16x16x32_bf16 v[60:63], v[132:135], v[148:151], v[60:63]
	v_mfma_f32_16x16x32_bf16 v[56:59], v[140:143], v[148:151], v[56:59]
	v_mfma_f32_16x16x32_bf16 v[44:47], v[132:135], v[174:177], v[44:47]
	v_mfma_f32_16x16x32_bf16 v[40:43], v[140:143], v[174:177], v[40:43]
	v_mfma_f32_16x16x32_bf16 v[28:31], v[132:135], v[182:185], v[28:31]
	v_mfma_f32_16x16x32_bf16 v[24:27], v[140:143], v[182:185], v[24:27]
	v_mfma_f32_16x16x32_bf16 v[12:15], v[132:135], v[190:193], v[12:15]
	v_mfma_f32_16x16x32_bf16 v[8:11], v[140:143], v[190:193], v[8:11]
	v_mfma_f32_16x16x32_bf16 v[52:55], v[194:197], v[144:147], v[52:55]
	v_mfma_f32_16x16x32_bf16 v[48:51], v[202:205], v[144:147], v[48:51]
	s_add_i32 s38, s38, 2
	s_add_u32 s12, s12, 0x8000
	s_addc_u32 s13, s13, 0
	s_add_u32 s36, s36, 0x8000
	s_addc_u32 s37, s37, 0
	v_mfma_f32_16x16x32_bf16 v[36:39], v[194:197], v[166:169], v[36:39]
	v_mfma_f32_16x16x32_bf16 v[32:35], v[202:205], v[166:169], v[32:35]
	v_mfma_f32_16x16x32_bf16 v[20:23], v[194:197], v[178:181], v[20:23]
	v_mfma_f32_16x16x32_bf16 v[16:19], v[202:205], v[178:181], v[16:19]
	v_mfma_f32_16x16x32_bf16 v[4:7], v[194:197], v[186:189], v[4:7]
	v_mfma_f32_16x16x32_bf16 v[0:3], v[202:205], v[186:189], v[0:3]
	v_mfma_f32_16x16x32_bf16 v[52:55], v[198:201], v[148:151], v[52:55]
	v_mfma_f32_16x16x32_bf16 v[48:51], v[206:209], v[148:151], v[48:51]
	v_mfma_f32_16x16x32_bf16 v[36:39], v[198:201], v[174:177], v[36:39]
	v_mfma_f32_16x16x32_bf16 v[32:35], v[206:209], v[174:177], v[32:35]
	v_mfma_f32_16x16x32_bf16 v[20:23], v[198:201], v[182:185], v[20:23]
	v_mfma_f32_16x16x32_bf16 v[16:19], v[206:209], v[182:185], v[16:19]
	v_mfma_f32_16x16x32_bf16 v[4:7], v[198:201], v[190:193], v[4:7]
	s_cmp_gt_u32 s38, 29
	s_setprio 0
	v_mfma_f32_16x16x32_bf16 v[0:3], v[206:209], v[190:193], v[0:3]
	s_cbranch_scc1 .Lkexit_247
	s_barrier
	s_branch .LBB0_247
; #define PG8_MMA(ai, bj, At, Bt) do { __builtin_amdgcn_s_setprio(1); _Pragma("unroll") for (int m = 0; m < 4; ++m) _Pragma("unroll") for (int n = 0; n < 2; ++n) _Pragma("unroll") for (int k = 0; k < 2; ++k) \
;         acc[ai][bj][m][n] = __builtin_amdgcn_mfma_f32_16x16x32_bf16(Bt[n][k], At[m][k], acc[ai][bj][m][n], 0, 0, 0); __builtin_amdgcn_s_setprio(0); } while (0)
; #define PG8_WAIT_V(n) asm volatile("s_waitcnt vmcnt(" #n ")" ::: "memory")
; #define PG8_BAR __builtin_amdgcn_s_barrier()
; template <class Epi>
; __device__ __forceinline__ void gemm_phase(LAS unsigned char* lds, const Gemm g, const StaticOrder& S, const Epi& E) {
;     ...
;             PG8_WAIT_V(6); PG8_BAR; PG8_MMA(1, 1, At, B1); PG8_BAR;
;         }
;         E(acc, cur, wr, wc, fr, fq);
;         if (!has_next) break;
.Lkexit_247:
	s_cmpk_gt_u32 s20, 0xff
	s_cbranch_scc1 .Lpeel_done_247
	s_barrier
